# nt hint on attention Q loads only (read once per tile; keeps K/V in L2)
# baseline (speedup 1.0000x reference)
.Latt_entry:
	s_mov_b64 exec, -1
	v_readlane_b32 s4, v254, 0
	v_readlane_b32 s5, v254, 1
	v_readlane_b32 s6, v254, 42
	v_readlane_b32 s7, v254, 43
	v_readlane_b32 s8, v254, 46
	v_readlane_b32 s10, v254, 53
	v_readfirstlane_b32 s0, v145
	s_movk_i32 s78, 0x90
	s_movk_i32 s79, 0x110
	s_mov_b32 s80, 0x12100
	s_movk_i32 s82, 0x4000
	s_movk_i32 s83, 0x1000
	s_mov_b32 s84, 0xc000
	s_mov_b32 s85, 0x7ffff000
	s_lshr_b32 s0, s0, 6
	s_mul_i32 s1, s0, 0x1200
	s_add_i32 s1, s1, 0x12500
	s_mov_b32 s37, 0
	v_and_b32_e32 v142, 63, v145
	v_and_b32_e32 v160, 15, v145
	v_bfe_u32 v134, v145, 4, 2
	v_lshlrev_b32_e32 v161, 4, v134
	v_lshlrev_b32_e32 v169, 2, v134
	v_and_b32_e32 v135, 7, v145
	v_lshlrev_b32_e32 v162, 4, v135
	v_bfe_u32 v164, v145, 3, 3
	v_mad_u32_u24 v165, v164, s78, v162
	v_add_u32_e32 v165, s1, v165
	v_bfe_u32 v134, v145, 2, 2
	v_add_u32_e32 v134, v134, v169
	v_and_b32_e32 v135, 3, v145
	v_lshlrev_b32_e32 v135, 3, v135
	v_mad_u32_u24 v166, v134, s78, v135
	v_add_u32_e32 v166, s1, v166
	v_xor_b32_e32 v134, 16, v142
	v_lshlrev_b32_e32 v167, 2, v134
	v_xor_b32_e32 v134, 32, v142
	v_lshlrev_b32_e32 v168, 2, v134
	v_sub_u32_e32 v134, v169, v160
	v_cmp_ge_i32_e64 s[54:55], v134, 0
	v_cmp_le_i32_e64 s[62:63], v134, 0
	v_cmp_ge_i32_e64 s[56:57], v134, -1
	v_cmp_le_i32_e64 s[64:65], v134, -1
	v_cmp_ge_i32_e64 s[58:59], v134, -2
	v_cmp_le_i32_e64 s[66:67], v134, -2
	v_cmp_ge_i32_e64 s[60:61], v134, -3
	v_cmp_le_i32_e64 s[68:69], v134, -3
	v_lshrrev_b32_e32 v134, 1, v145
	v_lshrrev_b32_e32 v135, 4, v134
	v_add_u32_e32 v135, v135, v134
	v_and_b32_e32 v136, 1, v145
	v_lshlrev_b32_e32 v137, 7, v136
	v_mad_u32_u24 v170, v135, s79, v137
	v_lshl_add_u32 v171, v134, 2, s80
	v_lshlrev_b32_e32 v135, 11, v134
	v_lshl_add_u32 v172, v136, 6, v135
	v_mov_b32_e32 v130, 0
	v_mov_b32_e32 v131, 0
	v_mov_b32_e32 v184, 0
	v_mov_b32_e32 v185, 0
	s_lshr_b32 s2, s10, 3
	s_and_b32 s3, s10, 7
	s_and_b32 s30, s2, 31
	s_lshl_b32 s31, s3, 5
	s_or_b32 s31, s31, s30
	s_lshr_b32 s30, s10, 8
	s_cmp_eq_u32 s8, 0x100
	s_cselect_b32 s2, s31, s2
	s_cselect_b32 s17, s30, s3
	s_lshl_b32 s16, s2, 8
	s_cmp_lt_u32 s2, 0x80
	s_cselect_b32 s12, s82, s83
	s_cselect_b32 s13, 12, 10
	s_cselect_b32 s3, s84, s85
	s_and_b32 s3, s16, s3
	s_sub_i32 s15, s16, s3
	s_lshr_b32 s30, s12, 4
	s_add_i32 s14, s30, -1
	s_lshl_b32 s30, s17, 23
	s_lshl_b32 s3, s3, 7
	s_add_u32 s30, s30, s3
	s_add_u32 s18, s4, s30
	s_addc_u32 s19, s5, 0
	s_add_u32 s20, s18, 0x4000000
	s_addc_u32 s21, s19, 0
	s_add_u32 s22, s18, 0x8000000
	s_addc_u32 s23, s19, 0
	s_lshl_b32 s2, s0, 5
	s_add_i32 s42, s15, s2
	s_mov_b32 s43, 0
	v_add_u32_e32 v134, s42, v160
	v_add_u32_e32 v134, s43, v134
	v_subrev_u32_e32 v135, s15, v134
	v_lshrrev_b32_e32 v136, 4, v135
	v_add_u32_e32 v136, v136, v135
	v_mad_u32_u24 v176, v136, s79, v161
	v_lshl_add_u32 v177, v135, 2, s80
	s_sub_i32 s2, s42, 64
	v_add_u32_e32 v178, s2, v169
	v_and_b32_e32 v135, 3, v134
	v_lshlrev_b32_e32 v135, s13, v135
	v_lshrrev_b32_e32 v136, 2, v134
	v_add_u32_e32 v135, v135, v136
	v_lshl_add_u32 v135, v135, 7, v161
	global_load_dwordx4 v[48:51], v135, s[18:19] nt
	global_load_dwordx4 v[52:55], v135, s[18:19] offset:64 nt
	v_add_u32_e32 v137, 16, v134
	v_and_b32_e32 v135, 3, v137
	v_lshlrev_b32_e32 v135, s13, v135
	v_lshrrev_b32_e32 v136, 2, v137
	v_add_u32_e32 v135, v135, v136
	v_lshl_add_u32 v135, v135, 7, v161
	global_load_dwordx4 v[56:59], v135, s[18:19] nt
	global_load_dwordx4 v[60:63], v135, s[18:19] offset:64 nt
	v_subrev_u32_e32 v134, 64, v134
	v_and_b32_e32 v137, 3, v134
	v_lshlrev_b32_e32 v137, s13, v137
	v_bfe_u32 v135, v134, 2, 2
	v_add_u32_e32 v137, v137, v135
	v_lshl_add_u32 v183, v137, 7, v161
	v_ashrrev_i32_e32 v252, 4, v134
	v_med3_i32 v136, v252, 0, s14
	v_lshl_add_u32 v136, v136, 9, v183
	global_load_dwordx4 v[0:3], v136, s[20:21]
	global_load_dwordx4 v[4:7], v136, s[20:21] offset:64
	v_add_u32_e32 v135, 1, v252
	v_med3_i32 v135, v135, 0, s14
	v_lshl_add_u32 v135, v135, 9, v183
	global_load_dwordx4 v[8:11], v135, s[20:21]
	global_load_dwordx4 v[12:15], v135, s[20:21] offset:64
	v_add_u32_e32 v136, 2, v252
	v_med3_i32 v136, v136, 0, s14
	v_lshl_add_u32 v136, v136, 9, v183
	global_load_dwordx4 v[16:19], v136, s[20:21]
	global_load_dwordx4 v[20:23], v136, s[20:21] offset:64
	v_add_u32_e32 v135, 3, v252
	v_med3_i32 v135, v135, 0, s14
	v_lshl_add_u32 v135, v135, 9, v183
	global_load_dwordx4 v[24:27], v135, s[20:21]
	global_load_dwordx4 v[28:31], v135, s[20:21] offset:64
	v_add_u32_e32 v136, 4, v252
	v_med3_i32 v136, v136, 0, s14
	v_lshl_add_u32 v136, v136, 9, v183
	global_load_dwordx4 v[32:35], v136, s[20:21]
	global_load_dwordx4 v[36:39], v136, s[20:21] offset:64
	v_add_u32_e32 v135, 5, v252
	v_med3_i32 v135, v135, 0, s14
	v_lshl_add_u32 v135, v135, 9, v183
	global_load_dwordx4 v[40:43], v135, s[20:21]
	global_load_dwordx4 v[44:47], v135, s[20:21] offset:64
	s_add_i32 s2, s42, -64
	v_add_u32_e32 v138, s2, v164
	v_add_u32_e32 v138, s43, v138
	v_and_b32_e32 v139, 3, v138
	v_lshlrev_b32_e32 v139, s13, v139
	v_bfe_u32 v140, v138, 2, 2
	v_add_u32_e32 v139, v139, v140
	v_lshl_add_u32 v139, v139, 7, v162
	v_ashrrev_i32_e32 v138, 4, v138
	v_med3_i32 v138, v138, 0, s14
	v_lshl_add_u32 v138, v138, 9, v139
	global_load_dwordx4 v[64:67], v138, s[22:23]
	s_add_i32 s2, s42, -56
	v_add_u32_e32 v138, s2, v164
	v_add_u32_e32 v138, s43, v138
	v_and_b32_e32 v139, 3, v138
	v_lshlrev_b32_e32 v139, s13, v139
	v_bfe_u32 v140, v138, 2, 2
	v_add_u32_e32 v139, v139, v140
	v_lshl_add_u32 v139, v139, 7, v162
	v_ashrrev_i32_e32 v138, 4, v138
	v_med3_i32 v138, v138, 0, s14
	v_lshl_add_u32 v138, v138, 9, v139
	global_load_dwordx4 v[68:71], v138, s[22:23]
	s_add_i32 s2, s42, -48
	v_add_u32_e32 v138, s2, v164
	v_add_u32_e32 v138, s43, v138
	v_and_b32_e32 v139, 3, v138
	v_lshlrev_b32_e32 v139, s13, v139
	v_bfe_u32 v140, v138, 2, 2
	v_add_u32_e32 v139, v139, v140
	v_lshl_add_u32 v139, v139, 7, v162
	v_ashrrev_i32_e32 v138, 4, v138
	v_med3_i32 v138, v138, 0, s14
	v_lshl_add_u32 v138, v138, 9, v139
	global_load_dwordx4 v[72:75], v138, s[22:23]
	s_add_i32 s2, s42, -40
	v_add_u32_e32 v138, s2, v164
	v_add_u32_e32 v138, s43, v138
	v_and_b32_e32 v139, 3, v138
	v_lshlrev_b32_e32 v139, s13, v139
	v_bfe_u32 v140, v138, 2, 2
	v_add_u32_e32 v139, v139, v140
	v_lshl_add_u32 v139, v139, 7, v162
	v_ashrrev_i32_e32 v138, 4, v138
	v_med3_i32 v138, v138, 0, s14
	v_lshl_add_u32 v138, v138, 9, v139
	global_load_dwordx4 v[76:79], v138, s[22:23]
	s_add_i32 s2, s42, -32
	v_add_u32_e32 v138, s2, v164
	v_add_u32_e32 v138, s43, v138
	v_and_b32_e32 v139, 3, v138
	v_lshlrev_b32_e32 v139, s13, v139
	v_bfe_u32 v140, v138, 2, 2
	v_add_u32_e32 v139, v139, v140
	v_lshl_add_u32 v139, v139, 7, v162
	v_ashrrev_i32_e32 v138, 4, v138
	v_med3_i32 v138, v138, 0, s14
	v_lshl_add_u32 v138, v138, 9, v139
	global_load_dwordx4 v[80:83], v138, s[22:23]
	s_add_i32 s2, s42, -24
	v_add_u32_e32 v138, s2, v164
	v_add_u32_e32 v138, s43, v138
	v_and_b32_e32 v139, 3, v138
	v_lshlrev_b32_e32 v139, s13, v139
	v_bfe_u32 v140, v138, 2, 2
	v_add_u32_e32 v139, v139, v140
	v_lshl_add_u32 v139, v139, 7, v162
	v_ashrrev_i32_e32 v138, 4, v138
	v_med3_i32 v138, v138, 0, s14
	v_lshl_add_u32 v138, v138, 9, v139
	global_load_dwordx4 v[84:87], v138, s[22:23]
	s_add_i32 s2, s42, -16
	v_add_u32_e32 v138, s2, v164
	v_add_u32_e32 v138, s43, v138
	v_and_b32_e32 v139, 3, v138
	v_lshlrev_b32_e32 v139, s13, v139
	v_bfe_u32 v140, v138, 2, 2
	v_add_u32_e32 v139, v139, v140
	v_lshl_add_u32 v139, v139, 7, v162
	v_ashrrev_i32_e32 v138, 4, v138
	v_med3_i32 v138, v138, 0, s14
	v_lshl_add_u32 v138, v138, 9, v139
	global_load_dwordx4 v[88:91], v138, s[22:23]
	s_add_i32 s2, s42, -8
	v_add_u32_e32 v138, s2, v164
	v_add_u32_e32 v138, s43, v138
	v_and_b32_e32 v139, 3, v138
	v_lshlrev_b32_e32 v139, s13, v139
	v_bfe_u32 v140, v138, 2, 2
	v_add_u32_e32 v139, v139, v140
	v_lshl_add_u32 v139, v139, 7, v162
	v_ashrrev_i32_e32 v138, 4, v138
	v_med3_i32 v138, v138, 0, s14
	v_lshl_add_u32 v138, v138, 9, v139
	global_load_dwordx4 v[92:95], v138, s[22:23]
	s_add_i32 s2, s42, 0
	v_add_u32_e32 v138, s2, v164
	v_add_u32_e32 v138, s43, v138
	v_and_b32_e32 v139, 3, v138
	v_lshlrev_b32_e32 v139, s13, v139
	v_bfe_u32 v140, v138, 2, 2
	v_add_u32_e32 v139, v139, v140
	v_lshl_add_u32 v139, v139, 7, v162
	v_ashrrev_i32_e32 v138, 4, v138
	v_med3_i32 v138, v138, 0, s14
	v_lshl_add_u32 v138, v138, 9, v139
	global_load_dwordx4 v[96:99], v138, s[22:23]
	s_add_i32 s2, s42, 8
	v_add_u32_e32 v138, s2, v164
	v_add_u32_e32 v138, s43, v138
	v_and_b32_e32 v139, 3, v138
	v_lshlrev_b32_e32 v139, s13, v139
	v_bfe_u32 v140, v138, 2, 2
	v_add_u32_e32 v139, v139, v140
	v_lshl_add_u32 v139, v139, 7, v162
	v_ashrrev_i32_e32 v138, 4, v138
	v_med3_i32 v138, v138, 0, s14
	v_lshl_add_u32 v138, v138, 9, v139
	global_load_dwordx4 v[100:103], v138, s[22:23]
	s_add_i32 s2, s42, 16
	v_add_u32_e32 v138, s2, v164
	v_add_u32_e32 v138, s43, v138
	v_and_b32_e32 v139, 3, v138
	v_lshlrev_b32_e32 v139, s13, v139
	v_bfe_u32 v140, v138, 2, 2
	v_add_u32_e32 v139, v139, v140
	v_lshl_add_u32 v139, v139, 7, v162
	v_ashrrev_i32_e32 v138, 4, v138
	v_med3_i32 v138, v138, 0, s14
	v_lshl_add_u32 v138, v138, 9, v139
	global_load_dwordx4 v[104:107], v138, s[22:23]
	s_add_i32 s2, s42, 24
	v_add_u32_e32 v138, s2, v164
	v_add_u32_e32 v138, s43, v138
	v_and_b32_e32 v139, 3, v138
	v_lshlrev_b32_e32 v139, s13, v139
	v_bfe_u32 v140, v138, 2, 2
	v_add_u32_e32 v139, v139, v140
	v_lshl_add_u32 v139, v139, 7, v162
	v_ashrrev_i32_e32 v138, 4, v138
	v_med3_i32 v138, v138, 0, s14
	v_lshl_add_u32 v138, v138, 9, v139
	global_load_dwordx4 v[108:111], v138, s[22:23]
.Latt_unit:
	s_mov_b32 s33, s12
	s_mov_b32 s34, s15
	s_mov_b32 s35, s16
	s_mov_b32 s36, s17
	s_mov_b32 s38, s14
	s_mov_b32 s39, s13
	s_mov_b32 s24, s20
	s_mov_b32 s25, s21
	s_mov_b32 s26, s22
	s_mov_b32 s27, s23
	s_mov_b32 s40, s42
	s_mov_b32 s41, s43
	v_mov_b32_e32 v173, v176
	v_mov_b32_e32 v174, v177
	v_mov_b32_e32 v175, v178
	v_mov_b32_e32 v179, v183
	v_mov_b32_e32 v182, v252
	s_lshr_b32 s44, s33, 0
	s_lshr_b32 s2, s0, 2
	s_lshl_b32 s2, s2, 5
	s_lshr_b32 s3, s15, 2
	s_add_i32 s42, s3, s2
	s_and_b32 s43, s0, 3
	s_waitcnt vmcnt(12)
	v_mov_b32_e32 v132, 0
	v_mov_b32_e32 v133, 0
	v_mfma_f32_16x16x32_bf16 v[236:239], v[0:3], v[48:51], 0
	v_mfma_f32_16x16x32_bf16 v[236:239], v[4:7], v[52:55], v[236:239]
	v_mfma_f32_16x16x32_bf16 v[240:243], v[8:11], v[48:51], 0
	v_mfma_f32_16x16x32_bf16 v[240:243], v[12:15], v[52:55], v[240:243]
	v_mfma_f32_16x16x32_bf16 v[248:251], v[8:11], v[56:59], 0
	v_mfma_f32_16x16x32_bf16 v[248:251], v[12:15], v[60:63], v[248:251]
	s_nop 7
	v_min_f32_e32 v152, 0x42a00000, v236
	v_min_f32_e32 v153, 0x42a00000, v237
	v_min_f32_e32 v154, 0x42a00000, v238
	v_min_f32_e32 v155, 0x42a00000, v239
	v_mfma_f32_16x16x32_bf16 v[236:239], v[16:19], v[48:51], 0
	v_mfma_f32_16x16x32_bf16 v[236:239], v[20:23], v[52:55], v[236:239]
	v_mfma_f32_16x16x32_bf16 v[244:247], v[16:19], v[56:59], 0
	v_mfma_f32_16x16x32_bf16 v[244:247], v[20:23], v[60:63], v[244:247]
	v_add_u32_e32 v136, 6, v182
	v_med3_i32 v136, v136, 0, s38
	v_lshl_add_u32 v136, v136, 9, v179
	global_load_dwordx4 v[0:3], v136, s[24:25]
	global_load_dwordx4 v[4:7], v136, s[24:25] offset:64
	v_mul_f32_e32 v152, 0x3fb8aa3b, v152
	v_mul_f32_e32 v153, 0x3fb8aa3b, v153
	v_mul_f32_e32 v154, 0x3fb8aa3b, v154
	v_mul_f32_e32 v155, 0x3fb8aa3b, v155
	v_exp_f32_e32 v152, v152
	v_exp_f32_e32 v153, v153
	v_exp_f32_e32 v154, v154
	v_exp_f32_e32 v155, v155
	v_add_u32_e32 v138, 0, v175
	v_add_u32_e32 v139, 1, v175
	v_add_u32_e32 v140, 2, v175
	v_add_u32_e32 v141, 3, v175
	v_cmp_gt_u32_e64 s[70:71], s44, v138
	v_cmp_gt_u32_e64 s[72:73], s44, v139
	v_cmp_gt_u32_e64 s[74:75], s44, v140
	v_cmp_gt_u32_e64 s[76:77], s44, v141
	v_cndmask_b32_e64 v152, 0, v152, s[54:55]
	v_cndmask_b32_e64 v153, 0, v153, s[56:57]
	v_cndmask_b32_e64 v154, 0, v154, s[58:59]
	v_cndmask_b32_e64 v155, 0, v155, s[60:61]
	v_cndmask_b32_e64 v152, 0, v152, s[70:71]
	v_cndmask_b32_e64 v153, 0, v153, s[72:73]
	v_cndmask_b32_e64 v154, 0, v154, s[74:75]
	v_cndmask_b32_e64 v155, 0, v155, s[76:77]
	v_add_f32_e32 v132, v132, v152
	v_add_f32_e32 v132, v132, v153
	v_add_f32_e32 v132, v132, v154
	v_add_f32_e32 v132, v132, v155
	v_cvt_pk_bf16_f32 v112, v152, v153
	v_cvt_pk_bf16_f32 v113, v154, v155
	v_min_f32_e32 v152, 0x42a00000, v240
	v_min_f32_e32 v153, 0x42a00000, v241
	v_min_f32_e32 v154, 0x42a00000, v242
	v_min_f32_e32 v155, 0x42a00000, v243
	v_min_f32_e32 v156, 0x42a00000, v248
	v_min_f32_e32 v157, 0x42a00000, v249
	v_min_f32_e32 v158, 0x42a00000, v250
	v_min_f32_e32 v159, 0x42a00000, v251
	v_mfma_f32_16x16x32_bf16 v[240:243], v[24:27], v[48:51], 0
	v_mfma_f32_16x16x32_bf16 v[240:243], v[28:31], v[52:55], v[240:243]
	v_mfma_f32_16x16x32_bf16 v[248:251], v[24:27], v[56:59], 0
	v_mfma_f32_16x16x32_bf16 v[248:251], v[28:31], v[60:63], v[248:251]
	v_add_u32_e32 v135, 7, v182
	v_med3_i32 v135, v135, 0, s38
	v_lshl_add_u32 v135, v135, 9, v179
	global_load_dwordx4 v[8:11], v135, s[24:25]
	global_load_dwordx4 v[12:15], v135, s[24:25] offset:64
	v_mul_f32_e32 v152, 0x3fb8aa3b, v152
	v_mul_f32_e32 v153, 0x3fb8aa3b, v153
	v_mul_f32_e32 v154, 0x3fb8aa3b, v154
	v_mul_f32_e32 v155, 0x3fb8aa3b, v155
	v_exp_f32_e32 v152, v152
	v_exp_f32_e32 v153, v153
	v_exp_f32_e32 v154, v154
	v_exp_f32_e32 v155, v155
	v_add_u32_e32 v138, 16, v175
	v_add_u32_e32 v139, 17, v175
	v_add_u32_e32 v140, 18, v175
	v_add_u32_e32 v141, 19, v175
	v_cmp_gt_u32_e64 s[70:71], s44, v138
	v_cmp_gt_u32_e64 s[72:73], s44, v139
	v_cmp_gt_u32_e64 s[74:75], s44, v140
	v_cmp_gt_u32_e64 s[76:77], s44, v141
	v_cndmask_b32_e64 v152, 0, v152, s[70:71]
	v_cndmask_b32_e64 v153, 0, v153, s[72:73]
	v_cndmask_b32_e64 v154, 0, v154, s[74:75]
	v_cndmask_b32_e64 v155, 0, v155, s[76:77]
	v_add_f32_e32 v132, v132, v152
	v_add_f32_e32 v132, v132, v153
	v_add_f32_e32 v132, v132, v154
	v_add_f32_e32 v132, v132, v155
	v_cvt_pk_bf16_f32 v114, v152, v153
	v_cvt_pk_bf16_f32 v115, v154, v155
	v_mul_f32_e32 v156, 0x3fb8aa3b, v156
	v_mul_f32_e32 v157, 0x3fb8aa3b, v157
	v_mul_f32_e32 v158, 0x3fb8aa3b, v158
	v_mul_f32_e32 v159, 0x3fb8aa3b, v159
	v_exp_f32_e32 v156, v156
	v_exp_f32_e32 v157, v157
	v_exp_f32_e32 v158, v158
	v_exp_f32_e32 v159, v159
	v_add_u32_e32 v138, 16, v175
	v_add_u32_e32 v139, 17, v175
	v_add_u32_e32 v140, 18, v175
	v_add_u32_e32 v141, 19, v175
	v_cmp_gt_u32_e64 s[70:71], s44, v138
	v_cmp_gt_u32_e64 s[72:73], s44, v139
	v_cmp_gt_u32_e64 s[74:75], s44, v140
	v_cmp_gt_u32_e64 s[76:77], s44, v141
	v_cndmask_b32_e64 v156, 0, v156, s[54:55]
	v_cndmask_b32_e64 v157, 0, v157, s[56:57]
	v_cndmask_b32_e64 v158, 0, v158, s[58:59]
	v_cndmask_b32_e64 v159, 0, v159, s[60:61]
	v_cndmask_b32_e64 v156, 0, v156, s[70:71]
	v_cndmask_b32_e64 v157, 0, v157, s[72:73]
	v_cndmask_b32_e64 v158, 0, v158, s[74:75]
	v_cndmask_b32_e64 v159, 0, v159, s[76:77]
	v_add_f32_e32 v133, v133, v156
	v_add_f32_e32 v133, v133, v157
	v_add_f32_e32 v133, v133, v158
	v_add_f32_e32 v133, v133, v159
	v_cvt_pk_bf16_f32 v186, v156, v157
	v_cvt_pk_bf16_f32 v187, v158, v159
	v_min_f32_e32 v152, 0x42a00000, v236
	v_min_f32_e32 v153, 0x42a00000, v237
	v_min_f32_e32 v154, 0x42a00000, v238
	v_min_f32_e32 v155, 0x42a00000, v239
	v_min_f32_e32 v156, 0x42a00000, v244
	v_min_f32_e32 v157, 0x42a00000, v245
	v_min_f32_e32 v158, 0x42a00000, v246
	v_min_f32_e32 v159, 0x42a00000, v247
	v_mfma_f32_16x16x32_bf16 v[236:239], v[32:35], v[48:51], 0
	v_mfma_f32_16x16x32_bf16 v[236:239], v[36:39], v[52:55], v[236:239]
	v_mfma_f32_16x16x32_bf16 v[244:247], v[32:35], v[56:59], 0
	v_mfma_f32_16x16x32_bf16 v[244:247], v[36:39], v[60:63], v[244:247]
	v_add_u32_e32 v136, 8, v182
	v_med3_i32 v136, v136, 0, s38
	v_lshl_add_u32 v136, v136, 9, v179
	global_load_dwordx4 v[16:19], v136, s[24:25]
	global_load_dwordx4 v[20:23], v136, s[24:25] offset:64
	v_mul_f32_e32 v152, 0x3fb8aa3b, v152
	v_mul_f32_e32 v153, 0x3fb8aa3b, v153
	v_mul_f32_e32 v154, 0x3fb8aa3b, v154
	v_mul_f32_e32 v155, 0x3fb8aa3b, v155
	v_exp_f32_e32 v152, v152
	v_exp_f32_e32 v153, v153
	v_exp_f32_e32 v154, v154
	v_exp_f32_e32 v155, v155
	v_add_u32_e32 v138, 32, v175
	v_add_u32_e32 v139, 33, v175
	v_add_u32_e32 v140, 34, v175
	v_add_u32_e32 v141, 35, v175
	v_cmp_gt_u32_e64 s[70:71], s44, v138
	v_cmp_gt_u32_e64 s[72:73], s44, v139
	v_cmp_gt_u32_e64 s[74:75], s44, v140
	v_cmp_gt_u32_e64 s[76:77], s44, v141
	v_cndmask_b32_e64 v152, 0, v152, s[70:71]
	v_cndmask_b32_e64 v153, 0, v153, s[72:73]
	v_cndmask_b32_e64 v154, 0, v154, s[74:75]
	v_cndmask_b32_e64 v155, 0, v155, s[76:77]
	v_add_f32_e32 v132, v132, v152
	v_add_f32_e32 v132, v132, v153
	v_add_f32_e32 v132, v132, v154
	v_add_f32_e32 v132, v132, v155
	v_cvt_pk_bf16_f32 v116, v152, v153
	v_cvt_pk_bf16_f32 v117, v154, v155
	v_mul_f32_e32 v156, 0x3fb8aa3b, v156
	v_mul_f32_e32 v157, 0x3fb8aa3b, v157
	v_mul_f32_e32 v158, 0x3fb8aa3b, v158
	v_mul_f32_e32 v159, 0x3fb8aa3b, v159
	v_exp_f32_e32 v156, v156
	v_exp_f32_e32 v157, v157
	v_exp_f32_e32 v158, v158
	v_exp_f32_e32 v159, v159
	v_add_u32_e32 v138, 32, v175
	v_add_u32_e32 v139, 33, v175
	v_add_u32_e32 v140, 34, v175
	v_add_u32_e32 v141, 35, v175
	v_cmp_gt_u32_e64 s[70:71], s44, v138
	v_cmp_gt_u32_e64 s[72:73], s44, v139
	v_cmp_gt_u32_e64 s[74:75], s44, v140
	v_cmp_gt_u32_e64 s[76:77], s44, v141
	v_cndmask_b32_e64 v156, 0, v156, s[70:71]
	v_cndmask_b32_e64 v157, 0, v157, s[72:73]
	v_cndmask_b32_e64 v158, 0, v158, s[74:75]
	v_cndmask_b32_e64 v159, 0, v159, s[76:77]
	v_add_f32_e32 v133, v133, v156
	v_add_f32_e32 v133, v133, v157
	v_add_f32_e32 v133, v133, v158
	v_add_f32_e32 v133, v133, v159
	v_cvt_pk_bf16_f32 v188, v156, v157
	v_cvt_pk_bf16_f32 v189, v158, v159
	v_min_f32_e32 v152, 0x42a00000, v240
	v_min_f32_e32 v153, 0x42a00000, v241
	v_min_f32_e32 v154, 0x42a00000, v242
	v_min_f32_e32 v155, 0x42a00000, v243
	v_min_f32_e32 v156, 0x42a00000, v248
	v_min_f32_e32 v157, 0x42a00000, v249
	v_min_f32_e32 v158, 0x42a00000, v250
	v_min_f32_e32 v159, 0x42a00000, v251
	v_mfma_f32_16x16x32_bf16 v[240:243], v[40:43], v[48:51], 0
	v_mfma_f32_16x16x32_bf16 v[240:243], v[44:47], v[52:55], v[240:243]
	v_mfma_f32_16x16x32_bf16 v[248:251], v[40:43], v[56:59], 0
	v_mfma_f32_16x16x32_bf16 v[248:251], v[44:47], v[60:63], v[248:251]
	v_add_u32_e32 v135, 9, v182
	v_med3_i32 v135, v135, 0, s38
	v_lshl_add_u32 v135, v135, 9, v179
	global_load_dwordx4 v[24:27], v135, s[24:25]
	global_load_dwordx4 v[28:31], v135, s[24:25] offset:64
	v_mul_f32_e32 v152, 0x3fb8aa3b, v152
	v_mul_f32_e32 v153, 0x3fb8aa3b, v153
	v_mul_f32_e32 v154, 0x3fb8aa3b, v154
	v_mul_f32_e32 v155, 0x3fb8aa3b, v155
	v_exp_f32_e32 v152, v152
	v_exp_f32_e32 v153, v153
	v_exp_f32_e32 v154, v154
	v_exp_f32_e32 v155, v155
	v_add_u32_e32 v138, 48, v175
	v_add_u32_e32 v139, 49, v175
	v_add_u32_e32 v140, 50, v175
	v_add_u32_e32 v141, 51, v175
	v_cmp_gt_u32_e64 s[70:71], s44, v138
	v_cmp_gt_u32_e64 s[72:73], s44, v139
	v_cmp_gt_u32_e64 s[74:75], s44, v140
	v_cmp_gt_u32_e64 s[76:77], s44, v141
	v_cndmask_b32_e64 v152, 0, v152, s[70:71]
	v_cndmask_b32_e64 v153, 0, v153, s[72:73]
	v_cndmask_b32_e64 v154, 0, v154, s[74:75]
	v_cndmask_b32_e64 v155, 0, v155, s[76:77]
	v_add_f32_e32 v132, v132, v152
	v_add_f32_e32 v132, v132, v153
	v_add_f32_e32 v132, v132, v154
	v_add_f32_e32 v132, v132, v155
	v_cvt_pk_bf16_f32 v118, v152, v153
	v_cvt_pk_bf16_f32 v119, v154, v155
	v_mul_f32_e32 v156, 0x3fb8aa3b, v156
	v_mul_f32_e32 v157, 0x3fb8aa3b, v157
	v_mul_f32_e32 v158, 0x3fb8aa3b, v158
	v_mul_f32_e32 v159, 0x3fb8aa3b, v159
	v_exp_f32_e32 v156, v156
	v_exp_f32_e32 v157, v157
	v_exp_f32_e32 v158, v158
	v_exp_f32_e32 v159, v159
	v_add_u32_e32 v138, 48, v175
	v_add_u32_e32 v139, 49, v175
	v_add_u32_e32 v140, 50, v175
	v_add_u32_e32 v141, 51, v175
	v_cmp_gt_u32_e64 s[70:71], s44, v138
	v_cmp_gt_u32_e64 s[72:73], s44, v139
	v_cmp_gt_u32_e64 s[74:75], s44, v140
	v_cmp_gt_u32_e64 s[76:77], s44, v141
	v_cndmask_b32_e64 v156, 0, v156, s[70:71]
	v_cndmask_b32_e64 v157, 0, v157, s[72:73]
	v_cndmask_b32_e64 v158, 0, v158, s[74:75]
	v_cndmask_b32_e64 v159, 0, v159, s[76:77]
	v_add_f32_e32 v133, v133, v156
	v_add_f32_e32 v133, v133, v157
	v_add_f32_e32 v133, v133, v158
	v_add_f32_e32 v133, v133, v159
	v_cvt_pk_bf16_f32 v190, v156, v157
	v_cvt_pk_bf16_f32 v191, v158, v159
	v_min_f32_e32 v152, 0x42a00000, v236
	v_min_f32_e32 v153, 0x42a00000, v237
	v_min_f32_e32 v154, 0x42a00000, v238
	v_min_f32_e32 v155, 0x42a00000, v239
	v_min_f32_e32 v156, 0x42a00000, v244
	v_min_f32_e32 v157, 0x42a00000, v245
	v_min_f32_e32 v158, 0x42a00000, v246
	v_min_f32_e32 v159, 0x42a00000, v247
	s_waitcnt vmcnt(6)
	v_mfma_f32_16x16x32_bf16 v[236:239], v[0:3], v[48:51], 0
	v_mfma_f32_16x16x32_bf16 v[236:239], v[4:7], v[52:55], v[236:239]
	v_mfma_f32_16x16x32_bf16 v[244:247], v[0:3], v[56:59], 0
	v_mfma_f32_16x16x32_bf16 v[244:247], v[4:7], v[60:63], v[244:247]
	v_mul_f32_e32 v152, 0x3fb8aa3b, v152
	v_mul_f32_e32 v153, 0x3fb8aa3b, v153
	v_mul_f32_e32 v154, 0x3fb8aa3b, v154
	v_mul_f32_e32 v155, 0x3fb8aa3b, v155
	v_exp_f32_e32 v152, v152
	v_exp_f32_e32 v153, v153
	v_exp_f32_e32 v154, v154
	v_exp_f32_e32 v155, v155
	v_add_u32_e32 v138, 64, v175
	v_add_u32_e32 v139, 0x41, v175
	v_add_u32_e32 v140, 0x42, v175
	v_add_u32_e32 v141, 0x43, v175
	v_cmp_gt_u32_e64 s[70:71], s44, v138
	v_cmp_gt_u32_e64 s[72:73], s44, v139
	v_cmp_gt_u32_e64 s[74:75], s44, v140
	v_cmp_gt_u32_e64 s[76:77], s44, v141
	v_cndmask_b32_e64 v152, 0, v152, s[70:71]
	v_cndmask_b32_e64 v153, 0, v153, s[72:73]
	v_cndmask_b32_e64 v154, 0, v154, s[74:75]
	v_cndmask_b32_e64 v155, 0, v155, s[76:77]
	v_add_f32_e32 v132, v132, v152
	v_add_f32_e32 v132, v132, v153
	v_add_f32_e32 v132, v132, v154
	v_add_f32_e32 v132, v132, v155
	v_cvt_pk_bf16_f32 v120, v152, v153
	v_cvt_pk_bf16_f32 v121, v154, v155
	v_mul_f32_e32 v156, 0x3fb8aa3b, v156
	v_mul_f32_e32 v157, 0x3fb8aa3b, v157
	v_mul_f32_e32 v158, 0x3fb8aa3b, v158
	v_mul_f32_e32 v159, 0x3fb8aa3b, v159
	v_exp_f32_e32 v156, v156
	v_exp_f32_e32 v157, v157
	v_exp_f32_e32 v158, v158
	v_exp_f32_e32 v159, v159
	v_add_u32_e32 v138, 64, v175
	v_add_u32_e32 v139, 0x41, v175
	v_add_u32_e32 v140, 0x42, v175
	v_add_u32_e32 v141, 0x43, v175
	v_cmp_gt_u32_e64 s[70:71], s44, v138
	v_cmp_gt_u32_e64 s[72:73], s44, v139
	v_cmp_gt_u32_e64 s[74:75], s44, v140
	v_cmp_gt_u32_e64 s[76:77], s44, v141
	v_cndmask_b32_e64 v156, 0, v156, s[70:71]
	v_cndmask_b32_e64 v157, 0, v157, s[72:73]
	v_cndmask_b32_e64 v158, 0, v158, s[74:75]
	v_cndmask_b32_e64 v159, 0, v159, s[76:77]
	v_add_f32_e32 v133, v133, v156
	v_add_f32_e32 v133, v133, v157
	v_add_f32_e32 v133, v133, v158
	v_add_f32_e32 v133, v133, v159
	v_cvt_pk_bf16_f32 v192, v156, v157
	v_cvt_pk_bf16_f32 v193, v158, v159
	v_min_f32_e32 v152, 0x42a00000, v240
	v_min_f32_e32 v153, 0x42a00000, v241
	v_min_f32_e32 v154, 0x42a00000, v242
	v_min_f32_e32 v155, 0x42a00000, v243
	v_min_f32_e32 v156, 0x42a00000, v248
	v_min_f32_e32 v157, 0x42a00000, v249
	v_min_f32_e32 v158, 0x42a00000, v250
	v_min_f32_e32 v159, 0x42a00000, v251
	s_waitcnt vmcnt(4)
	v_mfma_f32_16x16x32_bf16 v[240:243], v[8:11], v[48:51], 0
	v_mfma_f32_16x16x32_bf16 v[240:243], v[12:15], v[52:55], v[240:243]
	v_mfma_f32_16x16x32_bf16 v[248:251], v[8:11], v[56:59], 0
	v_mfma_f32_16x16x32_bf16 v[248:251], v[12:15], v[60:63], v[248:251]
	v_mul_f32_e32 v152, 0x3fb8aa3b, v152
	v_mul_f32_e32 v153, 0x3fb8aa3b, v153
	v_mul_f32_e32 v154, 0x3fb8aa3b, v154
	v_mul_f32_e32 v155, 0x3fb8aa3b, v155
	v_exp_f32_e32 v152, v152
	v_exp_f32_e32 v153, v153
	v_exp_f32_e32 v154, v154
	v_exp_f32_e32 v155, v155
	v_add_u32_e32 v138, 0x50, v175
	v_add_u32_e32 v139, 0x51, v175
	v_add_u32_e32 v140, 0x52, v175
	v_add_u32_e32 v141, 0x53, v175
	v_cmp_gt_u32_e64 s[70:71], s44, v138
	v_cmp_gt_u32_e64 s[72:73], s44, v139
	v_cmp_gt_u32_e64 s[74:75], s44, v140
	v_cmp_gt_u32_e64 s[76:77], s44, v141
	v_cndmask_b32_e64 v152, 0, v152, s[70:71]
	v_cndmask_b32_e64 v153, 0, v153, s[72:73]
	v_cndmask_b32_e64 v154, 0, v154, s[74:75]
	v_cndmask_b32_e64 v155, 0, v155, s[76:77]
	v_add_f32_e32 v132, v132, v152
	v_add_f32_e32 v132, v132, v153
	v_add_f32_e32 v132, v132, v154
	v_add_f32_e32 v132, v132, v155
	v_cvt_pk_bf16_f32 v122, v152, v153
	v_cvt_pk_bf16_f32 v123, v154, v155
	v_mul_f32_e32 v156, 0x3fb8aa3b, v156
	v_mul_f32_e32 v157, 0x3fb8aa3b, v157
	v_mul_f32_e32 v158, 0x3fb8aa3b, v158
	v_mul_f32_e32 v159, 0x3fb8aa3b, v159
	v_exp_f32_e32 v156, v156
	v_exp_f32_e32 v157, v157
	v_exp_f32_e32 v158, v158
	v_exp_f32_e32 v159, v159
	v_add_u32_e32 v138, 0x50, v175
	v_add_u32_e32 v139, 0x51, v175
	v_add_u32_e32 v140, 0x52, v175
	v_add_u32_e32 v141, 0x53, v175
	v_cmp_gt_u32_e64 s[70:71], s44, v138
	v_cmp_gt_u32_e64 s[72:73], s44, v139
	v_cmp_gt_u32_e64 s[74:75], s44, v140
	v_cmp_gt_u32_e64 s[76:77], s44, v141
	v_cndmask_b32_e64 v156, 0, v156, s[70:71]
	v_cndmask_b32_e64 v157, 0, v157, s[72:73]
	v_cndmask_b32_e64 v158, 0, v158, s[74:75]
	v_cndmask_b32_e64 v159, 0, v159, s[76:77]
	v_add_f32_e32 v133, v133, v156
	v_add_f32_e32 v133, v133, v157
	v_add_f32_e32 v133, v133, v158
	v_add_f32_e32 v133, v133, v159
	v_cvt_pk_bf16_f32 v194, v156, v157
	v_cvt_pk_bf16_f32 v195, v158, v159
	v_min_f32_e32 v152, 0x42a00000, v236
	v_min_f32_e32 v153, 0x42a00000, v237
	v_min_f32_e32 v154, 0x42a00000, v238
	v_min_f32_e32 v155, 0x42a00000, v239
	v_min_f32_e32 v156, 0x42a00000, v244
	v_min_f32_e32 v157, 0x42a00000, v245
	v_min_f32_e32 v158, 0x42a00000, v246
	v_min_f32_e32 v159, 0x42a00000, v247
	s_waitcnt vmcnt(2)
	v_mfma_f32_16x16x32_bf16 v[236:239], v[16:19], v[48:51], 0
	v_mfma_f32_16x16x32_bf16 v[236:239], v[20:23], v[52:55], v[236:239]
	v_mfma_f32_16x16x32_bf16 v[244:247], v[16:19], v[56:59], 0
	v_mfma_f32_16x16x32_bf16 v[244:247], v[20:23], v[60:63], v[244:247]
	v_mul_f32_e32 v152, 0x3fb8aa3b, v152
	v_mul_f32_e32 v153, 0x3fb8aa3b, v153
	v_mul_f32_e32 v154, 0x3fb8aa3b, v154
	v_mul_f32_e32 v155, 0x3fb8aa3b, v155
	v_exp_f32_e32 v152, v152
	v_exp_f32_e32 v153, v153
	v_exp_f32_e32 v154, v154
	v_exp_f32_e32 v155, v155
	v_add_u32_e32 v138, 0x60, v175
	v_add_u32_e32 v139, 0x61, v175
	v_add_u32_e32 v140, 0x62, v175
	v_add_u32_e32 v141, 0x63, v175
	v_cmp_gt_u32_e64 s[70:71], s44, v138
	v_cmp_gt_u32_e64 s[72:73], s44, v139
	v_cmp_gt_u32_e64 s[74:75], s44, v140
	v_cmp_gt_u32_e64 s[76:77], s44, v141
	v_cndmask_b32_e64 v152, 0, v152, s[70:71]
	v_cndmask_b32_e64 v153, 0, v153, s[72:73]
	v_cndmask_b32_e64 v154, 0, v154, s[74:75]
	v_cndmask_b32_e64 v155, 0, v155, s[76:77]
	v_add_f32_e32 v132, v132, v152
	v_add_f32_e32 v132, v132, v153
	v_add_f32_e32 v132, v132, v154
	v_add_f32_e32 v132, v132, v155
	v_cvt_pk_bf16_f32 v124, v152, v153
	v_cvt_pk_bf16_f32 v125, v154, v155
	v_mul_f32_e32 v156, 0x3fb8aa3b, v156
	v_mul_f32_e32 v157, 0x3fb8aa3b, v157
	v_mul_f32_e32 v158, 0x3fb8aa3b, v158
	v_mul_f32_e32 v159, 0x3fb8aa3b, v159
	v_exp_f32_e32 v156, v156
	v_exp_f32_e32 v157, v157
	v_exp_f32_e32 v158, v158
	v_exp_f32_e32 v159, v159
	v_add_u32_e32 v138, 0x60, v175
	v_add_u32_e32 v139, 0x61, v175
	v_add_u32_e32 v140, 0x62, v175
	v_add_u32_e32 v141, 0x63, v175
	v_cmp_gt_u32_e64 s[70:71], s44, v138
	v_cmp_gt_u32_e64 s[72:73], s44, v139
	v_cmp_gt_u32_e64 s[74:75], s44, v140
	v_cmp_gt_u32_e64 s[76:77], s44, v141
	v_cndmask_b32_e64 v156, 0, v156, s[70:71]
	v_cndmask_b32_e64 v157, 0, v157, s[72:73]
	v_cndmask_b32_e64 v158, 0, v158, s[74:75]
	v_cndmask_b32_e64 v159, 0, v159, s[76:77]
	v_add_f32_e32 v133, v133, v156
	v_add_f32_e32 v133, v133, v157
	v_add_f32_e32 v133, v133, v158
	v_add_f32_e32 v133, v133, v159
	v_cvt_pk_bf16_f32 v196, v156, v157
	v_cvt_pk_bf16_f32 v197, v158, v159
	v_min_f32_e32 v152, 0x42a00000, v240
	v_min_f32_e32 v153, 0x42a00000, v241
	v_min_f32_e32 v154, 0x42a00000, v242
	v_min_f32_e32 v155, 0x42a00000, v243
	v_min_f32_e32 v156, 0x42a00000, v248
	v_min_f32_e32 v157, 0x42a00000, v249
	v_min_f32_e32 v158, 0x42a00000, v250
	v_min_f32_e32 v159, 0x42a00000, v251
	s_waitcnt vmcnt(0)
	v_mfma_f32_16x16x32_bf16 v[248:251], v[24:27], v[56:59], 0
	v_mfma_f32_16x16x32_bf16 v[248:251], v[28:31], v[60:63], v[248:251]
	v_mul_f32_e32 v152, 0x3fb8aa3b, v152
	v_mul_f32_e32 v153, 0x3fb8aa3b, v153
	v_mul_f32_e32 v154, 0x3fb8aa3b, v154
	v_mul_f32_e32 v155, 0x3fb8aa3b, v155
	v_exp_f32_e32 v152, v152
	v_exp_f32_e32 v153, v153
	v_exp_f32_e32 v154, v154
	v_exp_f32_e32 v155, v155
	v_add_u32_e32 v138, 0x70, v175
	v_add_u32_e32 v139, 0x71, v175
	v_add_u32_e32 v140, 0x72, v175
	v_add_u32_e32 v141, 0x73, v175
	v_cmp_gt_u32_e64 s[70:71], s44, v138
	v_cmp_gt_u32_e64 s[72:73], s44, v139
	v_cmp_gt_u32_e64 s[74:75], s44, v140
	v_cmp_gt_u32_e64 s[76:77], s44, v141
	v_cndmask_b32_e64 v152, 0, v152, s[70:71]
	v_cndmask_b32_e64 v153, 0, v153, s[72:73]
	v_cndmask_b32_e64 v154, 0, v154, s[74:75]
	v_cndmask_b32_e64 v155, 0, v155, s[76:77]
	v_add_f32_e32 v132, v132, v152
	v_add_f32_e32 v132, v132, v153
	v_add_f32_e32 v132, v132, v154
	v_add_f32_e32 v132, v132, v155
	v_cvt_pk_bf16_f32 v126, v152, v153
	v_cvt_pk_bf16_f32 v127, v154, v155
	v_mul_f32_e32 v156, 0x3fb8aa3b, v156
	v_mul_f32_e32 v157, 0x3fb8aa3b, v157
	v_mul_f32_e32 v158, 0x3fb8aa3b, v158
	v_mul_f32_e32 v159, 0x3fb8aa3b, v159
	v_exp_f32_e32 v156, v156
	v_exp_f32_e32 v157, v157
	v_exp_f32_e32 v158, v158
	v_exp_f32_e32 v159, v159
	v_add_u32_e32 v138, 0x70, v175
	v_add_u32_e32 v139, 0x71, v175
	v_add_u32_e32 v140, 0x72, v175
	v_add_u32_e32 v141, 0x73, v175
	v_cmp_gt_u32_e64 s[70:71], s44, v138
	v_cmp_gt_u32_e64 s[72:73], s44, v139
	v_cmp_gt_u32_e64 s[74:75], s44, v140
	v_cmp_gt_u32_e64 s[76:77], s44, v141
	v_cndmask_b32_e64 v156, 0, v156, s[70:71]
	v_cndmask_b32_e64 v157, 0, v157, s[72:73]
	v_cndmask_b32_e64 v158, 0, v158, s[74:75]
	v_cndmask_b32_e64 v159, 0, v159, s[76:77]
	v_add_f32_e32 v133, v133, v156
	v_add_f32_e32 v133, v133, v157
	v_add_f32_e32 v133, v133, v158
	v_add_f32_e32 v133, v133, v159
	v_cvt_pk_bf16_f32 v198, v156, v157
	v_cvt_pk_bf16_f32 v199, v158, v159
	v_min_f32_e32 v152, 0x42a00000, v236
	v_min_f32_e32 v153, 0x42a00000, v237
	v_min_f32_e32 v154, 0x42a00000, v238
	v_min_f32_e32 v155, 0x42a00000, v239
	v_min_f32_e32 v156, 0x42a00000, v244
	v_min_f32_e32 v157, 0x42a00000, v245
	v_min_f32_e32 v158, 0x42a00000, v246
	v_min_f32_e32 v159, 0x42a00000, v247
	v_mul_f32_e32 v152, 0x3fb8aa3b, v152
	v_mul_f32_e32 v153, 0x3fb8aa3b, v153
	v_mul_f32_e32 v154, 0x3fb8aa3b, v154
	v_mul_f32_e32 v155, 0x3fb8aa3b, v155
	v_exp_f32_e32 v152, v152
	v_exp_f32_e32 v153, v153
	v_exp_f32_e32 v154, v154
	v_exp_f32_e32 v155, v155
	v_add_u32_e32 v138, 0x80, v175
	v_add_u32_e32 v139, 0x81, v175
	v_add_u32_e32 v140, 0x82, v175
	v_add_u32_e32 v141, 0x83, v175
	v_cmp_gt_u32_e64 s[70:71], s44, v138
	v_cmp_gt_u32_e64 s[72:73], s44, v139
	v_cmp_gt_u32_e64 s[74:75], s44, v140
	v_cmp_gt_u32_e64 s[76:77], s44, v141
	v_cndmask_b32_e64 v152, 0, v152, s[62:63]
	v_cndmask_b32_e64 v153, 0, v153, s[64:65]
	v_cndmask_b32_e64 v154, 0, v154, s[66:67]
	v_cndmask_b32_e64 v155, 0, v155, s[68:69]
	v_cndmask_b32_e64 v152, 0, v152, s[70:71]
	v_cndmask_b32_e64 v153, 0, v153, s[72:73]
	v_cndmask_b32_e64 v154, 0, v154, s[74:75]
	v_cndmask_b32_e64 v155, 0, v155, s[76:77]
	v_add_f32_e32 v132, v132, v152
	v_add_f32_e32 v132, v132, v153
	v_add_f32_e32 v132, v132, v154
	v_add_f32_e32 v132, v132, v155
	v_cvt_pk_bf16_f32 v128, v152, v153
	v_cvt_pk_bf16_f32 v129, v154, v155
	v_mul_f32_e32 v156, 0x3fb8aa3b, v156
	v_mul_f32_e32 v157, 0x3fb8aa3b, v157
	v_mul_f32_e32 v158, 0x3fb8aa3b, v158
	v_mul_f32_e32 v159, 0x3fb8aa3b, v159
	v_exp_f32_e32 v156, v156
	v_exp_f32_e32 v157, v157
	v_exp_f32_e32 v158, v158
	v_exp_f32_e32 v159, v159
	v_add_u32_e32 v138, 0x80, v175
	v_add_u32_e32 v139, 0x81, v175
	v_add_u32_e32 v140, 0x82, v175
	v_add_u32_e32 v141, 0x83, v175
	v_cmp_gt_u32_e64 s[70:71], s44, v138
	v_cmp_gt_u32_e64 s[72:73], s44, v139
	v_cmp_gt_u32_e64 s[74:75], s44, v140
	v_cmp_gt_u32_e64 s[76:77], s44, v141
	v_cndmask_b32_e64 v156, 0, v156, s[70:71]
	v_cndmask_b32_e64 v157, 0, v157, s[72:73]
	v_cndmask_b32_e64 v158, 0, v158, s[74:75]
	v_cndmask_b32_e64 v159, 0, v159, s[76:77]
	v_add_f32_e32 v133, v133, v156
	v_add_f32_e32 v133, v133, v157
	v_add_f32_e32 v133, v133, v158
	v_add_f32_e32 v133, v133, v159
	v_cvt_pk_bf16_f32 v200, v156, v157
	v_cvt_pk_bf16_f32 v201, v158, v159
	v_min_f32_e32 v156, 0x42a00000, v248
	v_min_f32_e32 v157, 0x42a00000, v249
	v_min_f32_e32 v158, 0x42a00000, v250
	v_min_f32_e32 v159, 0x42a00000, v251
	v_mul_f32_e32 v156, 0x3fb8aa3b, v156
	v_mul_f32_e32 v157, 0x3fb8aa3b, v157
	v_mul_f32_e32 v158, 0x3fb8aa3b, v158
	v_mul_f32_e32 v159, 0x3fb8aa3b, v159
	v_exp_f32_e32 v156, v156
	v_exp_f32_e32 v157, v157
	v_exp_f32_e32 v158, v158
	v_exp_f32_e32 v159, v159
	v_add_u32_e32 v138, 0x90, v175
	v_add_u32_e32 v139, 0x91, v175
	v_add_u32_e32 v140, 0x92, v175
	v_add_u32_e32 v141, 0x93, v175
	v_cmp_gt_u32_e64 s[70:71], s44, v138
	v_cmp_gt_u32_e64 s[72:73], s44, v139
	v_cmp_gt_u32_e64 s[74:75], s44, v140
	v_cmp_gt_u32_e64 s[76:77], s44, v141
	v_cndmask_b32_e64 v156, 0, v156, s[62:63]
	v_cndmask_b32_e64 v157, 0, v157, s[64:65]
	v_cndmask_b32_e64 v158, 0, v158, s[66:67]
	v_cndmask_b32_e64 v159, 0, v159, s[68:69]
	v_cndmask_b32_e64 v156, 0, v156, s[70:71]
	v_cndmask_b32_e64 v157, 0, v157, s[72:73]
	v_cndmask_b32_e64 v158, 0, v158, s[74:75]
	v_cndmask_b32_e64 v159, 0, v159, s[76:77]
	v_add_f32_e32 v133, v133, v156
	v_add_f32_e32 v133, v133, v157
	v_add_f32_e32 v133, v133, v158
	v_add_f32_e32 v133, v133, v159
	v_cvt_pk_bf16_f32 v202, v156, v157
	v_cvt_pk_bf16_f32 v203, v158, v159
	v_add_u32_e32 v134, s42, v160
	v_lshlrev_b32_e32 v134, 2, v134
	v_add_u32_e32 v134, s43, v134
	v_subrev_u32_e32 v135, s15, v134
	v_lshrrev_b32_e32 v136, 4, v135
	v_add_u32_e32 v136, v136, v135
	v_mad_u32_u24 v176, v136, s79, v161
	v_lshl_add_u32 v177, v135, 2, s80
	s_sub_i32 s2, s42, 64
	v_add_u32_e32 v178, s2, v169
	v_and_b32_e32 v135, 3, v134
	v_lshlrev_b32_e32 v135, s13, v135
	v_lshrrev_b32_e32 v136, 2, v134
	v_add_u32_e32 v135, v135, v136
	v_lshl_add_u32 v135, v135, 7, v161
	global_load_dwordx4 v[48:51], v135, s[18:19] nt
	global_load_dwordx4 v[52:55], v135, s[18:19] offset:64 nt
	v_add_u32_e32 v137, 64, v134
	v_and_b32_e32 v135, 3, v137
	v_lshlrev_b32_e32 v135, s13, v135
	v_lshrrev_b32_e32 v136, 2, v137
	v_add_u32_e32 v135, v135, v136
	v_lshl_add_u32 v135, v135, 7, v161
	global_load_dwordx4 v[56:59], v135, s[18:19] nt
	global_load_dwordx4 v[60:63], v135, s[18:19] offset:64 nt
	v_subrev_u32_e32 v134, 0x100, v134
	v_and_b32_e32 v137, 3, v134
	v_lshlrev_b32_e32 v137, s13, v137
	v_bfe_u32 v135, v134, 2, 2
	v_add_u32_e32 v137, v137, v135
	v_lshl_add_u32 v183, v137, 7, v161
	v_ashrrev_i32_e32 v252, 4, v134
	v_med3_i32 v136, v252, 0, s14
	v_lshl_add_u32 v136, v136, 9, v183
	global_load_dwordx4 v[0:3], v136, s[20:21]
	global_load_dwordx4 v[4:7], v136, s[20:21] offset:64
	v_add_u32_e32 v135, 4, v252
	v_med3_i32 v135, v135, 0, s14
	v_lshl_add_u32 v135, v135, 9, v183
	global_load_dwordx4 v[8:11], v135, s[20:21]
	global_load_dwordx4 v[12:15], v135, s[20:21] offset:64
	v_add_u32_e32 v136, 8, v252
	v_med3_i32 v136, v136, 0, s14
	v_lshl_add_u32 v136, v136, 9, v183
	global_load_dwordx4 v[16:19], v136, s[20:21]
	global_load_dwordx4 v[20:23], v136, s[20:21] offset:64
	v_add_u32_e32 v135, 12, v252
	v_med3_i32 v135, v135, 0, s14
	v_lshl_add_u32 v135, v135, 9, v183
	global_load_dwordx4 v[24:27], v135, s[20:21]
	global_load_dwordx4 v[28:31], v135, s[20:21] offset:64
	v_add_u32_e32 v136, 16, v252
	v_med3_i32 v136, v136, 0, s14
	v_lshl_add_u32 v136, v136, 9, v183
	global_load_dwordx4 v[32:35], v136, s[20:21]
	global_load_dwordx4 v[36:39], v136, s[20:21] offset:64
	v_add_u32_e32 v135, 20, v252
	v_med3_i32 v135, v135, 0, s14
	v_lshl_add_u32 v135, v135, 9, v183
	global_load_dwordx4 v[40:43], v135, s[20:21]
	global_load_dwordx4 v[44:47], v135, s[20:21] offset:64
	ds_bpermute_b32 v142, v167, v132
	s_waitcnt lgkmcnt(0)
	v_add_f32_e32 v132, v132, v142
	ds_bpermute_b32 v142, v168, v132
	s_waitcnt lgkmcnt(0)
	v_add_f32_e32 v132, v132, v142
	ds_bpermute_b32 v142, v167, v133
	s_waitcnt lgkmcnt(0)
	v_add_f32_e32 v133, v133, v142
	ds_bpermute_b32 v142, v168, v133
	s_waitcnt lgkmcnt(0)
	v_add_f32_e32 v133, v133, v142
	s_waitcnt vmcnt(16)
	ds_write_b128 v165, v[64:67]
	ds_write_b128 v165, v[68:71] offset:1152
	ds_write_b128 v165, v[72:75] offset:2304
	ds_write_b128 v165, v[76:79] offset:3456
	s_waitcnt lgkmcnt(0)
	ds_read_b64_tr_b16 v[236:237], v166
	ds_read_b64_tr_b16 v[238:239], v166 offset:2304
	ds_read_b64_tr_b16 v[240:241], v166 offset:32
	ds_read_b64_tr_b16 v[242:243], v166 offset:2336
	ds_read_b64_tr_b16 v[244:245], v166 offset:64
	ds_read_b64_tr_b16 v[246:247], v166 offset:2368
	ds_read_b64_tr_b16 v[248:249], v166 offset:96
	ds_read_b64_tr_b16 v[250:251], v166 offset:2400
	s_waitcnt lgkmcnt(0)
	s_add_i32 s2, s40, 32
	v_add_u32_e32 v138, s2, v164
	v_add_u32_e32 v138, s41, v138
	v_and_b32_e32 v139, 3, v138
	v_lshlrev_b32_e32 v139, s39, v139
	v_bfe_u32 v140, v138, 2, 2
	v_add_u32_e32 v139, v139, v140
	v_lshl_add_u32 v139, v139, 7, v162
	v_ashrrev_i32_e32 v138, 4, v138
	v_med3_i32 v138, v138, 0, s38
	v_lshl_add_u32 v138, v138, 9, v139
	global_load_dwordx4 v[64:67], v138, s[26:27]
	s_add_i32 s2, s40, 40
	v_add_u32_e32 v138, s2, v164
	v_add_u32_e32 v138, s41, v138
	v_and_b32_e32 v139, 3, v138
	v_lshlrev_b32_e32 v139, s39, v139
	v_bfe_u32 v140, v138, 2, 2
	v_add_u32_e32 v139, v139, v140
	v_lshl_add_u32 v139, v139, 7, v162
	v_ashrrev_i32_e32 v138, 4, v138
	v_med3_i32 v138, v138, 0, s38
	v_lshl_add_u32 v138, v138, 9, v139
	global_load_dwordx4 v[68:71], v138, s[26:27]
	s_add_i32 s2, s40, 48
	v_add_u32_e32 v138, s2, v164
	v_add_u32_e32 v138, s41, v138
	v_and_b32_e32 v139, 3, v138
	v_lshlrev_b32_e32 v139, s39, v139
	v_bfe_u32 v140, v138, 2, 2
	v_add_u32_e32 v139, v139, v140
	v_lshl_add_u32 v139, v139, 7, v162
	v_ashrrev_i32_e32 v138, 4, v138
	v_med3_i32 v138, v138, 0, s38
	v_lshl_add_u32 v138, v138, 9, v139
	global_load_dwordx4 v[72:75], v138, s[26:27]
	s_add_i32 s2, s40, 56
	v_add_u32_e32 v138, s2, v164
	v_add_u32_e32 v138, s41, v138
	v_and_b32_e32 v139, 3, v138
	v_lshlrev_b32_e32 v139, s39, v139
	v_bfe_u32 v140, v138, 2, 2
	v_add_u32_e32 v139, v139, v140
	v_lshl_add_u32 v139, v139, 7, v162
	v_ashrrev_i32_e32 v138, 4, v138
	v_med3_i32 v138, v138, 0, s38
	v_lshl_add_u32 v138, v138, 9, v139
	global_load_dwordx4 v[76:79], v138, s[26:27]
	ds_write_b128 v165, v[80:83]
	ds_write_b128 v165, v[84:87] offset:1152
	ds_write_b128 v165, v[88:91] offset:2304
	ds_write_b128 v165, v[92:95] offset:3456
	v_mfma_f32_16x16x32_bf16 v[204:207], v[236:239], v[112:115], 0
	v_mfma_f32_16x16x32_bf16 v[208:211], v[240:243], v[112:115], 0
	v_mfma_f32_16x16x32_bf16 v[212:215], v[244:247], v[112:115], 0
	v_mfma_f32_16x16x32_bf16 v[216:219], v[248:251], v[112:115], 0
	v_mfma_f32_16x16x32_bf16 v[220:223], v[236:239], v[184:187], 0
	v_mfma_f32_16x16x32_bf16 v[224:227], v[240:243], v[184:187], 0
	v_mfma_f32_16x16x32_bf16 v[228:231], v[244:247], v[184:187], 0
	v_mfma_f32_16x16x32_bf16 v[232:235], v[248:251], v[184:187], 0
	s_waitcnt lgkmcnt(0)
	ds_read_b64_tr_b16 v[236:237], v166
	ds_read_b64_tr_b16 v[238:239], v166 offset:2304
	ds_read_b64_tr_b16 v[240:241], v166 offset:32
	ds_read_b64_tr_b16 v[242:243], v166 offset:2336
	ds_read_b64_tr_b16 v[244:245], v166 offset:64
	ds_read_b64_tr_b16 v[246:247], v166 offset:2368
	ds_read_b64_tr_b16 v[248:249], v166 offset:96
	ds_read_b64_tr_b16 v[250:251], v166 offset:2400
	s_waitcnt lgkmcnt(0)
	s_add_i32 s2, s40, 64
	v_add_u32_e32 v138, s2, v164
	v_add_u32_e32 v138, s41, v138
	v_and_b32_e32 v139, 3, v138
	v_lshlrev_b32_e32 v139, s39, v139
	v_bfe_u32 v140, v138, 2, 2
	v_add_u32_e32 v139, v139, v140
	v_lshl_add_u32 v139, v139, 7, v162
	v_ashrrev_i32_e32 v138, 4, v138
	v_med3_i32 v138, v138, 0, s38
	v_lshl_add_u32 v138, v138, 9, v139
	global_load_dwordx4 v[80:83], v138, s[26:27]
	s_add_i32 s2, s40, 72
	v_add_u32_e32 v138, s2, v164
	v_add_u32_e32 v138, s41, v138
	v_and_b32_e32 v139, 3, v138
	v_lshlrev_b32_e32 v139, s39, v139
	v_bfe_u32 v140, v138, 2, 2
	v_add_u32_e32 v139, v139, v140
	v_lshl_add_u32 v139, v139, 7, v162
	v_ashrrev_i32_e32 v138, 4, v138
	v_med3_i32 v138, v138, 0, s38
	v_lshl_add_u32 v138, v138, 9, v139
	global_load_dwordx4 v[84:87], v138, s[26:27]
	s_add_i32 s2, s40, 80
	v_add_u32_e32 v138, s2, v164
	v_add_u32_e32 v138, s41, v138
	v_and_b32_e32 v139, 3, v138
	v_lshlrev_b32_e32 v139, s39, v139
	v_bfe_u32 v140, v138, 2, 2
	v_add_u32_e32 v139, v139, v140
	v_lshl_add_u32 v139, v139, 7, v162
	v_ashrrev_i32_e32 v138, 4, v138
	v_med3_i32 v138, v138, 0, s38
	v_lshl_add_u32 v138, v138, 9, v139
	global_load_dwordx4 v[88:91], v138, s[26:27]
	s_add_i32 s2, s40, 88
	v_add_u32_e32 v138, s2, v164
	v_add_u32_e32 v138, s41, v138
	v_and_b32_e32 v139, 3, v138
	v_lshlrev_b32_e32 v139, s39, v139
	v_bfe_u32 v140, v138, 2, 2
	v_add_u32_e32 v139, v139, v140
	v_lshl_add_u32 v139, v139, 7, v162
	v_ashrrev_i32_e32 v138, 4, v138
	v_med3_i32 v138, v138, 0, s38
	v_lshl_add_u32 v138, v138, 9, v139
	global_load_dwordx4 v[92:95], v138, s[26:27]
	ds_write_b128 v165, v[96:99]
	ds_write_b128 v165, v[100:103] offset:1152
	ds_write_b128 v165, v[104:107] offset:2304
	ds_write_b128 v165, v[108:111] offset:3456
	v_mfma_f32_16x16x32_bf16 v[204:207], v[236:239], v[116:119], v[204:207]
	v_mfma_f32_16x16x32_bf16 v[208:211], v[240:243], v[116:119], v[208:211]
	v_mfma_f32_16x16x32_bf16 v[212:215], v[244:247], v[116:119], v[212:215]
	v_mfma_f32_16x16x32_bf16 v[216:219], v[248:251], v[116:119], v[216:219]
	v_mfma_f32_16x16x32_bf16 v[220:223], v[236:239], v[188:191], v[220:223]
	v_mfma_f32_16x16x32_bf16 v[224:227], v[240:243], v[188:191], v[224:227]
	v_mfma_f32_16x16x32_bf16 v[228:231], v[244:247], v[188:191], v[228:231]
	v_mfma_f32_16x16x32_bf16 v[232:235], v[248:251], v[188:191], v[232:235]
	s_waitcnt lgkmcnt(0)
	ds_read_b64_tr_b16 v[236:237], v166
	ds_read_b64_tr_b16 v[238:239], v166 offset:2304
	ds_read_b64_tr_b16 v[240:241], v166 offset:32
	ds_read_b64_tr_b16 v[242:243], v166 offset:2336
	ds_read_b64_tr_b16 v[244:245], v166 offset:64
	ds_read_b64_tr_b16 v[246:247], v166 offset:2368
	ds_read_b64_tr_b16 v[248:249], v166 offset:96
	ds_read_b64_tr_b16 v[250:251], v166 offset:2400
	s_waitcnt lgkmcnt(0)
	s_waitcnt vmcnt(4)
	ds_write_b128 v165, v[64:67]
	ds_write_b128 v165, v[68:71] offset:1152
	ds_write_b128 v165, v[72:75] offset:2304
	ds_write_b128 v165, v[76:79] offset:3456
	v_mfma_f32_16x16x32_bf16 v[204:207], v[236:239], v[120:123], v[204:207]
	v_mfma_f32_16x16x32_bf16 v[208:211], v[240:243], v[120:123], v[208:211]
	v_mfma_f32_16x16x32_bf16 v[212:215], v[244:247], v[120:123], v[212:215]
	v_mfma_f32_16x16x32_bf16 v[216:219], v[248:251], v[120:123], v[216:219]
	v_mfma_f32_16x16x32_bf16 v[220:223], v[236:239], v[192:195], v[220:223]
	v_mfma_f32_16x16x32_bf16 v[224:227], v[240:243], v[192:195], v[224:227]
	v_mfma_f32_16x16x32_bf16 v[228:231], v[244:247], v[192:195], v[228:231]
	v_mfma_f32_16x16x32_bf16 v[232:235], v[248:251], v[192:195], v[232:235]
	s_waitcnt lgkmcnt(0)
	ds_read_b64_tr_b16 v[236:237], v166
	ds_read_b64_tr_b16 v[238:239], v166 offset:2304
	ds_read_b64_tr_b16 v[240:241], v166 offset:32
	ds_read_b64_tr_b16 v[242:243], v166 offset:2336
	ds_read_b64_tr_b16 v[244:245], v166 offset:64
	ds_read_b64_tr_b16 v[246:247], v166 offset:2368
	ds_read_b64_tr_b16 v[248:249], v166 offset:96
	ds_read_b64_tr_b16 v[250:251], v166 offset:2400
	s_waitcnt lgkmcnt(0)
	s_waitcnt vmcnt(0)
	ds_write_b128 v165, v[80:83]
	ds_write_b128 v165, v[84:87] offset:1152
	ds_write_b128 v165, v[88:91] offset:2304
	ds_write_b128 v165, v[92:95] offset:3456
	v_mfma_f32_16x16x32_bf16 v[204:207], v[236:239], v[124:127], v[204:207]
	v_mfma_f32_16x16x32_bf16 v[208:211], v[240:243], v[124:127], v[208:211]
	v_mfma_f32_16x16x32_bf16 v[212:215], v[244:247], v[124:127], v[212:215]
	v_mfma_f32_16x16x32_bf16 v[216:219], v[248:251], v[124:127], v[216:219]
	v_mfma_f32_16x16x32_bf16 v[220:223], v[236:239], v[196:199], v[220:223]
	v_mfma_f32_16x16x32_bf16 v[224:227], v[240:243], v[196:199], v[224:227]
	v_mfma_f32_16x16x32_bf16 v[228:231], v[244:247], v[196:199], v[228:231]
	v_mfma_f32_16x16x32_bf16 v[232:235], v[248:251], v[196:199], v[232:235]
	s_waitcnt lgkmcnt(0)
	ds_read_b64_tr_b16 v[236:237], v166
	ds_read_b64_tr_b16 v[238:239], v166 offset:2304
	ds_read_b64_tr_b16 v[240:241], v166 offset:32
	ds_read_b64_tr_b16 v[242:243], v166 offset:2336
	ds_read_b64_tr_b16 v[244:245], v166 offset:64
	ds_read_b64_tr_b16 v[246:247], v166 offset:2368
	ds_read_b64_tr_b16 v[248:249], v166 offset:96
	ds_read_b64_tr_b16 v[250:251], v166 offset:2400
	s_waitcnt lgkmcnt(0)
	v_mfma_f32_16x16x32_bf16 v[204:207], v[236:239], v[128:131], v[204:207]
	v_mfma_f32_16x16x32_bf16 v[208:211], v[240:243], v[128:131], v[208:211]
	v_mfma_f32_16x16x32_bf16 v[212:215], v[244:247], v[128:131], v[212:215]
	v_mfma_f32_16x16x32_bf16 v[216:219], v[248:251], v[128:131], v[216:219]
	v_mfma_f32_16x16x32_bf16 v[220:223], v[236:239], v[200:203], v[220:223]
	v_mfma_f32_16x16x32_bf16 v[224:227], v[240:243], v[200:203], v[224:227]
	v_mfma_f32_16x16x32_bf16 v[228:231], v[244:247], v[200:203], v[228:231]
	v_mfma_f32_16x16x32_bf16 v[232:235], v[248:251], v[200:203], v[232:235]
	s_add_i32 s2, s42, -64
	v_add_u32_e32 v138, s2, v164
	v_lshlrev_b32_e32 v138, 2, v138
	v_add_u32_e32 v138, s43, v138
	v_and_b32_e32 v139, 3, v138
	v_lshlrev_b32_e32 v139, s13, v139
	v_bfe_u32 v140, v138, 2, 2
	v_add_u32_e32 v139, v139, v140
	v_lshl_add_u32 v139, v139, 7, v162
	v_ashrrev_i32_e32 v138, 4, v138
	v_med3_i32 v138, v138, 0, s14
	v_lshl_add_u32 v138, v138, 9, v139
	global_load_dwordx4 v[64:67], v138, s[22:23]
	s_add_i32 s2, s42, -56
	v_add_u32_e32 v138, s2, v164
	v_lshlrev_b32_e32 v138, 2, v138
	v_add_u32_e32 v138, s43, v138
	v_and_b32_e32 v139, 3, v138
	v_lshlrev_b32_e32 v139, s13, v139
	v_bfe_u32 v140, v138, 2, 2
	v_add_u32_e32 v139, v139, v140
	v_lshl_add_u32 v139, v139, 7, v162
	v_ashrrev_i32_e32 v138, 4, v138
	v_med3_i32 v138, v138, 0, s14
	v_lshl_add_u32 v138, v138, 9, v139
	global_load_dwordx4 v[68:71], v138, s[22:23]
	s_add_i32 s2, s42, -48
	v_add_u32_e32 v138, s2, v164
	v_lshlrev_b32_e32 v138, 2, v138
	v_add_u32_e32 v138, s43, v138
	v_and_b32_e32 v139, 3, v138
	v_lshlrev_b32_e32 v139, s13, v139
	v_bfe_u32 v140, v138, 2, 2
	v_add_u32_e32 v139, v139, v140
	v_lshl_add_u32 v139, v139, 7, v162
	v_ashrrev_i32_e32 v138, 4, v138
	v_med3_i32 v138, v138, 0, s14
	v_lshl_add_u32 v138, v138, 9, v139
	global_load_dwordx4 v[72:75], v138, s[22:23]
	s_add_i32 s2, s42, -40
	v_add_u32_e32 v138, s2, v164
	v_lshlrev_b32_e32 v138, 2, v138
	v_add_u32_e32 v138, s43, v138
	v_and_b32_e32 v139, 3, v138
	v_lshlrev_b32_e32 v139, s13, v139
	v_bfe_u32 v140, v138, 2, 2
	v_add_u32_e32 v139, v139, v140
	v_lshl_add_u32 v139, v139, 7, v162
	v_ashrrev_i32_e32 v138, 4, v138
	v_med3_i32 v138, v138, 0, s14
	v_lshl_add_u32 v138, v138, 9, v139
	global_load_dwordx4 v[76:79], v138, s[22:23]
	s_add_i32 s2, s42, -32
	v_add_u32_e32 v138, s2, v164
	v_lshlrev_b32_e32 v138, 2, v138
	v_add_u32_e32 v138, s43, v138
	v_and_b32_e32 v139, 3, v138
	v_lshlrev_b32_e32 v139, s13, v139
	v_bfe_u32 v140, v138, 2, 2
	v_add_u32_e32 v139, v139, v140
	v_lshl_add_u32 v139, v139, 7, v162
	v_ashrrev_i32_e32 v138, 4, v138
	v_med3_i32 v138, v138, 0, s14
	v_lshl_add_u32 v138, v138, 9, v139
	global_load_dwordx4 v[80:83], v138, s[22:23]
	s_add_i32 s2, s42, -24
	v_add_u32_e32 v138, s2, v164
	v_lshlrev_b32_e32 v138, 2, v138
	v_add_u32_e32 v138, s43, v138
	v_and_b32_e32 v139, 3, v138
	v_lshlrev_b32_e32 v139, s13, v139
	v_bfe_u32 v140, v138, 2, 2
	v_add_u32_e32 v139, v139, v140
	v_lshl_add_u32 v139, v139, 7, v162
	v_ashrrev_i32_e32 v138, 4, v138
	v_med3_i32 v138, v138, 0, s14
	v_lshl_add_u32 v138, v138, 9, v139
	global_load_dwordx4 v[84:87], v138, s[22:23]
	s_add_i32 s2, s42, -16
	v_add_u32_e32 v138, s2, v164
	v_lshlrev_b32_e32 v138, 2, v138
	v_add_u32_e32 v138, s43, v138
	v_and_b32_e32 v139, 3, v138
	v_lshlrev_b32_e32 v139, s13, v139
	v_bfe_u32 v140, v138, 2, 2
	v_add_u32_e32 v139, v139, v140
	v_lshl_add_u32 v139, v139, 7, v162
	v_ashrrev_i32_e32 v138, 4, v138
	v_med3_i32 v138, v138, 0, s14
	v_lshl_add_u32 v138, v138, 9, v139
	global_load_dwordx4 v[88:91], v138, s[22:23]
	s_add_i32 s2, s42, -8
	v_add_u32_e32 v138, s2, v164
	v_lshlrev_b32_e32 v138, 2, v138
	v_add_u32_e32 v138, s43, v138
	v_and_b32_e32 v139, 3, v138
	v_lshlrev_b32_e32 v139, s13, v139
	v_bfe_u32 v140, v138, 2, 2
	v_add_u32_e32 v139, v139, v140
	v_lshl_add_u32 v139, v139, 7, v162
	v_ashrrev_i32_e32 v138, 4, v138
	v_med3_i32 v138, v138, 0, s14
	v_lshl_add_u32 v138, v138, 9, v139
	global_load_dwordx4 v[92:95], v138, s[22:23]
	s_add_i32 s2, s42, 0
	v_add_u32_e32 v138, s2, v164
	v_lshlrev_b32_e32 v138, 2, v138
	v_add_u32_e32 v138, s43, v138
	v_and_b32_e32 v139, 3, v138
	v_lshlrev_b32_e32 v139, s13, v139
	v_bfe_u32 v140, v138, 2, 2
	v_add_u32_e32 v139, v139, v140
	v_lshl_add_u32 v139, v139, 7, v162
	v_ashrrev_i32_e32 v138, 4, v138
	v_med3_i32 v138, v138, 0, s14
	v_lshl_add_u32 v138, v138, 9, v139
	global_load_dwordx4 v[96:99], v138, s[22:23]
	s_add_i32 s2, s42, 8
	v_add_u32_e32 v138, s2, v164
	v_lshlrev_b32_e32 v138, 2, v138
	v_add_u32_e32 v138, s43, v138
	v_and_b32_e32 v139, 3, v138
	v_lshlrev_b32_e32 v139, s13, v139
	v_bfe_u32 v140, v138, 2, 2
	v_add_u32_e32 v139, v139, v140
	v_lshl_add_u32 v139, v139, 7, v162
	v_ashrrev_i32_e32 v138, 4, v138
	v_med3_i32 v138, v138, 0, s14
	v_lshl_add_u32 v138, v138, 9, v139
	global_load_dwordx4 v[100:103], v138, s[22:23]
	s_add_i32 s2, s42, 16
	v_add_u32_e32 v138, s2, v164
	v_lshlrev_b32_e32 v138, 2, v138
	v_add_u32_e32 v138, s43, v138
	v_and_b32_e32 v139, 3, v138
	v_lshlrev_b32_e32 v139, s13, v139
	v_bfe_u32 v140, v138, 2, 2
	v_add_u32_e32 v139, v139, v140
	v_lshl_add_u32 v139, v139, 7, v162
	v_ashrrev_i32_e32 v138, 4, v138
	v_med3_i32 v138, v138, 0, s14
	v_lshl_add_u32 v138, v138, 9, v139
	global_load_dwordx4 v[104:107], v138, s[22:23]
	s_add_i32 s2, s42, 24
	v_add_u32_e32 v138, s2, v164
	v_lshlrev_b32_e32 v138, 2, v138
	v_add_u32_e32 v138, s43, v138
	v_and_b32_e32 v139, 3, v138
	v_lshlrev_b32_e32 v139, s13, v139
	v_bfe_u32 v140, v138, 2, 2
	v_add_u32_e32 v139, v139, v140
	v_lshl_add_u32 v139, v139, 7, v162
	v_ashrrev_i32_e32 v138, 4, v138
	v_med3_i32 v138, v138, 0, s14
	v_lshl_add_u32 v138, v138, 9, v139
	global_load_dwordx4 v[108:111], v138, s[22:23]
	ds_write_b128 v173, v[204:207] offset:0
	ds_write_b128 v173, v[208:211] offset:64
	ds_write_b128 v173, v[212:215] offset:128
	ds_write_b128 v173, v[216:219] offset:192
	ds_write_b32 v174, v132 offset:0
	ds_write_b128 v173, v[220:223] offset:4624
	ds_write_b128 v173, v[224:227] offset:4688
	ds_write_b128 v173, v[228:231] offset:4752
	ds_write_b128 v173, v[232:235] offset:4816
	ds_write_b32 v174, v133 offset:64
	s_waitcnt lgkmcnt(0)
	s_barrier
	s_mov_b32 s40, s42
	s_mov_b32 s41, s43
	v_mov_b32_e32 v173, v176
	v_mov_b32_e32 v174, v177
	v_mov_b32_e32 v175, v178
	v_mov_b32_e32 v179, v183
	v_mov_b32_e32 v182, v252
	s_lshr_b32 s44, s33, 2
	s_lshr_b32 s42, s15, 4
	s_add_i32 s43, s0, 0
	s_waitcnt vmcnt(12)
	v_mov_b32_e32 v132, 0
	v_mov_b32_e32 v133, 0
	v_mfma_f32_16x16x32_bf16 v[236:239], v[0:3], v[48:51], 0
	v_mfma_f32_16x16x32_bf16 v[236:239], v[4:7], v[52:55], v[236:239]
	v_mfma_f32_16x16x32_bf16 v[240:243], v[8:11], v[48:51], 0
	v_mfma_f32_16x16x32_bf16 v[240:243], v[12:15], v[52:55], v[240:243]
	v_mfma_f32_16x16x32_bf16 v[248:251], v[8:11], v[56:59], 0
	v_mfma_f32_16x16x32_bf16 v[248:251], v[12:15], v[60:63], v[248:251]
	s_nop 7
	v_min_f32_e32 v152, 0x42a00000, v236
	v_min_f32_e32 v153, 0x42a00000, v237
	v_min_f32_e32 v154, 0x42a00000, v238
	v_min_f32_e32 v155, 0x42a00000, v239
	v_mfma_f32_16x16x32_bf16 v[236:239], v[16:19], v[48:51], 0
	v_mfma_f32_16x16x32_bf16 v[236:239], v[20:23], v[52:55], v[236:239]
	v_mfma_f32_16x16x32_bf16 v[244:247], v[16:19], v[56:59], 0
	v_mfma_f32_16x16x32_bf16 v[244:247], v[20:23], v[60:63], v[244:247]
	v_add_u32_e32 v136, 24, v182
	v_med3_i32 v136, v136, 0, s38
	v_lshl_add_u32 v136, v136, 9, v179
	global_load_dwordx4 v[0:3], v136, s[24:25]
	global_load_dwordx4 v[4:7], v136, s[24:25] offset:64
	v_mul_f32_e32 v152, 0x3fb8aa3b, v152
	v_mul_f32_e32 v153, 0x3fb8aa3b, v153
	v_mul_f32_e32 v154, 0x3fb8aa3b, v154
	v_mul_f32_e32 v155, 0x3fb8aa3b, v155
	v_exp_f32_e32 v152, v152
	v_exp_f32_e32 v153, v153
	v_exp_f32_e32 v154, v154
	v_exp_f32_e32 v155, v155
	v_add_u32_e32 v138, 0, v175
	v_add_u32_e32 v139, 1, v175
	v_add_u32_e32 v140, 2, v175
	v_add_u32_e32 v141, 3, v175
	v_cmp_gt_u32_e64 s[70:71], s44, v138
	v_cmp_gt_u32_e64 s[72:73], s44, v139
	v_cmp_gt_u32_e64 s[74:75], s44, v140
	v_cmp_gt_u32_e64 s[76:77], s44, v141
	v_cndmask_b32_e64 v152, 0, v152, s[54:55]
	v_cndmask_b32_e64 v153, 0, v153, s[56:57]
	v_cndmask_b32_e64 v154, 0, v154, s[58:59]
	v_cndmask_b32_e64 v155, 0, v155, s[60:61]
	v_cndmask_b32_e64 v152, 0, v152, s[70:71]
	v_cndmask_b32_e64 v153, 0, v153, s[72:73]
	v_cndmask_b32_e64 v154, 0, v154, s[74:75]
	v_cndmask_b32_e64 v155, 0, v155, s[76:77]
	v_add_f32_e32 v132, v132, v152
	v_add_f32_e32 v132, v132, v153
	v_add_f32_e32 v132, v132, v154
	v_add_f32_e32 v132, v132, v155
	v_cvt_pk_bf16_f32 v112, v152, v153
	v_cvt_pk_bf16_f32 v113, v154, v155
	v_min_f32_e32 v152, 0x42a00000, v240
	v_min_f32_e32 v153, 0x42a00000, v241
	v_min_f32_e32 v154, 0x42a00000, v242
	v_min_f32_e32 v155, 0x42a00000, v243
	v_min_f32_e32 v156, 0x42a00000, v248
	v_min_f32_e32 v157, 0x42a00000, v249
	v_min_f32_e32 v158, 0x42a00000, v250
	v_min_f32_e32 v159, 0x42a00000, v251
	v_mfma_f32_16x16x32_bf16 v[240:243], v[24:27], v[48:51], 0
	v_mfma_f32_16x16x32_bf16 v[240:243], v[28:31], v[52:55], v[240:243]
	v_mfma_f32_16x16x32_bf16 v[248:251], v[24:27], v[56:59], 0
	v_mfma_f32_16x16x32_bf16 v[248:251], v[28:31], v[60:63], v[248:251]
	v_add_u32_e32 v135, 28, v182
	v_med3_i32 v135, v135, 0, s38
	v_lshl_add_u32 v135, v135, 9, v179
	global_load_dwordx4 v[8:11], v135, s[24:25]
	global_load_dwordx4 v[12:15], v135, s[24:25] offset:64
	v_mul_f32_e32 v152, 0x3fb8aa3b, v152
	v_mul_f32_e32 v153, 0x3fb8aa3b, v153
	v_mul_f32_e32 v154, 0x3fb8aa3b, v154
	v_mul_f32_e32 v155, 0x3fb8aa3b, v155
	v_exp_f32_e32 v152, v152
	v_exp_f32_e32 v153, v153
	v_exp_f32_e32 v154, v154
	v_exp_f32_e32 v155, v155
	v_add_u32_e32 v138, 16, v175
	v_add_u32_e32 v139, 17, v175
	v_add_u32_e32 v140, 18, v175
	v_add_u32_e32 v141, 19, v175
	v_cmp_gt_u32_e64 s[70:71], s44, v138
	v_cmp_gt_u32_e64 s[72:73], s44, v139
	v_cmp_gt_u32_e64 s[74:75], s44, v140
	v_cmp_gt_u32_e64 s[76:77], s44, v141
	v_cndmask_b32_e64 v152, 0, v152, s[70:71]
	v_cndmask_b32_e64 v153, 0, v153, s[72:73]
	v_cndmask_b32_e64 v154, 0, v154, s[74:75]
	v_cndmask_b32_e64 v155, 0, v155, s[76:77]
	v_add_f32_e32 v132, v132, v152
	v_add_f32_e32 v132, v132, v153
	v_add_f32_e32 v132, v132, v154
	v_add_f32_e32 v132, v132, v155
	v_cvt_pk_bf16_f32 v114, v152, v153
	v_cvt_pk_bf16_f32 v115, v154, v155
	v_mul_f32_e32 v156, 0x3fb8aa3b, v156
	v_mul_f32_e32 v157, 0x3fb8aa3b, v157
	v_mul_f32_e32 v158, 0x3fb8aa3b, v158
	v_mul_f32_e32 v159, 0x3fb8aa3b, v159
	v_exp_f32_e32 v156, v156
	v_exp_f32_e32 v157, v157
	v_exp_f32_e32 v158, v158
	v_exp_f32_e32 v159, v159
	v_add_u32_e32 v138, 16, v175
	v_add_u32_e32 v139, 17, v175
	v_add_u32_e32 v140, 18, v175
	v_add_u32_e32 v141, 19, v175
	v_cmp_gt_u32_e64 s[70:71], s44, v138
	v_cmp_gt_u32_e64 s[72:73], s44, v139
	v_cmp_gt_u32_e64 s[74:75], s44, v140
	v_cmp_gt_u32_e64 s[76:77], s44, v141
	v_cndmask_b32_e64 v156, 0, v156, s[54:55]
	v_cndmask_b32_e64 v157, 0, v157, s[56:57]
	v_cndmask_b32_e64 v158, 0, v158, s[58:59]
	v_cndmask_b32_e64 v159, 0, v159, s[60:61]
	v_cndmask_b32_e64 v156, 0, v156, s[70:71]
	v_cndmask_b32_e64 v157, 0, v157, s[72:73]
	v_cndmask_b32_e64 v158, 0, v158, s[74:75]
	v_cndmask_b32_e64 v159, 0, v159, s[76:77]
	v_add_f32_e32 v133, v133, v156
	v_add_f32_e32 v133, v133, v157
	v_add_f32_e32 v133, v133, v158
	v_add_f32_e32 v133, v133, v159
	v_cvt_pk_bf16_f32 v186, v156, v157
	v_cvt_pk_bf16_f32 v187, v158, v159
	v_min_f32_e32 v152, 0x42a00000, v236
	v_min_f32_e32 v153, 0x42a00000, v237
	v_min_f32_e32 v154, 0x42a00000, v238
	v_min_f32_e32 v155, 0x42a00000, v239
	v_min_f32_e32 v156, 0x42a00000, v244
	v_min_f32_e32 v157, 0x42a00000, v245
	v_min_f32_e32 v158, 0x42a00000, v246
	v_min_f32_e32 v159, 0x42a00000, v247
	v_mfma_f32_16x16x32_bf16 v[236:239], v[32:35], v[48:51], 0
	v_mfma_f32_16x16x32_bf16 v[236:239], v[36:39], v[52:55], v[236:239]
	v_mfma_f32_16x16x32_bf16 v[244:247], v[32:35], v[56:59], 0
	v_mfma_f32_16x16x32_bf16 v[244:247], v[36:39], v[60:63], v[244:247]
	v_add_u32_e32 v136, 32, v182
	v_med3_i32 v136, v136, 0, s38
	v_lshl_add_u32 v136, v136, 9, v179
	global_load_dwordx4 v[16:19], v136, s[24:25]
	global_load_dwordx4 v[20:23], v136, s[24:25] offset:64
	v_mul_f32_e32 v152, 0x3fb8aa3b, v152
	v_mul_f32_e32 v153, 0x3fb8aa3b, v153
	v_mul_f32_e32 v154, 0x3fb8aa3b, v154
	v_mul_f32_e32 v155, 0x3fb8aa3b, v155
	v_exp_f32_e32 v152, v152
	v_exp_f32_e32 v153, v153
	v_exp_f32_e32 v154, v154
	v_exp_f32_e32 v155, v155
	v_add_u32_e32 v138, 32, v175
	v_add_u32_e32 v139, 33, v175
	v_add_u32_e32 v140, 34, v175
	v_add_u32_e32 v141, 35, v175
	v_cmp_gt_u32_e64 s[70:71], s44, v138
	v_cmp_gt_u32_e64 s[72:73], s44, v139
	v_cmp_gt_u32_e64 s[74:75], s44, v140
	v_cmp_gt_u32_e64 s[76:77], s44, v141
	v_cndmask_b32_e64 v152, 0, v152, s[70:71]
	v_cndmask_b32_e64 v153, 0, v153, s[72:73]
	v_cndmask_b32_e64 v154, 0, v154, s[74:75]
	v_cndmask_b32_e64 v155, 0, v155, s[76:77]
	v_add_f32_e32 v132, v132, v152
	v_add_f32_e32 v132, v132, v153
	v_add_f32_e32 v132, v132, v154
	v_add_f32_e32 v132, v132, v155
	v_cvt_pk_bf16_f32 v116, v152, v153
	v_cvt_pk_bf16_f32 v117, v154, v155
	v_mul_f32_e32 v156, 0x3fb8aa3b, v156
	v_mul_f32_e32 v157, 0x3fb8aa3b, v157
	v_mul_f32_e32 v158, 0x3fb8aa3b, v158
	v_mul_f32_e32 v159, 0x3fb8aa3b, v159
	v_exp_f32_e32 v156, v156
	v_exp_f32_e32 v157, v157
	v_exp_f32_e32 v158, v158
	v_exp_f32_e32 v159, v159
	v_add_u32_e32 v138, 32, v175
	v_add_u32_e32 v139, 33, v175
	v_add_u32_e32 v140, 34, v175
	v_add_u32_e32 v141, 35, v175
	v_cmp_gt_u32_e64 s[70:71], s44, v138
	v_cmp_gt_u32_e64 s[72:73], s44, v139
	v_cmp_gt_u32_e64 s[74:75], s44, v140
	v_cmp_gt_u32_e64 s[76:77], s44, v141
	v_cndmask_b32_e64 v156, 0, v156, s[70:71]
	v_cndmask_b32_e64 v157, 0, v157, s[72:73]
	v_cndmask_b32_e64 v158, 0, v158, s[74:75]
	v_cndmask_b32_e64 v159, 0, v159, s[76:77]
	v_add_f32_e32 v133, v133, v156
	v_add_f32_e32 v133, v133, v157
	v_add_f32_e32 v133, v133, v158
	v_add_f32_e32 v133, v133, v159
	v_cvt_pk_bf16_f32 v188, v156, v157
	v_cvt_pk_bf16_f32 v189, v158, v159
	v_min_f32_e32 v152, 0x42a00000, v240
	v_min_f32_e32 v153, 0x42a00000, v241
	v_min_f32_e32 v154, 0x42a00000, v242
	v_min_f32_e32 v155, 0x42a00000, v243
	v_min_f32_e32 v156, 0x42a00000, v248
	v_min_f32_e32 v157, 0x42a00000, v249
	v_min_f32_e32 v158, 0x42a00000, v250
	v_min_f32_e32 v159, 0x42a00000, v251
	v_mfma_f32_16x16x32_bf16 v[240:243], v[40:43], v[48:51], 0
	v_mfma_f32_16x16x32_bf16 v[240:243], v[44:47], v[52:55], v[240:243]
	v_mfma_f32_16x16x32_bf16 v[248:251], v[40:43], v[56:59], 0
	v_mfma_f32_16x16x32_bf16 v[248:251], v[44:47], v[60:63], v[248:251]
	v_add_u32_e32 v135, 36, v182
	v_med3_i32 v135, v135, 0, s38
	v_lshl_add_u32 v135, v135, 9, v179
	global_load_dwordx4 v[24:27], v135, s[24:25]
	global_load_dwordx4 v[28:31], v135, s[24:25] offset:64
	v_mul_f32_e32 v152, 0x3fb8aa3b, v152
	v_mul_f32_e32 v153, 0x3fb8aa3b, v153
	v_mul_f32_e32 v154, 0x3fb8aa3b, v154
	v_mul_f32_e32 v155, 0x3fb8aa3b, v155
	v_exp_f32_e32 v152, v152
	v_exp_f32_e32 v153, v153
	v_exp_f32_e32 v154, v154
	v_exp_f32_e32 v155, v155
	v_add_u32_e32 v138, 48, v175
	v_add_u32_e32 v139, 49, v175
	v_add_u32_e32 v140, 50, v175
	v_add_u32_e32 v141, 51, v175
	v_cmp_gt_u32_e64 s[70:71], s44, v138
	v_cmp_gt_u32_e64 s[72:73], s44, v139
	v_cmp_gt_u32_e64 s[74:75], s44, v140
	v_cmp_gt_u32_e64 s[76:77], s44, v141
	v_cndmask_b32_e64 v152, 0, v152, s[70:71]
	v_cndmask_b32_e64 v153, 0, v153, s[72:73]
	v_cndmask_b32_e64 v154, 0, v154, s[74:75]
	v_cndmask_b32_e64 v155, 0, v155, s[76:77]
	v_add_f32_e32 v132, v132, v152
	v_add_f32_e32 v132, v132, v153
	v_add_f32_e32 v132, v132, v154
	v_add_f32_e32 v132, v132, v155
	v_cvt_pk_bf16_f32 v118, v152, v153
	v_cvt_pk_bf16_f32 v119, v154, v155
	v_mul_f32_e32 v156, 0x3fb8aa3b, v156
	v_mul_f32_e32 v157, 0x3fb8aa3b, v157
	v_mul_f32_e32 v158, 0x3fb8aa3b, v158
	v_mul_f32_e32 v159, 0x3fb8aa3b, v159
	v_exp_f32_e32 v156, v156
	v_exp_f32_e32 v157, v157
	v_exp_f32_e32 v158, v158
	v_exp_f32_e32 v159, v159
	v_add_u32_e32 v138, 48, v175
	v_add_u32_e32 v139, 49, v175
	v_add_u32_e32 v140, 50, v175
	v_add_u32_e32 v141, 51, v175
	v_cmp_gt_u32_e64 s[70:71], s44, v138
	v_cmp_gt_u32_e64 s[72:73], s44, v139
	v_cmp_gt_u32_e64 s[74:75], s44, v140
	v_cmp_gt_u32_e64 s[76:77], s44, v141
	v_cndmask_b32_e64 v156, 0, v156, s[70:71]
	v_cndmask_b32_e64 v157, 0, v157, s[72:73]
	v_cndmask_b32_e64 v158, 0, v158, s[74:75]
	v_cndmask_b32_e64 v159, 0, v159, s[76:77]
	v_add_f32_e32 v133, v133, v156
	v_add_f32_e32 v133, v133, v157
	v_add_f32_e32 v133, v133, v158
	v_add_f32_e32 v133, v133, v159
	v_cvt_pk_bf16_f32 v190, v156, v157
	v_cvt_pk_bf16_f32 v191, v158, v159
	v_min_f32_e32 v152, 0x42a00000, v236
	v_min_f32_e32 v153, 0x42a00000, v237
	v_min_f32_e32 v154, 0x42a00000, v238
	v_min_f32_e32 v155, 0x42a00000, v239
	v_min_f32_e32 v156, 0x42a00000, v244
	v_min_f32_e32 v157, 0x42a00000, v245
	v_min_f32_e32 v158, 0x42a00000, v246
	v_min_f32_e32 v159, 0x42a00000, v247
	s_waitcnt vmcnt(6)
	v_mfma_f32_16x16x32_bf16 v[236:239], v[0:3], v[48:51], 0
	v_mfma_f32_16x16x32_bf16 v[236:239], v[4:7], v[52:55], v[236:239]
	v_mfma_f32_16x16x32_bf16 v[244:247], v[0:3], v[56:59], 0
	v_mfma_f32_16x16x32_bf16 v[244:247], v[4:7], v[60:63], v[244:247]
	v_mul_f32_e32 v152, 0x3fb8aa3b, v152
	v_mul_f32_e32 v153, 0x3fb8aa3b, v153
	v_mul_f32_e32 v154, 0x3fb8aa3b, v154
	v_mul_f32_e32 v155, 0x3fb8aa3b, v155
	v_exp_f32_e32 v152, v152
	v_exp_f32_e32 v153, v153
	v_exp_f32_e32 v154, v154
	v_exp_f32_e32 v155, v155
	v_add_u32_e32 v138, 64, v175
	v_add_u32_e32 v139, 0x41, v175
	v_add_u32_e32 v140, 0x42, v175
	v_add_u32_e32 v141, 0x43, v175
	v_cmp_gt_u32_e64 s[70:71], s44, v138
	v_cmp_gt_u32_e64 s[72:73], s44, v139
	v_cmp_gt_u32_e64 s[74:75], s44, v140
	v_cmp_gt_u32_e64 s[76:77], s44, v141
	v_cndmask_b32_e64 v152, 0, v152, s[70:71]
	v_cndmask_b32_e64 v153, 0, v153, s[72:73]
	v_cndmask_b32_e64 v154, 0, v154, s[74:75]
	v_cndmask_b32_e64 v155, 0, v155, s[76:77]
	v_add_f32_e32 v132, v132, v152
	v_add_f32_e32 v132, v132, v153
	v_add_f32_e32 v132, v132, v154
	v_add_f32_e32 v132, v132, v155
	v_cvt_pk_bf16_f32 v120, v152, v153
	v_cvt_pk_bf16_f32 v121, v154, v155
	v_mul_f32_e32 v156, 0x3fb8aa3b, v156
	v_mul_f32_e32 v157, 0x3fb8aa3b, v157
	v_mul_f32_e32 v158, 0x3fb8aa3b, v158
	v_mul_f32_e32 v159, 0x3fb8aa3b, v159
	v_exp_f32_e32 v156, v156
	v_exp_f32_e32 v157, v157
	v_exp_f32_e32 v158, v158
	v_exp_f32_e32 v159, v159
	v_add_u32_e32 v138, 64, v175
	v_add_u32_e32 v139, 0x41, v175
	v_add_u32_e32 v140, 0x42, v175
	v_add_u32_e32 v141, 0x43, v175
	v_cmp_gt_u32_e64 s[70:71], s44, v138
	v_cmp_gt_u32_e64 s[72:73], s44, v139
	v_cmp_gt_u32_e64 s[74:75], s44, v140
	v_cmp_gt_u32_e64 s[76:77], s44, v141
	v_cndmask_b32_e64 v156, 0, v156, s[70:71]
	v_cndmask_b32_e64 v157, 0, v157, s[72:73]
	v_cndmask_b32_e64 v158, 0, v158, s[74:75]
	v_cndmask_b32_e64 v159, 0, v159, s[76:77]
	v_add_f32_e32 v133, v133, v156
	v_add_f32_e32 v133, v133, v157
	v_add_f32_e32 v133, v133, v158
	v_add_f32_e32 v133, v133, v159
	v_cvt_pk_bf16_f32 v192, v156, v157
	v_cvt_pk_bf16_f32 v193, v158, v159
	v_min_f32_e32 v152, 0x42a00000, v240
	v_min_f32_e32 v153, 0x42a00000, v241
	v_min_f32_e32 v154, 0x42a00000, v242
	v_min_f32_e32 v155, 0x42a00000, v243
	v_min_f32_e32 v156, 0x42a00000, v248
	v_min_f32_e32 v157, 0x42a00000, v249
	v_min_f32_e32 v158, 0x42a00000, v250
	v_min_f32_e32 v159, 0x42a00000, v251
	s_waitcnt vmcnt(4)
	v_mfma_f32_16x16x32_bf16 v[240:243], v[8:11], v[48:51], 0
	v_mfma_f32_16x16x32_bf16 v[240:243], v[12:15], v[52:55], v[240:243]
	v_mfma_f32_16x16x32_bf16 v[248:251], v[8:11], v[56:59], 0
	v_mfma_f32_16x16x32_bf16 v[248:251], v[12:15], v[60:63], v[248:251]
	v_mul_f32_e32 v152, 0x3fb8aa3b, v152
	v_mul_f32_e32 v153, 0x3fb8aa3b, v153
	v_mul_f32_e32 v154, 0x3fb8aa3b, v154
	v_mul_f32_e32 v155, 0x3fb8aa3b, v155
	v_exp_f32_e32 v152, v152
	v_exp_f32_e32 v153, v153
	v_exp_f32_e32 v154, v154
	v_exp_f32_e32 v155, v155
	v_add_u32_e32 v138, 0x50, v175
	v_add_u32_e32 v139, 0x51, v175
	v_add_u32_e32 v140, 0x52, v175
	v_add_u32_e32 v141, 0x53, v175
	v_cmp_gt_u32_e64 s[70:71], s44, v138
	v_cmp_gt_u32_e64 s[72:73], s44, v139
	v_cmp_gt_u32_e64 s[74:75], s44, v140
	v_cmp_gt_u32_e64 s[76:77], s44, v141
	v_cndmask_b32_e64 v152, 0, v152, s[70:71]
	v_cndmask_b32_e64 v153, 0, v153, s[72:73]
	v_cndmask_b32_e64 v154, 0, v154, s[74:75]
	v_cndmask_b32_e64 v155, 0, v155, s[76:77]
	v_add_f32_e32 v132, v132, v152
	v_add_f32_e32 v132, v132, v153
	v_add_f32_e32 v132, v132, v154
	v_add_f32_e32 v132, v132, v155
	v_cvt_pk_bf16_f32 v122, v152, v153
	v_cvt_pk_bf16_f32 v123, v154, v155
	v_mul_f32_e32 v156, 0x3fb8aa3b, v156
	v_mul_f32_e32 v157, 0x3fb8aa3b, v157
	v_mul_f32_e32 v158, 0x3fb8aa3b, v158
	v_mul_f32_e32 v159, 0x3fb8aa3b, v159
	v_exp_f32_e32 v156, v156
	v_exp_f32_e32 v157, v157
	v_exp_f32_e32 v158, v158
	v_exp_f32_e32 v159, v159
	v_add_u32_e32 v138, 0x50, v175
	v_add_u32_e32 v139, 0x51, v175
	v_add_u32_e32 v140, 0x52, v175
	v_add_u32_e32 v141, 0x53, v175
	v_cmp_gt_u32_e64 s[70:71], s44, v138
	v_cmp_gt_u32_e64 s[72:73], s44, v139
	v_cmp_gt_u32_e64 s[74:75], s44, v140
	v_cmp_gt_u32_e64 s[76:77], s44, v141
	v_cndmask_b32_e64 v156, 0, v156, s[70:71]
	v_cndmask_b32_e64 v157, 0, v157, s[72:73]
	v_cndmask_b32_e64 v158, 0, v158, s[74:75]
	v_cndmask_b32_e64 v159, 0, v159, s[76:77]
	v_add_f32_e32 v133, v133, v156
	v_add_f32_e32 v133, v133, v157
	v_add_f32_e32 v133, v133, v158
	v_add_f32_e32 v133, v133, v159
	v_cvt_pk_bf16_f32 v194, v156, v157
	v_cvt_pk_bf16_f32 v195, v158, v159
	v_min_f32_e32 v152, 0x42a00000, v236
	v_min_f32_e32 v153, 0x42a00000, v237
	v_min_f32_e32 v154, 0x42a00000, v238
	v_min_f32_e32 v155, 0x42a00000, v239
	v_min_f32_e32 v156, 0x42a00000, v244
	v_min_f32_e32 v157, 0x42a00000, v245
	v_min_f32_e32 v158, 0x42a00000, v246
	v_min_f32_e32 v159, 0x42a00000, v247
	s_waitcnt vmcnt(2)
	v_mfma_f32_16x16x32_bf16 v[236:239], v[16:19], v[48:51], 0
	v_mfma_f32_16x16x32_bf16 v[236:239], v[20:23], v[52:55], v[236:239]
	v_mfma_f32_16x16x32_bf16 v[244:247], v[16:19], v[56:59], 0
	v_mfma_f32_16x16x32_bf16 v[244:247], v[20:23], v[60:63], v[244:247]
	v_mul_f32_e32 v152, 0x3fb8aa3b, v152
	v_mul_f32_e32 v153, 0x3fb8aa3b, v153
	v_mul_f32_e32 v154, 0x3fb8aa3b, v154
	v_mul_f32_e32 v155, 0x3fb8aa3b, v155
	v_exp_f32_e32 v152, v152
	v_exp_f32_e32 v153, v153
	v_exp_f32_e32 v154, v154
	v_exp_f32_e32 v155, v155
	v_add_u32_e32 v138, 0x60, v175
	v_add_u32_e32 v139, 0x61, v175
	v_add_u32_e32 v140, 0x62, v175
	v_add_u32_e32 v141, 0x63, v175
	v_cmp_gt_u32_e64 s[70:71], s44, v138
	v_cmp_gt_u32_e64 s[72:73], s44, v139
	v_cmp_gt_u32_e64 s[74:75], s44, v140
	v_cmp_gt_u32_e64 s[76:77], s44, v141
	v_cndmask_b32_e64 v152, 0, v152, s[70:71]
	v_cndmask_b32_e64 v153, 0, v153, s[72:73]
	v_cndmask_b32_e64 v154, 0, v154, s[74:75]
	v_cndmask_b32_e64 v155, 0, v155, s[76:77]
	v_add_f32_e32 v132, v132, v152
	v_add_f32_e32 v132, v132, v153
	v_add_f32_e32 v132, v132, v154
	v_add_f32_e32 v132, v132, v155
	v_cvt_pk_bf16_f32 v124, v152, v153
	v_cvt_pk_bf16_f32 v125, v154, v155
	v_mul_f32_e32 v156, 0x3fb8aa3b, v156
	v_mul_f32_e32 v157, 0x3fb8aa3b, v157
	v_mul_f32_e32 v158, 0x3fb8aa3b, v158
	v_mul_f32_e32 v159, 0x3fb8aa3b, v159
	v_exp_f32_e32 v156, v156
	v_exp_f32_e32 v157, v157
	v_exp_f32_e32 v158, v158
	v_exp_f32_e32 v159, v159
	v_add_u32_e32 v138, 0x60, v175
	v_add_u32_e32 v139, 0x61, v175
	v_add_u32_e32 v140, 0x62, v175
	v_add_u32_e32 v141, 0x63, v175
	v_cmp_gt_u32_e64 s[70:71], s44, v138
	v_cmp_gt_u32_e64 s[72:73], s44, v139
	v_cmp_gt_u32_e64 s[74:75], s44, v140
	v_cmp_gt_u32_e64 s[76:77], s44, v141
	v_cndmask_b32_e64 v156, 0, v156, s[70:71]
	v_cndmask_b32_e64 v157, 0, v157, s[72:73]
	v_cndmask_b32_e64 v158, 0, v158, s[74:75]
	v_cndmask_b32_e64 v159, 0, v159, s[76:77]
	v_add_f32_e32 v133, v133, v156
	v_add_f32_e32 v133, v133, v157
	v_add_f32_e32 v133, v133, v158
	v_add_f32_e32 v133, v133, v159
	v_cvt_pk_bf16_f32 v196, v156, v157
	v_cvt_pk_bf16_f32 v197, v158, v159
	v_min_f32_e32 v152, 0x42a00000, v240
	v_min_f32_e32 v153, 0x42a00000, v241
	v_min_f32_e32 v154, 0x42a00000, v242
	v_min_f32_e32 v155, 0x42a00000, v243
	v_min_f32_e32 v156, 0x42a00000, v248
	v_min_f32_e32 v157, 0x42a00000, v249
	v_min_f32_e32 v158, 0x42a00000, v250
	v_min_f32_e32 v159, 0x42a00000, v251
	s_waitcnt vmcnt(0)
	v_mfma_f32_16x16x32_bf16 v[248:251], v[24:27], v[56:59], 0
	v_mfma_f32_16x16x32_bf16 v[248:251], v[28:31], v[60:63], v[248:251]
	v_mul_f32_e32 v152, 0x3fb8aa3b, v152
	v_mul_f32_e32 v153, 0x3fb8aa3b, v153
	v_mul_f32_e32 v154, 0x3fb8aa3b, v154
	v_mul_f32_e32 v155, 0x3fb8aa3b, v155
	v_exp_f32_e32 v152, v152
	v_exp_f32_e32 v153, v153
	v_exp_f32_e32 v154, v154
	v_exp_f32_e32 v155, v155
	v_add_u32_e32 v138, 0x70, v175
	v_add_u32_e32 v139, 0x71, v175
	v_add_u32_e32 v140, 0x72, v175
	v_add_u32_e32 v141, 0x73, v175
	v_cmp_gt_u32_e64 s[70:71], s44, v138
	v_cmp_gt_u32_e64 s[72:73], s44, v139
	v_cmp_gt_u32_e64 s[74:75], s44, v140
	v_cmp_gt_u32_e64 s[76:77], s44, v141
	v_cndmask_b32_e64 v152, 0, v152, s[70:71]
	v_cndmask_b32_e64 v153, 0, v153, s[72:73]
	v_cndmask_b32_e64 v154, 0, v154, s[74:75]
	v_cndmask_b32_e64 v155, 0, v155, s[76:77]
	v_add_f32_e32 v132, v132, v152
	v_add_f32_e32 v132, v132, v153
	v_add_f32_e32 v132, v132, v154
	v_add_f32_e32 v132, v132, v155
	v_cvt_pk_bf16_f32 v126, v152, v153
	v_cvt_pk_bf16_f32 v127, v154, v155
	v_mul_f32_e32 v156, 0x3fb8aa3b, v156
	v_mul_f32_e32 v157, 0x3fb8aa3b, v157
	v_mul_f32_e32 v158, 0x3fb8aa3b, v158
	v_mul_f32_e32 v159, 0x3fb8aa3b, v159
	v_exp_f32_e32 v156, v156
	v_exp_f32_e32 v157, v157
	v_exp_f32_e32 v158, v158
	v_exp_f32_e32 v159, v159
	v_add_u32_e32 v138, 0x70, v175
	v_add_u32_e32 v139, 0x71, v175
	v_add_u32_e32 v140, 0x72, v175
	v_add_u32_e32 v141, 0x73, v175
	v_cmp_gt_u32_e64 s[70:71], s44, v138
	v_cmp_gt_u32_e64 s[72:73], s44, v139
	v_cmp_gt_u32_e64 s[74:75], s44, v140
	v_cmp_gt_u32_e64 s[76:77], s44, v141
	v_cndmask_b32_e64 v156, 0, v156, s[70:71]
	v_cndmask_b32_e64 v157, 0, v157, s[72:73]
	v_cndmask_b32_e64 v158, 0, v158, s[74:75]
	v_cndmask_b32_e64 v159, 0, v159, s[76:77]
	v_add_f32_e32 v133, v133, v156
	v_add_f32_e32 v133, v133, v157
	v_add_f32_e32 v133, v133, v158
	v_add_f32_e32 v133, v133, v159
	v_cvt_pk_bf16_f32 v198, v156, v157
	v_cvt_pk_bf16_f32 v199, v158, v159
	v_min_f32_e32 v152, 0x42a00000, v236
	v_min_f32_e32 v153, 0x42a00000, v237
	v_min_f32_e32 v154, 0x42a00000, v238
	v_min_f32_e32 v155, 0x42a00000, v239
	v_min_f32_e32 v156, 0x42a00000, v244
	v_min_f32_e32 v157, 0x42a00000, v245
	v_min_f32_e32 v158, 0x42a00000, v246
	v_min_f32_e32 v159, 0x42a00000, v247
	v_mul_f32_e32 v152, 0x3fb8aa3b, v152
	v_mul_f32_e32 v153, 0x3fb8aa3b, v153
	v_mul_f32_e32 v154, 0x3fb8aa3b, v154
	v_mul_f32_e32 v155, 0x3fb8aa3b, v155
	v_exp_f32_e32 v152, v152
	v_exp_f32_e32 v153, v153
	v_exp_f32_e32 v154, v154
	v_exp_f32_e32 v155, v155
	v_add_u32_e32 v138, 0x80, v175
	v_add_u32_e32 v139, 0x81, v175
	v_add_u32_e32 v140, 0x82, v175
	v_add_u32_e32 v141, 0x83, v175
	v_cmp_gt_u32_e64 s[70:71], s44, v138
	v_cmp_gt_u32_e64 s[72:73], s44, v139
	v_cmp_gt_u32_e64 s[74:75], s44, v140
	v_cmp_gt_u32_e64 s[76:77], s44, v141
	v_cndmask_b32_e64 v152, 0, v152, s[62:63]
	v_cndmask_b32_e64 v153, 0, v153, s[64:65]
	v_cndmask_b32_e64 v154, 0, v154, s[66:67]
	v_cndmask_b32_e64 v155, 0, v155, s[68:69]
	v_cndmask_b32_e64 v152, 0, v152, s[70:71]
	v_cndmask_b32_e64 v153, 0, v153, s[72:73]
	v_cndmask_b32_e64 v154, 0, v154, s[74:75]
	v_cndmask_b32_e64 v155, 0, v155, s[76:77]
	v_add_f32_e32 v132, v132, v152
	v_add_f32_e32 v132, v132, v153
	v_add_f32_e32 v132, v132, v154
	v_add_f32_e32 v132, v132, v155
	v_cvt_pk_bf16_f32 v128, v152, v153
	v_cvt_pk_bf16_f32 v129, v154, v155
	v_mul_f32_e32 v156, 0x3fb8aa3b, v156
	v_mul_f32_e32 v157, 0x3fb8aa3b, v157
	v_mul_f32_e32 v158, 0x3fb8aa3b, v158
	v_mul_f32_e32 v159, 0x3fb8aa3b, v159
	v_exp_f32_e32 v156, v156
	v_exp_f32_e32 v157, v157
	v_exp_f32_e32 v158, v158
	v_exp_f32_e32 v159, v159
	v_add_u32_e32 v138, 0x80, v175
	v_add_u32_e32 v139, 0x81, v175
	v_add_u32_e32 v140, 0x82, v175
	v_add_u32_e32 v141, 0x83, v175
	v_cmp_gt_u32_e64 s[70:71], s44, v138
	v_cmp_gt_u32_e64 s[72:73], s44, v139
	v_cmp_gt_u32_e64 s[74:75], s44, v140
	v_cmp_gt_u32_e64 s[76:77], s44, v141
	v_cndmask_b32_e64 v156, 0, v156, s[70:71]
	v_cndmask_b32_e64 v157, 0, v157, s[72:73]
	v_cndmask_b32_e64 v158, 0, v158, s[74:75]
	v_cndmask_b32_e64 v159, 0, v159, s[76:77]
	v_add_f32_e32 v133, v133, v156
	v_add_f32_e32 v133, v133, v157
	v_add_f32_e32 v133, v133, v158
	v_add_f32_e32 v133, v133, v159
	v_cvt_pk_bf16_f32 v200, v156, v157
	v_cvt_pk_bf16_f32 v201, v158, v159
	v_min_f32_e32 v156, 0x42a00000, v248
	v_min_f32_e32 v157, 0x42a00000, v249
	v_min_f32_e32 v158, 0x42a00000, v250
	v_min_f32_e32 v159, 0x42a00000, v251
	v_mul_f32_e32 v156, 0x3fb8aa3b, v156
	v_mul_f32_e32 v157, 0x3fb8aa3b, v157
	v_mul_f32_e32 v158, 0x3fb8aa3b, v158
	v_mul_f32_e32 v159, 0x3fb8aa3b, v159
	v_exp_f32_e32 v156, v156
	v_exp_f32_e32 v157, v157
	v_exp_f32_e32 v158, v158
	v_exp_f32_e32 v159, v159
	v_add_u32_e32 v138, 0x90, v175
	v_add_u32_e32 v139, 0x91, v175
	v_add_u32_e32 v140, 0x92, v175
	v_add_u32_e32 v141, 0x93, v175
	v_cmp_gt_u32_e64 s[70:71], s44, v138
	v_cmp_gt_u32_e64 s[72:73], s44, v139
	v_cmp_gt_u32_e64 s[74:75], s44, v140
	v_cmp_gt_u32_e64 s[76:77], s44, v141
	v_cndmask_b32_e64 v156, 0, v156, s[62:63]
	v_cndmask_b32_e64 v157, 0, v157, s[64:65]
	v_cndmask_b32_e64 v158, 0, v158, s[66:67]
	v_cndmask_b32_e64 v159, 0, v159, s[68:69]
	v_cndmask_b32_e64 v156, 0, v156, s[70:71]
	v_cndmask_b32_e64 v157, 0, v157, s[72:73]
	v_cndmask_b32_e64 v158, 0, v158, s[74:75]
	v_cndmask_b32_e64 v159, 0, v159, s[76:77]
	v_add_f32_e32 v133, v133, v156
	v_add_f32_e32 v133, v133, v157
	v_add_f32_e32 v133, v133, v158
	v_add_f32_e32 v133, v133, v159
	v_cvt_pk_bf16_f32 v202, v156, v157
	v_cvt_pk_bf16_f32 v203, v158, v159
	v_add_u32_e32 v134, s42, v160
	v_lshlrev_b32_e32 v134, 4, v134
	v_add_u32_e32 v134, s43, v134
	v_subrev_u32_e32 v135, s15, v134
	v_lshrrev_b32_e32 v136, 4, v135
	v_add_u32_e32 v136, v136, v135
	v_mad_u32_u24 v176, v136, s79, v161
	v_lshl_add_u32 v177, v135, 2, s80
	s_sub_i32 s2, s42, 64
	v_add_u32_e32 v178, s2, v169
	v_and_b32_e32 v135, 3, v134
	v_lshlrev_b32_e32 v135, s13, v135
	v_lshrrev_b32_e32 v136, 2, v134
	v_add_u32_e32 v135, v135, v136
	v_lshl_add_u32 v135, v135, 7, v161
	global_load_dwordx4 v[48:51], v135, s[18:19] nt
	global_load_dwordx4 v[52:55], v135, s[18:19] offset:64 nt
	v_subrev_u32_e32 v134, 0x400, v134
	v_and_b32_e32 v137, 3, v134
	v_lshlrev_b32_e32 v137, s13, v137
	v_bfe_u32 v135, v134, 2, 2
	v_add_u32_e32 v137, v137, v135
	v_lshl_add_u32 v183, v137, 7, v161
	v_ashrrev_i32_e32 v252, 4, v134
	v_med3_i32 v136, v252, 0, s14
	v_lshl_add_u32 v136, v136, 9, v183
	global_load_dwordx4 v[0:3], v136, s[20:21]
	global_load_dwordx4 v[4:7], v136, s[20:21] offset:64
	v_add_u32_e32 v135, 16, v252
	v_med3_i32 v135, v135, 0, s14
	v_lshl_add_u32 v135, v135, 9, v183
	global_load_dwordx4 v[8:11], v135, s[20:21]
	global_load_dwordx4 v[12:15], v135, s[20:21] offset:64
	v_add_u32_e32 v136, 32, v252
	v_med3_i32 v136, v136, 0, s14
	v_lshl_add_u32 v136, v136, 9, v183
	global_load_dwordx4 v[16:19], v136, s[20:21]
	global_load_dwordx4 v[20:23], v136, s[20:21] offset:64
	v_add_u32_e32 v135, 48, v252
	v_med3_i32 v135, v135, 0, s14
	v_lshl_add_u32 v135, v135, 9, v183
	global_load_dwordx4 v[24:27], v135, s[20:21]
	global_load_dwordx4 v[28:31], v135, s[20:21] offset:64
	v_add_u32_e32 v136, 64, v252
	v_med3_i32 v136, v136, 0, s14
	v_lshl_add_u32 v136, v136, 9, v183
	global_load_dwordx4 v[32:35], v136, s[20:21]
	global_load_dwordx4 v[36:39], v136, s[20:21] offset:64
	v_add_u32_e32 v135, 0x50, v252
	v_med3_i32 v135, v135, 0, s14
	v_lshl_add_u32 v135, v135, 9, v183
	global_load_dwordx4 v[40:43], v135, s[20:21]
	global_load_dwordx4 v[44:47], v135, s[20:21] offset:64
	ds_bpermute_b32 v142, v167, v132
	s_waitcnt lgkmcnt(0)
	v_add_f32_e32 v132, v132, v142
	ds_bpermute_b32 v142, v168, v132
	s_waitcnt lgkmcnt(0)
	v_add_f32_e32 v132, v132, v142
	ds_bpermute_b32 v142, v167, v133
	s_waitcnt lgkmcnt(0)
	v_add_f32_e32 v133, v133, v142
	ds_bpermute_b32 v142, v168, v133
	s_waitcnt lgkmcnt(0)
	v_add_f32_e32 v133, v133, v142
	s_waitcnt vmcnt(14)
	ds_write_b128 v165, v[64:67]
	ds_write_b128 v165, v[68:71] offset:1152
	ds_write_b128 v165, v[72:75] offset:2304
	ds_write_b128 v165, v[76:79] offset:3456
	s_waitcnt lgkmcnt(0)
	ds_read_b64_tr_b16 v[236:237], v166
	ds_read_b64_tr_b16 v[238:239], v166 offset:2304
	ds_read_b64_tr_b16 v[240:241], v166 offset:32
	ds_read_b64_tr_b16 v[242:243], v166 offset:2336
	ds_read_b64_tr_b16 v[244:245], v166 offset:64
	ds_read_b64_tr_b16 v[246:247], v166 offset:2368
	ds_read_b64_tr_b16 v[248:249], v166 offset:96
	ds_read_b64_tr_b16 v[250:251], v166 offset:2400
	s_waitcnt lgkmcnt(0)
	s_add_i32 s2, s40, 32
	v_add_u32_e32 v138, s2, v164
	v_lshlrev_b32_e32 v138, 2, v138
	v_add_u32_e32 v138, s41, v138
	v_and_b32_e32 v139, 3, v138
	v_lshlrev_b32_e32 v139, s39, v139
	v_bfe_u32 v140, v138, 2, 2
	v_add_u32_e32 v139, v139, v140
	v_lshl_add_u32 v139, v139, 7, v162
	v_ashrrev_i32_e32 v138, 4, v138
	v_med3_i32 v138, v138, 0, s38
	v_lshl_add_u32 v138, v138, 9, v139
	global_load_dwordx4 v[64:67], v138, s[26:27]
	s_add_i32 s2, s40, 40
	v_add_u32_e32 v138, s2, v164
	v_lshlrev_b32_e32 v138, 2, v138
	v_add_u32_e32 v138, s41, v138
	v_and_b32_e32 v139, 3, v138
	v_lshlrev_b32_e32 v139, s39, v139
	v_bfe_u32 v140, v138, 2, 2
	v_add_u32_e32 v139, v139, v140
	v_lshl_add_u32 v139, v139, 7, v162
	v_ashrrev_i32_e32 v138, 4, v138
	v_med3_i32 v138, v138, 0, s38
	v_lshl_add_u32 v138, v138, 9, v139
	global_load_dwordx4 v[68:71], v138, s[26:27]
	s_add_i32 s2, s40, 48
	v_add_u32_e32 v138, s2, v164
	v_lshlrev_b32_e32 v138, 2, v138
	v_add_u32_e32 v138, s41, v138
	v_and_b32_e32 v139, 3, v138
	v_lshlrev_b32_e32 v139, s39, v139
	v_bfe_u32 v140, v138, 2, 2
	v_add_u32_e32 v139, v139, v140
	v_lshl_add_u32 v139, v139, 7, v162
	v_ashrrev_i32_e32 v138, 4, v138
	v_med3_i32 v138, v138, 0, s38
	v_lshl_add_u32 v138, v138, 9, v139
	global_load_dwordx4 v[72:75], v138, s[26:27]
	s_add_i32 s2, s40, 56
	v_add_u32_e32 v138, s2, v164
	v_lshlrev_b32_e32 v138, 2, v138
	v_add_u32_e32 v138, s41, v138
	v_and_b32_e32 v139, 3, v138
	v_lshlrev_b32_e32 v139, s39, v139
	v_bfe_u32 v140, v138, 2, 2
	v_add_u32_e32 v139, v139, v140
	v_lshl_add_u32 v139, v139, 7, v162
	v_ashrrev_i32_e32 v138, 4, v138
	v_med3_i32 v138, v138, 0, s38
	v_lshl_add_u32 v138, v138, 9, v139
	global_load_dwordx4 v[76:79], v138, s[26:27]
	ds_write_b128 v165, v[80:83]
	ds_write_b128 v165, v[84:87] offset:1152
	ds_write_b128 v165, v[88:91] offset:2304
	ds_write_b128 v165, v[92:95] offset:3456
	v_mfma_f32_16x16x32_bf16 v[204:207], v[236:239], v[112:115], 0
	v_mfma_f32_16x16x32_bf16 v[208:211], v[240:243], v[112:115], 0
	v_mfma_f32_16x16x32_bf16 v[212:215], v[244:247], v[112:115], 0
	v_mfma_f32_16x16x32_bf16 v[216:219], v[248:251], v[112:115], 0
	v_mfma_f32_16x16x32_bf16 v[220:223], v[236:239], v[184:187], 0
	v_mfma_f32_16x16x32_bf16 v[224:227], v[240:243], v[184:187], 0
	v_mfma_f32_16x16x32_bf16 v[228:231], v[244:247], v[184:187], 0
	v_mfma_f32_16x16x32_bf16 v[232:235], v[248:251], v[184:187], 0
	s_waitcnt lgkmcnt(0)
	ds_read_b64_tr_b16 v[236:237], v166
	ds_read_b64_tr_b16 v[238:239], v166 offset:2304
	ds_read_b64_tr_b16 v[240:241], v166 offset:32
	ds_read_b64_tr_b16 v[242:243], v166 offset:2336
	ds_read_b64_tr_b16 v[244:245], v166 offset:64
	ds_read_b64_tr_b16 v[246:247], v166 offset:2368
	ds_read_b64_tr_b16 v[248:249], v166 offset:96
	ds_read_b64_tr_b16 v[250:251], v166 offset:2400
	s_waitcnt lgkmcnt(0)
	s_add_i32 s2, s40, 64
	v_add_u32_e32 v138, s2, v164
	v_lshlrev_b32_e32 v138, 2, v138
	v_add_u32_e32 v138, s41, v138
	v_and_b32_e32 v139, 3, v138
	v_lshlrev_b32_e32 v139, s39, v139
	v_bfe_u32 v140, v138, 2, 2
	v_add_u32_e32 v139, v139, v140
	v_lshl_add_u32 v139, v139, 7, v162
	v_ashrrev_i32_e32 v138, 4, v138
	v_med3_i32 v138, v138, 0, s38
	v_lshl_add_u32 v138, v138, 9, v139
	global_load_dwordx4 v[80:83], v138, s[26:27]
	s_add_i32 s2, s40, 72
	v_add_u32_e32 v138, s2, v164
	v_lshlrev_b32_e32 v138, 2, v138
	v_add_u32_e32 v138, s41, v138
	v_and_b32_e32 v139, 3, v138
	v_lshlrev_b32_e32 v139, s39, v139
	v_bfe_u32 v140, v138, 2, 2
	v_add_u32_e32 v139, v139, v140
	v_lshl_add_u32 v139, v139, 7, v162
	v_ashrrev_i32_e32 v138, 4, v138
	v_med3_i32 v138, v138, 0, s38
	v_lshl_add_u32 v138, v138, 9, v139
	global_load_dwordx4 v[84:87], v138, s[26:27]
	s_add_i32 s2, s40, 80
	v_add_u32_e32 v138, s2, v164
	v_lshlrev_b32_e32 v138, 2, v138
	v_add_u32_e32 v138, s41, v138
	v_and_b32_e32 v139, 3, v138
	v_lshlrev_b32_e32 v139, s39, v139
	v_bfe_u32 v140, v138, 2, 2
	v_add_u32_e32 v139, v139, v140
	v_lshl_add_u32 v139, v139, 7, v162
	v_ashrrev_i32_e32 v138, 4, v138
	v_med3_i32 v138, v138, 0, s38
	v_lshl_add_u32 v138, v138, 9, v139
	global_load_dwordx4 v[88:91], v138, s[26:27]
	s_add_i32 s2, s40, 88
	v_add_u32_e32 v138, s2, v164
	v_lshlrev_b32_e32 v138, 2, v138
	v_add_u32_e32 v138, s41, v138
	v_and_b32_e32 v139, 3, v138
	v_lshlrev_b32_e32 v139, s39, v139
	v_bfe_u32 v140, v138, 2, 2
	v_add_u32_e32 v139, v139, v140
	v_lshl_add_u32 v139, v139, 7, v162
	v_ashrrev_i32_e32 v138, 4, v138
	v_med3_i32 v138, v138, 0, s38
	v_lshl_add_u32 v138, v138, 9, v139
	global_load_dwordx4 v[92:95], v138, s[26:27]
	ds_write_b128 v165, v[96:99]
	ds_write_b128 v165, v[100:103] offset:1152
	ds_write_b128 v165, v[104:107] offset:2304
	ds_write_b128 v165, v[108:111] offset:3456
	v_mfma_f32_16x16x32_bf16 v[204:207], v[236:239], v[116:119], v[204:207]
	v_mfma_f32_16x16x32_bf16 v[208:211], v[240:243], v[116:119], v[208:211]
	v_mfma_f32_16x16x32_bf16 v[212:215], v[244:247], v[116:119], v[212:215]
	v_mfma_f32_16x16x32_bf16 v[216:219], v[248:251], v[116:119], v[216:219]
	v_mfma_f32_16x16x32_bf16 v[220:223], v[236:239], v[188:191], v[220:223]
	v_mfma_f32_16x16x32_bf16 v[224:227], v[240:243], v[188:191], v[224:227]
	v_mfma_f32_16x16x32_bf16 v[228:231], v[244:247], v[188:191], v[228:231]
	v_mfma_f32_16x16x32_bf16 v[232:235], v[248:251], v[188:191], v[232:235]
	s_waitcnt lgkmcnt(0)
	ds_read_b64_tr_b16 v[236:237], v166
	ds_read_b64_tr_b16 v[238:239], v166 offset:2304
	ds_read_b64_tr_b16 v[240:241], v166 offset:32
	ds_read_b64_tr_b16 v[242:243], v166 offset:2336
	ds_read_b64_tr_b16 v[244:245], v166 offset:64
	ds_read_b64_tr_b16 v[246:247], v166 offset:2368
	ds_read_b64_tr_b16 v[248:249], v166 offset:96
	ds_read_b64_tr_b16 v[250:251], v166 offset:2400
	s_waitcnt lgkmcnt(0)
	s_waitcnt vmcnt(4)
	ds_write_b128 v165, v[64:67]
	ds_write_b128 v165, v[68:71] offset:1152
	ds_write_b128 v165, v[72:75] offset:2304
	ds_write_b128 v165, v[76:79] offset:3456
	v_mfma_f32_16x16x32_bf16 v[204:207], v[236:239], v[120:123], v[204:207]
	v_mfma_f32_16x16x32_bf16 v[208:211], v[240:243], v[120:123], v[208:211]
	v_mfma_f32_16x16x32_bf16 v[212:215], v[244:247], v[120:123], v[212:215]
	v_mfma_f32_16x16x32_bf16 v[216:219], v[248:251], v[120:123], v[216:219]
	v_mfma_f32_16x16x32_bf16 v[220:223], v[236:239], v[192:195], v[220:223]
	v_mfma_f32_16x16x32_bf16 v[224:227], v[240:243], v[192:195], v[224:227]
	v_mfma_f32_16x16x32_bf16 v[228:231], v[244:247], v[192:195], v[228:231]
	v_mfma_f32_16x16x32_bf16 v[232:235], v[248:251], v[192:195], v[232:235]
	s_waitcnt lgkmcnt(0)
	ds_read_b64_tr_b16 v[236:237], v166
	ds_read_b64_tr_b16 v[238:239], v166 offset:2304
	ds_read_b64_tr_b16 v[240:241], v166 offset:32
	ds_read_b64_tr_b16 v[242:243], v166 offset:2336
	ds_read_b64_tr_b16 v[244:245], v166 offset:64
	ds_read_b64_tr_b16 v[246:247], v166 offset:2368
	ds_read_b64_tr_b16 v[248:249], v166 offset:96
	ds_read_b64_tr_b16 v[250:251], v166 offset:2400
	s_waitcnt lgkmcnt(0)
	s_waitcnt vmcnt(0)
	ds_write_b128 v165, v[80:83]
	ds_write_b128 v165, v[84:87] offset:1152
	ds_write_b128 v165, v[88:91] offset:2304
	ds_write_b128 v165, v[92:95] offset:3456
	v_mfma_f32_16x16x32_bf16 v[204:207], v[236:239], v[124:127], v[204:207]
	v_mfma_f32_16x16x32_bf16 v[208:211], v[240:243], v[124:127], v[208:211]
	v_mfma_f32_16x16x32_bf16 v[212:215], v[244:247], v[124:127], v[212:215]
	v_mfma_f32_16x16x32_bf16 v[216:219], v[248:251], v[124:127], v[216:219]
	v_mfma_f32_16x16x32_bf16 v[220:223], v[236:239], v[196:199], v[220:223]
	v_mfma_f32_16x16x32_bf16 v[224:227], v[240:243], v[196:199], v[224:227]
	v_mfma_f32_16x16x32_bf16 v[228:231], v[244:247], v[196:199], v[228:231]
	v_mfma_f32_16x16x32_bf16 v[232:235], v[248:251], v[196:199], v[232:235]
	s_waitcnt lgkmcnt(0)
	ds_read_b64_tr_b16 v[236:237], v166
	ds_read_b64_tr_b16 v[238:239], v166 offset:2304
	ds_read_b64_tr_b16 v[240:241], v166 offset:32
	ds_read_b64_tr_b16 v[242:243], v166 offset:2336
	ds_read_b64_tr_b16 v[244:245], v166 offset:64
	ds_read_b64_tr_b16 v[246:247], v166 offset:2368
	ds_read_b64_tr_b16 v[248:249], v166 offset:96
	ds_read_b64_tr_b16 v[250:251], v166 offset:2400
	s_waitcnt lgkmcnt(0)
	v_mfma_f32_16x16x32_bf16 v[204:207], v[236:239], v[128:131], v[204:207]
	v_mfma_f32_16x16x32_bf16 v[208:211], v[240:243], v[128:131], v[208:211]
	v_mfma_f32_16x16x32_bf16 v[212:215], v[244:247], v[128:131], v[212:215]
	v_mfma_f32_16x16x32_bf16 v[216:219], v[248:251], v[128:131], v[216:219]
	v_mfma_f32_16x16x32_bf16 v[220:223], v[236:239], v[200:203], v[220:223]
	v_mfma_f32_16x16x32_bf16 v[224:227], v[240:243], v[200:203], v[224:227]
	v_mfma_f32_16x16x32_bf16 v[228:231], v[244:247], v[200:203], v[228:231]
	v_mfma_f32_16x16x32_bf16 v[232:235], v[248:251], v[200:203], v[232:235]
	s_add_i32 s2, s42, -64
	v_add_u32_e32 v138, s2, v164
	v_lshlrev_b32_e32 v138, 4, v138
	v_add_u32_e32 v138, s43, v138
	v_and_b32_e32 v139, 3, v138
	v_lshlrev_b32_e32 v139, s13, v139
	v_bfe_u32 v140, v138, 2, 2
	v_add_u32_e32 v139, v139, v140
	v_lshl_add_u32 v139, v139, 7, v162
	v_ashrrev_i32_e32 v138, 4, v138
	v_med3_i32 v138, v138, 0, s14
	v_lshl_add_u32 v138, v138, 9, v139
	global_load_dwordx4 v[64:67], v138, s[22:23]
	s_add_i32 s2, s42, -56
	v_add_u32_e32 v138, s2, v164
	v_lshlrev_b32_e32 v138, 4, v138
	v_add_u32_e32 v138, s43, v138
	v_and_b32_e32 v139, 3, v138
	v_lshlrev_b32_e32 v139, s13, v139
	v_bfe_u32 v140, v138, 2, 2
	v_add_u32_e32 v139, v139, v140
	v_lshl_add_u32 v139, v139, 7, v162
	v_ashrrev_i32_e32 v138, 4, v138
	v_med3_i32 v138, v138, 0, s14
	v_lshl_add_u32 v138, v138, 9, v139
	global_load_dwordx4 v[68:71], v138, s[22:23]
	s_add_i32 s2, s42, -48
	v_add_u32_e32 v138, s2, v164
	v_lshlrev_b32_e32 v138, 4, v138
	v_add_u32_e32 v138, s43, v138
	v_and_b32_e32 v139, 3, v138
	v_lshlrev_b32_e32 v139, s13, v139
	v_bfe_u32 v140, v138, 2, 2
	v_add_u32_e32 v139, v139, v140
	v_lshl_add_u32 v139, v139, 7, v162
	v_ashrrev_i32_e32 v138, 4, v138
	v_med3_i32 v138, v138, 0, s14
	v_lshl_add_u32 v138, v138, 9, v139
	global_load_dwordx4 v[72:75], v138, s[22:23]
	s_add_i32 s2, s42, -40
	v_add_u32_e32 v138, s2, v164
	v_lshlrev_b32_e32 v138, 4, v138
	v_add_u32_e32 v138, s43, v138
	v_and_b32_e32 v139, 3, v138
	v_lshlrev_b32_e32 v139, s13, v139
	v_bfe_u32 v140, v138, 2, 2
	v_add_u32_e32 v139, v139, v140
	v_lshl_add_u32 v139, v139, 7, v162
	v_ashrrev_i32_e32 v138, 4, v138
	v_med3_i32 v138, v138, 0, s14
	v_lshl_add_u32 v138, v138, 9, v139
	global_load_dwordx4 v[76:79], v138, s[22:23]
	s_add_i32 s2, s42, -32
	v_add_u32_e32 v138, s2, v164
	v_lshlrev_b32_e32 v138, 4, v138
	v_add_u32_e32 v138, s43, v138
	v_and_b32_e32 v139, 3, v138
	v_lshlrev_b32_e32 v139, s13, v139
	v_bfe_u32 v140, v138, 2, 2
	v_add_u32_e32 v139, v139, v140
	v_lshl_add_u32 v139, v139, 7, v162
	v_ashrrev_i32_e32 v138, 4, v138
	v_med3_i32 v138, v138, 0, s14
	v_lshl_add_u32 v138, v138, 9, v139
	global_load_dwordx4 v[80:83], v138, s[22:23]
	s_add_i32 s2, s42, -24
	v_add_u32_e32 v138, s2, v164
	v_lshlrev_b32_e32 v138, 4, v138
	v_add_u32_e32 v138, s43, v138
	v_and_b32_e32 v139, 3, v138
	v_lshlrev_b32_e32 v139, s13, v139
	v_bfe_u32 v140, v138, 2, 2
	v_add_u32_e32 v139, v139, v140
	v_lshl_add_u32 v139, v139, 7, v162
	v_ashrrev_i32_e32 v138, 4, v138
	v_med3_i32 v138, v138, 0, s14
	v_lshl_add_u32 v138, v138, 9, v139
	global_load_dwordx4 v[84:87], v138, s[22:23]
	s_add_i32 s2, s42, -16
	v_add_u32_e32 v138, s2, v164
	v_lshlrev_b32_e32 v138, 4, v138
	v_add_u32_e32 v138, s43, v138
	v_and_b32_e32 v139, 3, v138
	v_lshlrev_b32_e32 v139, s13, v139
	v_bfe_u32 v140, v138, 2, 2
	v_add_u32_e32 v139, v139, v140
	v_lshl_add_u32 v139, v139, 7, v162
	v_ashrrev_i32_e32 v138, 4, v138
	v_med3_i32 v138, v138, 0, s14
	v_lshl_add_u32 v138, v138, 9, v139
	global_load_dwordx4 v[88:91], v138, s[22:23]
	s_add_i32 s2, s42, -8
	v_add_u32_e32 v138, s2, v164
	v_lshlrev_b32_e32 v138, 4, v138
	v_add_u32_e32 v138, s43, v138
	v_and_b32_e32 v139, 3, v138
	v_lshlrev_b32_e32 v139, s13, v139
	v_bfe_u32 v140, v138, 2, 2
	v_add_u32_e32 v139, v139, v140
	v_lshl_add_u32 v139, v139, 7, v162
	v_ashrrev_i32_e32 v138, 4, v138
	v_med3_i32 v138, v138, 0, s14
	v_lshl_add_u32 v138, v138, 9, v139
	global_load_dwordx4 v[92:95], v138, s[22:23]
	s_add_i32 s2, s42, 0
	v_add_u32_e32 v138, s2, v164
	v_lshlrev_b32_e32 v138, 4, v138
	v_add_u32_e32 v138, s43, v138
	v_and_b32_e32 v139, 3, v138
	v_lshlrev_b32_e32 v139, s13, v139
	v_bfe_u32 v140, v138, 2, 2
	v_add_u32_e32 v139, v139, v140
	v_lshl_add_u32 v139, v139, 7, v162
	v_ashrrev_i32_e32 v138, 4, v138
	v_med3_i32 v138, v138, 0, s14
	v_lshl_add_u32 v138, v138, 9, v139
	global_load_dwordx4 v[96:99], v138, s[22:23]
	s_add_i32 s2, s42, 8
	v_add_u32_e32 v138, s2, v164
	v_lshlrev_b32_e32 v138, 4, v138
	v_add_u32_e32 v138, s43, v138
	v_and_b32_e32 v139, 3, v138
	v_lshlrev_b32_e32 v139, s13, v139
	v_bfe_u32 v140, v138, 2, 2
	v_add_u32_e32 v139, v139, v140
	v_lshl_add_u32 v139, v139, 7, v162
	v_ashrrev_i32_e32 v138, 4, v138
	v_med3_i32 v138, v138, 0, s14
	v_lshl_add_u32 v138, v138, 9, v139
	global_load_dwordx4 v[100:103], v138, s[22:23]
	s_add_i32 s2, s42, 16
	v_add_u32_e32 v138, s2, v164
	v_lshlrev_b32_e32 v138, 4, v138
	v_add_u32_e32 v138, s43, v138
	v_and_b32_e32 v139, 3, v138
	v_lshlrev_b32_e32 v139, s13, v139
	v_bfe_u32 v140, v138, 2, 2
	v_add_u32_e32 v139, v139, v140
	v_lshl_add_u32 v139, v139, 7, v162
	v_ashrrev_i32_e32 v138, 4, v138
	v_med3_i32 v138, v138, 0, s14
	v_lshl_add_u32 v138, v138, 9, v139
	global_load_dwordx4 v[104:107], v138, s[22:23]
	s_add_i32 s2, s42, 24
	v_add_u32_e32 v138, s2, v164
	v_lshlrev_b32_e32 v138, 4, v138
	v_add_u32_e32 v138, s43, v138
	v_and_b32_e32 v139, 3, v138
	v_lshlrev_b32_e32 v139, s13, v139
	v_bfe_u32 v140, v138, 2, 2
	v_add_u32_e32 v139, v139, v140
	v_lshl_add_u32 v139, v139, 7, v162
	v_ashrrev_i32_e32 v138, 4, v138
	v_med3_i32 v138, v138, 0, s14
	v_lshl_add_u32 v138, v138, 9, v139
	global_load_dwordx4 v[108:111], v138, s[22:23]
	ds_read_b128 v[236:239], v173 offset:0
	ds_read_b128 v[240:243], v173 offset:64
	ds_read_b128 v[244:247], v173 offset:128
	ds_read_b128 v[248:251], v173 offset:192
	ds_read_b32 v142, v174 offset:0
	s_waitcnt lgkmcnt(0)
	v_add_f32_e32 v204, v236, v204
	v_add_f32_e32 v205, v237, v205
	v_add_f32_e32 v206, v238, v206
	v_add_f32_e32 v207, v239, v207
	v_add_f32_e32 v208, v240, v208
	v_add_f32_e32 v209, v241, v209
	v_add_f32_e32 v210, v242, v210
	v_add_f32_e32 v211, v243, v211
	v_add_f32_e32 v212, v244, v212
	v_add_f32_e32 v213, v245, v213
	v_add_f32_e32 v214, v246, v214
	v_add_f32_e32 v215, v247, v215
	v_add_f32_e32 v216, v248, v216
	v_add_f32_e32 v217, v249, v217
	v_add_f32_e32 v218, v250, v218
	v_add_f32_e32 v219, v251, v219
	v_add_f32_e32 v132, v142, v132
	ds_write_b128 v173, v[204:207] offset:0
	ds_write_b128 v173, v[208:211] offset:64
	ds_write_b128 v173, v[212:215] offset:128
	ds_write_b128 v173, v[216:219] offset:192
	ds_write_b32 v174, v132 offset:0
	ds_read_b128 v[236:239], v173 offset:18496
	ds_read_b128 v[240:243], v173 offset:18560
	ds_read_b128 v[244:247], v173 offset:18624
	ds_read_b128 v[248:251], v173 offset:18688
	ds_read_b32 v142, v174 offset:256
	s_waitcnt lgkmcnt(0)
	v_add_f32_e32 v220, v236, v220
	v_add_f32_e32 v221, v237, v221
	v_add_f32_e32 v222, v238, v222
	v_add_f32_e32 v223, v239, v223
	v_add_f32_e32 v224, v240, v224
	v_add_f32_e32 v225, v241, v225
	v_add_f32_e32 v226, v242, v226
	v_add_f32_e32 v227, v243, v227
	v_add_f32_e32 v228, v244, v228
	v_add_f32_e32 v229, v245, v229
	v_add_f32_e32 v230, v246, v230
	v_add_f32_e32 v231, v247, v231
	v_add_f32_e32 v232, v248, v232
	v_add_f32_e32 v233, v249, v233
	v_add_f32_e32 v234, v250, v234
	v_add_f32_e32 v235, v251, v235
	v_add_f32_e32 v133, v142, v133
	ds_write_b128 v173, v[220:223] offset:18496
	ds_write_b128 v173, v[224:227] offset:18560
	ds_write_b128 v173, v[228:231] offset:18624
	ds_write_b128 v173, v[232:235] offset:18688
	ds_write_b32 v174, v133 offset:256
	s_waitcnt lgkmcnt(0)
	s_barrier
	s_mov_b32 s40, s42
	s_mov_b32 s41, s43
	v_mov_b32_e32 v173, v176
	v_mov_b32_e32 v174, v177
	v_mov_b32_e32 v175, v178
	v_mov_b32_e32 v179, v183
	v_mov_b32_e32 v182, v252
	s_lshr_b32 s44, s33, 4
	s_lshr_b32 s42, s15, 4
	s_add_i32 s43, s0, 8
	s_waitcnt vmcnt(12)
	v_mov_b32_e32 v132, 0
	v_mfma_f32_16x16x32_bf16 v[236:239], v[0:3], v[48:51], 0
	v_mfma_f32_16x16x32_bf16 v[236:239], v[4:7], v[52:55], v[236:239]
	v_mfma_f32_16x16x32_bf16 v[240:243], v[8:11], v[48:51], 0
	v_mfma_f32_16x16x32_bf16 v[240:243], v[12:15], v[52:55], v[240:243]
	s_nop 7
	v_min_f32_e32 v152, 0x42a00000, v236
	v_min_f32_e32 v153, 0x42a00000, v237
	v_min_f32_e32 v154, 0x42a00000, v238
	v_min_f32_e32 v155, 0x42a00000, v239
	v_mfma_f32_16x16x32_bf16 v[236:239], v[16:19], v[48:51], 0
	v_mfma_f32_16x16x32_bf16 v[236:239], v[20:23], v[52:55], v[236:239]
	v_add_u32_e32 v136, 0x60, v182
	v_med3_i32 v136, v136, 0, s38
	v_lshl_add_u32 v136, v136, 9, v179
	global_load_dwordx4 v[0:3], v136, s[24:25]
	global_load_dwordx4 v[4:7], v136, s[24:25] offset:64
	v_mul_f32_e32 v152, 0x3fb8aa3b, v152
	v_mul_f32_e32 v153, 0x3fb8aa3b, v153
	v_mul_f32_e32 v154, 0x3fb8aa3b, v154
	v_mul_f32_e32 v155, 0x3fb8aa3b, v155
	v_exp_f32_e32 v152, v152
	v_exp_f32_e32 v153, v153
	v_exp_f32_e32 v154, v154
	v_exp_f32_e32 v155, v155
	v_add_u32_e32 v138, 0, v175
	v_add_u32_e32 v139, 1, v175
	v_add_u32_e32 v140, 2, v175
	v_add_u32_e32 v141, 3, v175
	v_cmp_gt_u32_e64 s[70:71], s44, v138
	v_cmp_gt_u32_e64 s[72:73], s44, v139
	v_cmp_gt_u32_e64 s[74:75], s44, v140
	v_cmp_gt_u32_e64 s[76:77], s44, v141
	v_cndmask_b32_e64 v152, 0, v152, s[54:55]
	v_cndmask_b32_e64 v153, 0, v153, s[56:57]
	v_cndmask_b32_e64 v154, 0, v154, s[58:59]
	v_cndmask_b32_e64 v155, 0, v155, s[60:61]
	v_cndmask_b32_e64 v152, 0, v152, s[70:71]
	v_cndmask_b32_e64 v153, 0, v153, s[72:73]
	v_cndmask_b32_e64 v154, 0, v154, s[74:75]
	v_cndmask_b32_e64 v155, 0, v155, s[76:77]
	v_add_f32_e32 v132, v132, v152
	v_add_f32_e32 v132, v132, v153
	v_add_f32_e32 v132, v132, v154
	v_add_f32_e32 v132, v132, v155
	v_cvt_pk_bf16_f32 v112, v152, v153
	v_cvt_pk_bf16_f32 v113, v154, v155
	v_min_f32_e32 v152, 0x42a00000, v240
	v_min_f32_e32 v153, 0x42a00000, v241
	v_min_f32_e32 v154, 0x42a00000, v242
	v_min_f32_e32 v155, 0x42a00000, v243
	v_mfma_f32_16x16x32_bf16 v[240:243], v[24:27], v[48:51], 0
	v_mfma_f32_16x16x32_bf16 v[240:243], v[28:31], v[52:55], v[240:243]
	v_add_u32_e32 v135, 0x70, v182
	v_med3_i32 v135, v135, 0, s38
	v_lshl_add_u32 v135, v135, 9, v179
	global_load_dwordx4 v[8:11], v135, s[24:25]
	global_load_dwordx4 v[12:15], v135, s[24:25] offset:64
	v_mul_f32_e32 v152, 0x3fb8aa3b, v152
	v_mul_f32_e32 v153, 0x3fb8aa3b, v153
	v_mul_f32_e32 v154, 0x3fb8aa3b, v154
	v_mul_f32_e32 v155, 0x3fb8aa3b, v155
	v_exp_f32_e32 v152, v152
	v_exp_f32_e32 v153, v153
	v_exp_f32_e32 v154, v154
	v_exp_f32_e32 v155, v155
	v_add_u32_e32 v138, 16, v175
	v_add_u32_e32 v139, 17, v175
	v_add_u32_e32 v140, 18, v175
	v_add_u32_e32 v141, 19, v175
	v_cmp_gt_u32_e64 s[70:71], s44, v138
	v_cmp_gt_u32_e64 s[72:73], s44, v139
	v_cmp_gt_u32_e64 s[74:75], s44, v140
	v_cmp_gt_u32_e64 s[76:77], s44, v141
	v_cndmask_b32_e64 v152, 0, v152, s[70:71]
	v_cndmask_b32_e64 v153, 0, v153, s[72:73]
	v_cndmask_b32_e64 v154, 0, v154, s[74:75]
	v_cndmask_b32_e64 v155, 0, v155, s[76:77]
	v_add_f32_e32 v132, v132, v152
	v_add_f32_e32 v132, v132, v153
	v_add_f32_e32 v132, v132, v154
	v_add_f32_e32 v132, v132, v155
	v_cvt_pk_bf16_f32 v114, v152, v153
	v_cvt_pk_bf16_f32 v115, v154, v155
	v_min_f32_e32 v152, 0x42a00000, v236
	v_min_f32_e32 v153, 0x42a00000, v237
	v_min_f32_e32 v154, 0x42a00000, v238
	v_min_f32_e32 v155, 0x42a00000, v239
	v_mfma_f32_16x16x32_bf16 v[236:239], v[32:35], v[48:51], 0
	v_mfma_f32_16x16x32_bf16 v[236:239], v[36:39], v[52:55], v[236:239]
	v_add_u32_e32 v136, 0x80, v182
	v_med3_i32 v136, v136, 0, s38
	v_lshl_add_u32 v136, v136, 9, v179
	global_load_dwordx4 v[16:19], v136, s[24:25]
	global_load_dwordx4 v[20:23], v136, s[24:25] offset:64
	v_mul_f32_e32 v152, 0x3fb8aa3b, v152
	v_mul_f32_e32 v153, 0x3fb8aa3b, v153
	v_mul_f32_e32 v154, 0x3fb8aa3b, v154
	v_mul_f32_e32 v155, 0x3fb8aa3b, v155
	v_exp_f32_e32 v152, v152
	v_exp_f32_e32 v153, v153
	v_exp_f32_e32 v154, v154
	v_exp_f32_e32 v155, v155
	v_add_u32_e32 v138, 32, v175
	v_add_u32_e32 v139, 33, v175
	v_add_u32_e32 v140, 34, v175
	v_add_u32_e32 v141, 35, v175
	v_cmp_gt_u32_e64 s[70:71], s44, v138
	v_cmp_gt_u32_e64 s[72:73], s44, v139
	v_cmp_gt_u32_e64 s[74:75], s44, v140
	v_cmp_gt_u32_e64 s[76:77], s44, v141
	v_cndmask_b32_e64 v152, 0, v152, s[70:71]
	v_cndmask_b32_e64 v153, 0, v153, s[72:73]
	v_cndmask_b32_e64 v154, 0, v154, s[74:75]
	v_cndmask_b32_e64 v155, 0, v155, s[76:77]
	v_add_f32_e32 v132, v132, v152
	v_add_f32_e32 v132, v132, v153
	v_add_f32_e32 v132, v132, v154
	v_add_f32_e32 v132, v132, v155
	v_cvt_pk_bf16_f32 v116, v152, v153
	v_cvt_pk_bf16_f32 v117, v154, v155
	v_min_f32_e32 v152, 0x42a00000, v240
	v_min_f32_e32 v153, 0x42a00000, v241
	v_min_f32_e32 v154, 0x42a00000, v242
	v_min_f32_e32 v155, 0x42a00000, v243
	v_mfma_f32_16x16x32_bf16 v[240:243], v[40:43], v[48:51], 0
	v_mfma_f32_16x16x32_bf16 v[240:243], v[44:47], v[52:55], v[240:243]
	v_mul_f32_e32 v152, 0x3fb8aa3b, v152
	v_mul_f32_e32 v153, 0x3fb8aa3b, v153
	v_mul_f32_e32 v154, 0x3fb8aa3b, v154
	v_mul_f32_e32 v155, 0x3fb8aa3b, v155
	v_exp_f32_e32 v152, v152
	v_exp_f32_e32 v153, v153
	v_exp_f32_e32 v154, v154
	v_exp_f32_e32 v155, v155
	v_add_u32_e32 v138, 48, v175
	v_add_u32_e32 v139, 49, v175
	v_add_u32_e32 v140, 50, v175
	v_add_u32_e32 v141, 51, v175
	v_cmp_gt_u32_e64 s[70:71], s44, v138
	v_cmp_gt_u32_e64 s[72:73], s44, v139
	v_cmp_gt_u32_e64 s[74:75], s44, v140
	v_cmp_gt_u32_e64 s[76:77], s44, v141
	v_cndmask_b32_e64 v152, 0, v152, s[70:71]
	v_cndmask_b32_e64 v153, 0, v153, s[72:73]
	v_cndmask_b32_e64 v154, 0, v154, s[74:75]
	v_cndmask_b32_e64 v155, 0, v155, s[76:77]
	v_add_f32_e32 v132, v132, v152
	v_add_f32_e32 v132, v132, v153
	v_add_f32_e32 v132, v132, v154
	v_add_f32_e32 v132, v132, v155
	v_cvt_pk_bf16_f32 v118, v152, v153
	v_cvt_pk_bf16_f32 v119, v154, v155
	v_min_f32_e32 v152, 0x42a00000, v236
	v_min_f32_e32 v153, 0x42a00000, v237
	v_min_f32_e32 v154, 0x42a00000, v238
	v_min_f32_e32 v155, 0x42a00000, v239
	s_waitcnt vmcnt(4)
	v_mfma_f32_16x16x32_bf16 v[236:239], v[0:3], v[48:51], 0
	v_mfma_f32_16x16x32_bf16 v[236:239], v[4:7], v[52:55], v[236:239]
	v_mul_f32_e32 v152, 0x3fb8aa3b, v152
	v_mul_f32_e32 v153, 0x3fb8aa3b, v153
	v_mul_f32_e32 v154, 0x3fb8aa3b, v154
	v_mul_f32_e32 v155, 0x3fb8aa3b, v155
	v_exp_f32_e32 v152, v152
	v_exp_f32_e32 v153, v153
	v_exp_f32_e32 v154, v154
	v_exp_f32_e32 v155, v155
	v_add_u32_e32 v138, 64, v175
	v_add_u32_e32 v139, 0x41, v175
	v_add_u32_e32 v140, 0x42, v175
	v_add_u32_e32 v141, 0x43, v175
	v_cmp_gt_u32_e64 s[70:71], s44, v138
	v_cmp_gt_u32_e64 s[72:73], s44, v139
	v_cmp_gt_u32_e64 s[74:75], s44, v140
	v_cmp_gt_u32_e64 s[76:77], s44, v141
	v_cndmask_b32_e64 v152, 0, v152, s[70:71]
	v_cndmask_b32_e64 v153, 0, v153, s[72:73]
	v_cndmask_b32_e64 v154, 0, v154, s[74:75]
	v_cndmask_b32_e64 v155, 0, v155, s[76:77]
	v_add_f32_e32 v132, v132, v152
	v_add_f32_e32 v132, v132, v153
	v_add_f32_e32 v132, v132, v154
	v_add_f32_e32 v132, v132, v155
	v_cvt_pk_bf16_f32 v120, v152, v153
	v_cvt_pk_bf16_f32 v121, v154, v155
	v_min_f32_e32 v152, 0x42a00000, v240
	v_min_f32_e32 v153, 0x42a00000, v241
	v_min_f32_e32 v154, 0x42a00000, v242
	v_min_f32_e32 v155, 0x42a00000, v243
	s_waitcnt vmcnt(2)
	v_mfma_f32_16x16x32_bf16 v[240:243], v[8:11], v[48:51], 0
	v_mfma_f32_16x16x32_bf16 v[240:243], v[12:15], v[52:55], v[240:243]
	v_mul_f32_e32 v152, 0x3fb8aa3b, v152
	v_mul_f32_e32 v153, 0x3fb8aa3b, v153
	v_mul_f32_e32 v154, 0x3fb8aa3b, v154
	v_mul_f32_e32 v155, 0x3fb8aa3b, v155
	v_exp_f32_e32 v152, v152
	v_exp_f32_e32 v153, v153
	v_exp_f32_e32 v154, v154
	v_exp_f32_e32 v155, v155
	v_add_u32_e32 v138, 0x50, v175
	v_add_u32_e32 v139, 0x51, v175
	v_add_u32_e32 v140, 0x52, v175
	v_add_u32_e32 v141, 0x53, v175
	v_cmp_gt_u32_e64 s[70:71], s44, v138
	v_cmp_gt_u32_e64 s[72:73], s44, v139
	v_cmp_gt_u32_e64 s[74:75], s44, v140
	v_cmp_gt_u32_e64 s[76:77], s44, v141
	v_cndmask_b32_e64 v152, 0, v152, s[70:71]
	v_cndmask_b32_e64 v153, 0, v153, s[72:73]
	v_cndmask_b32_e64 v154, 0, v154, s[74:75]
	v_cndmask_b32_e64 v155, 0, v155, s[76:77]
	v_add_f32_e32 v132, v132, v152
	v_add_f32_e32 v132, v132, v153
	v_add_f32_e32 v132, v132, v154
	v_add_f32_e32 v132, v132, v155
	v_cvt_pk_bf16_f32 v122, v152, v153
	v_cvt_pk_bf16_f32 v123, v154, v155
	v_min_f32_e32 v152, 0x42a00000, v236
	v_min_f32_e32 v153, 0x42a00000, v237
	v_min_f32_e32 v154, 0x42a00000, v238
	v_min_f32_e32 v155, 0x42a00000, v239
	s_waitcnt vmcnt(0)
	v_mfma_f32_16x16x32_bf16 v[236:239], v[16:19], v[48:51], 0
	v_mfma_f32_16x16x32_bf16 v[236:239], v[20:23], v[52:55], v[236:239]
	v_mul_f32_e32 v152, 0x3fb8aa3b, v152
	v_mul_f32_e32 v153, 0x3fb8aa3b, v153
	v_mul_f32_e32 v154, 0x3fb8aa3b, v154
	v_mul_f32_e32 v155, 0x3fb8aa3b, v155
	v_exp_f32_e32 v152, v152
	v_exp_f32_e32 v153, v153
	v_exp_f32_e32 v154, v154
	v_exp_f32_e32 v155, v155
	v_add_u32_e32 v138, 0x60, v175
	v_add_u32_e32 v139, 0x61, v175
	v_add_u32_e32 v140, 0x62, v175
	v_add_u32_e32 v141, 0x63, v175
	v_cmp_gt_u32_e64 s[70:71], s44, v138
	v_cmp_gt_u32_e64 s[72:73], s44, v139
	v_cmp_gt_u32_e64 s[74:75], s44, v140
	v_cmp_gt_u32_e64 s[76:77], s44, v141
	v_cndmask_b32_e64 v152, 0, v152, s[70:71]
	v_cndmask_b32_e64 v153, 0, v153, s[72:73]
	v_cndmask_b32_e64 v154, 0, v154, s[74:75]
	v_cndmask_b32_e64 v155, 0, v155, s[76:77]
	v_add_f32_e32 v132, v132, v152
	v_add_f32_e32 v132, v132, v153
	v_add_f32_e32 v132, v132, v154
	v_add_f32_e32 v132, v132, v155
	v_cvt_pk_bf16_f32 v124, v152, v153
	v_cvt_pk_bf16_f32 v125, v154, v155
	v_min_f32_e32 v152, 0x42a00000, v240
	v_min_f32_e32 v153, 0x42a00000, v241
	v_min_f32_e32 v154, 0x42a00000, v242
	v_min_f32_e32 v155, 0x42a00000, v243
	v_mul_f32_e32 v152, 0x3fb8aa3b, v152
	v_mul_f32_e32 v153, 0x3fb8aa3b, v153
	v_mul_f32_e32 v154, 0x3fb8aa3b, v154
	v_mul_f32_e32 v155, 0x3fb8aa3b, v155
	v_exp_f32_e32 v152, v152
	v_exp_f32_e32 v153, v153
	v_exp_f32_e32 v154, v154
	v_exp_f32_e32 v155, v155
	v_add_u32_e32 v138, 0x70, v175
	v_add_u32_e32 v139, 0x71, v175
	v_add_u32_e32 v140, 0x72, v175
	v_add_u32_e32 v141, 0x73, v175
	v_cmp_gt_u32_e64 s[70:71], s44, v138
	v_cmp_gt_u32_e64 s[72:73], s44, v139
	v_cmp_gt_u32_e64 s[74:75], s44, v140
	v_cmp_gt_u32_e64 s[76:77], s44, v141
	v_cndmask_b32_e64 v152, 0, v152, s[70:71]
	v_cndmask_b32_e64 v153, 0, v153, s[72:73]
	v_cndmask_b32_e64 v154, 0, v154, s[74:75]
	v_cndmask_b32_e64 v155, 0, v155, s[76:77]
	v_add_f32_e32 v132, v132, v152
	v_add_f32_e32 v132, v132, v153
	v_add_f32_e32 v132, v132, v154
	v_add_f32_e32 v132, v132, v155
	v_cvt_pk_bf16_f32 v126, v152, v153
	v_cvt_pk_bf16_f32 v127, v154, v155
	v_min_f32_e32 v152, 0x42a00000, v236
	v_min_f32_e32 v153, 0x42a00000, v237
	v_min_f32_e32 v154, 0x42a00000, v238
	v_min_f32_e32 v155, 0x42a00000, v239
	v_mul_f32_e32 v152, 0x3fb8aa3b, v152
	v_mul_f32_e32 v153, 0x3fb8aa3b, v153
	v_mul_f32_e32 v154, 0x3fb8aa3b, v154
	v_mul_f32_e32 v155, 0x3fb8aa3b, v155
	v_exp_f32_e32 v152, v152
	v_exp_f32_e32 v153, v153
	v_exp_f32_e32 v154, v154
	v_exp_f32_e32 v155, v155
	v_add_u32_e32 v138, 0x80, v175
	v_add_u32_e32 v139, 0x81, v175
	v_add_u32_e32 v140, 0x82, v175
	v_add_u32_e32 v141, 0x83, v175
	v_cmp_gt_u32_e64 s[70:71], s44, v138
	v_cmp_gt_u32_e64 s[72:73], s44, v139
	v_cmp_gt_u32_e64 s[74:75], s44, v140
	v_cmp_gt_u32_e64 s[76:77], s44, v141
	v_cndmask_b32_e64 v152, 0, v152, s[62:63]
	v_cndmask_b32_e64 v153, 0, v153, s[64:65]
	v_cndmask_b32_e64 v154, 0, v154, s[66:67]
	v_cndmask_b32_e64 v155, 0, v155, s[68:69]
	v_cndmask_b32_e64 v152, 0, v152, s[70:71]
	v_cndmask_b32_e64 v153, 0, v153, s[72:73]
	v_cndmask_b32_e64 v154, 0, v154, s[74:75]
	v_cndmask_b32_e64 v155, 0, v155, s[76:77]
	v_add_f32_e32 v132, v132, v152
	v_add_f32_e32 v132, v132, v153
	v_add_f32_e32 v132, v132, v154
	v_add_f32_e32 v132, v132, v155
	v_cvt_pk_bf16_f32 v128, v152, v153
	v_cvt_pk_bf16_f32 v129, v154, v155
	v_add_u32_e32 v134, s42, v160
	v_lshlrev_b32_e32 v134, 4, v134
	v_add_u32_e32 v134, s43, v134
	v_subrev_u32_e32 v135, s15, v134
	v_lshrrev_b32_e32 v136, 4, v135
	v_add_u32_e32 v136, v136, v135
	v_mad_u32_u24 v176, v136, s79, v161
	v_lshl_add_u32 v177, v135, 2, s80
	s_sub_i32 s2, s42, 64
	v_add_u32_e32 v178, s2, v169
	v_and_b32_e32 v135, 3, v134
	v_lshlrev_b32_e32 v135, s13, v135
	v_lshrrev_b32_e32 v136, 2, v134
	v_add_u32_e32 v135, v135, v136
	v_lshl_add_u32 v135, v135, 7, v161
	global_load_dwordx4 v[48:51], v135, s[18:19] nt
	global_load_dwordx4 v[52:55], v135, s[18:19] offset:64 nt
	v_subrev_u32_e32 v134, 0x400, v134
	v_and_b32_e32 v137, 3, v134
	v_lshlrev_b32_e32 v137, s13, v137
	v_bfe_u32 v135, v134, 2, 2
	v_add_u32_e32 v137, v137, v135
	v_lshl_add_u32 v183, v137, 7, v161
	v_ashrrev_i32_e32 v252, 4, v134
	v_med3_i32 v136, v252, 0, s14
	v_lshl_add_u32 v136, v136, 9, v183
	global_load_dwordx4 v[0:3], v136, s[20:21]
	global_load_dwordx4 v[4:7], v136, s[20:21] offset:64
	v_add_u32_e32 v135, 16, v252
	v_med3_i32 v135, v135, 0, s14
	v_lshl_add_u32 v135, v135, 9, v183
	global_load_dwordx4 v[8:11], v135, s[20:21]
	global_load_dwordx4 v[12:15], v135, s[20:21] offset:64
	v_add_u32_e32 v136, 32, v252
	v_med3_i32 v136, v136, 0, s14
	v_lshl_add_u32 v136, v136, 9, v183
	global_load_dwordx4 v[16:19], v136, s[20:21]
	global_load_dwordx4 v[20:23], v136, s[20:21] offset:64
	v_add_u32_e32 v135, 48, v252
	v_med3_i32 v135, v135, 0, s14
	v_lshl_add_u32 v135, v135, 9, v183
	global_load_dwordx4 v[24:27], v135, s[20:21]
	global_load_dwordx4 v[28:31], v135, s[20:21] offset:64
	v_add_u32_e32 v136, 64, v252
	v_med3_i32 v136, v136, 0, s14
	v_lshl_add_u32 v136, v136, 9, v183
	global_load_dwordx4 v[32:35], v136, s[20:21]
	global_load_dwordx4 v[36:39], v136, s[20:21] offset:64
	v_add_u32_e32 v135, 0x50, v252
	v_med3_i32 v135, v135, 0, s14
	v_lshl_add_u32 v135, v135, 9, v183
	global_load_dwordx4 v[40:43], v135, s[20:21]
	global_load_dwordx4 v[44:47], v135, s[20:21] offset:64
	ds_bpermute_b32 v142, v167, v132
	s_waitcnt lgkmcnt(0)
	v_add_f32_e32 v132, v132, v142
	ds_bpermute_b32 v142, v168, v132
	s_waitcnt lgkmcnt(0)
	v_add_f32_e32 v132, v132, v142
	s_waitcnt vmcnt(14)
	ds_write_b128 v165, v[64:67]
	ds_write_b128 v165, v[68:71] offset:1152
	ds_write_b128 v165, v[72:75] offset:2304
	ds_write_b128 v165, v[76:79] offset:3456
	s_waitcnt lgkmcnt(0)
	ds_read_b64_tr_b16 v[236:237], v166
	ds_read_b64_tr_b16 v[238:239], v166 offset:2304
	ds_read_b64_tr_b16 v[240:241], v166 offset:32
	ds_read_b64_tr_b16 v[242:243], v166 offset:2336
	ds_read_b64_tr_b16 v[244:245], v166 offset:64
	ds_read_b64_tr_b16 v[246:247], v166 offset:2368
	ds_read_b64_tr_b16 v[248:249], v166 offset:96
	ds_read_b64_tr_b16 v[250:251], v166 offset:2400
	s_waitcnt lgkmcnt(0)
	s_add_i32 s2, s40, 32
	v_add_u32_e32 v138, s2, v164
	v_lshlrev_b32_e32 v138, 4, v138
	v_add_u32_e32 v138, s41, v138
	v_and_b32_e32 v139, 3, v138
	v_lshlrev_b32_e32 v139, s39, v139
	v_bfe_u32 v140, v138, 2, 2
	v_add_u32_e32 v139, v139, v140
	v_lshl_add_u32 v139, v139, 7, v162
	v_ashrrev_i32_e32 v138, 4, v138
	v_med3_i32 v138, v138, 0, s38
	v_lshl_add_u32 v138, v138, 9, v139
	global_load_dwordx4 v[64:67], v138, s[26:27]
	s_add_i32 s2, s40, 40
	v_add_u32_e32 v138, s2, v164
	v_lshlrev_b32_e32 v138, 4, v138
	v_add_u32_e32 v138, s41, v138
	v_and_b32_e32 v139, 3, v138
	v_lshlrev_b32_e32 v139, s39, v139
	v_bfe_u32 v140, v138, 2, 2
	v_add_u32_e32 v139, v139, v140
	v_lshl_add_u32 v139, v139, 7, v162
	v_ashrrev_i32_e32 v138, 4, v138
	v_med3_i32 v138, v138, 0, s38
	v_lshl_add_u32 v138, v138, 9, v139
	global_load_dwordx4 v[68:71], v138, s[26:27]
	s_add_i32 s2, s40, 48
	v_add_u32_e32 v138, s2, v164
	v_lshlrev_b32_e32 v138, 4, v138
	v_add_u32_e32 v138, s41, v138
	v_and_b32_e32 v139, 3, v138
	v_lshlrev_b32_e32 v139, s39, v139
	v_bfe_u32 v140, v138, 2, 2
	v_add_u32_e32 v139, v139, v140
	v_lshl_add_u32 v139, v139, 7, v162
	v_ashrrev_i32_e32 v138, 4, v138
	v_med3_i32 v138, v138, 0, s38
	v_lshl_add_u32 v138, v138, 9, v139
	global_load_dwordx4 v[72:75], v138, s[26:27]
	s_add_i32 s2, s40, 56
	v_add_u32_e32 v138, s2, v164
	v_lshlrev_b32_e32 v138, 4, v138
	v_add_u32_e32 v138, s41, v138
	v_and_b32_e32 v139, 3, v138
	v_lshlrev_b32_e32 v139, s39, v139
	v_bfe_u32 v140, v138, 2, 2
	v_add_u32_e32 v139, v139, v140
	v_lshl_add_u32 v139, v139, 7, v162
	v_ashrrev_i32_e32 v138, 4, v138
	v_med3_i32 v138, v138, 0, s38
	v_lshl_add_u32 v138, v138, 9, v139
	global_load_dwordx4 v[76:79], v138, s[26:27]
	ds_write_b128 v165, v[80:83]
	ds_write_b128 v165, v[84:87] offset:1152
	ds_write_b128 v165, v[88:91] offset:2304
	ds_write_b128 v165, v[92:95] offset:3456
	v_mfma_f32_16x16x32_bf16 v[204:207], v[236:239], v[112:115], 0
	v_mfma_f32_16x16x32_bf16 v[208:211], v[240:243], v[112:115], 0
	v_mfma_f32_16x16x32_bf16 v[212:215], v[244:247], v[112:115], 0
	v_mfma_f32_16x16x32_bf16 v[216:219], v[248:251], v[112:115], 0
	s_waitcnt lgkmcnt(0)
	ds_read_b64_tr_b16 v[236:237], v166
	ds_read_b64_tr_b16 v[238:239], v166 offset:2304
	ds_read_b64_tr_b16 v[240:241], v166 offset:32
	ds_read_b64_tr_b16 v[242:243], v166 offset:2336
	ds_read_b64_tr_b16 v[244:245], v166 offset:64
	ds_read_b64_tr_b16 v[246:247], v166 offset:2368
	ds_read_b64_tr_b16 v[248:249], v166 offset:96
	ds_read_b64_tr_b16 v[250:251], v166 offset:2400
	s_waitcnt lgkmcnt(0)
	s_add_i32 s2, s40, 64
	v_add_u32_e32 v138, s2, v164
	v_lshlrev_b32_e32 v138, 4, v138
	v_add_u32_e32 v138, s41, v138
	v_and_b32_e32 v139, 3, v138
	v_lshlrev_b32_e32 v139, s39, v139
	v_bfe_u32 v140, v138, 2, 2
	v_add_u32_e32 v139, v139, v140
	v_lshl_add_u32 v139, v139, 7, v162
	v_ashrrev_i32_e32 v138, 4, v138
	v_med3_i32 v138, v138, 0, s38
	v_lshl_add_u32 v138, v138, 9, v139
	global_load_dwordx4 v[80:83], v138, s[26:27]
	s_add_i32 s2, s40, 72
	v_add_u32_e32 v138, s2, v164
	v_lshlrev_b32_e32 v138, 4, v138
	v_add_u32_e32 v138, s41, v138
	v_and_b32_e32 v139, 3, v138
	v_lshlrev_b32_e32 v139, s39, v139
	v_bfe_u32 v140, v138, 2, 2
	v_add_u32_e32 v139, v139, v140
	v_lshl_add_u32 v139, v139, 7, v162
	v_ashrrev_i32_e32 v138, 4, v138
	v_med3_i32 v138, v138, 0, s38
	v_lshl_add_u32 v138, v138, 9, v139
	global_load_dwordx4 v[84:87], v138, s[26:27]
	ds_write_b128 v165, v[96:99]
	ds_write_b128 v165, v[100:103] offset:1152
	ds_write_b128 v165, v[104:107] offset:2304
	ds_write_b128 v165, v[108:111] offset:3456
	v_mfma_f32_16x16x32_bf16 v[204:207], v[236:239], v[116:119], v[204:207]
	v_mfma_f32_16x16x32_bf16 v[208:211], v[240:243], v[116:119], v[208:211]
	v_mfma_f32_16x16x32_bf16 v[212:215], v[244:247], v[116:119], v[212:215]
	v_mfma_f32_16x16x32_bf16 v[216:219], v[248:251], v[116:119], v[216:219]
	s_waitcnt lgkmcnt(0)
	ds_read_b64_tr_b16 v[236:237], v166
	ds_read_b64_tr_b16 v[238:239], v166 offset:2304
	ds_read_b64_tr_b16 v[240:241], v166 offset:32
	ds_read_b64_tr_b16 v[242:243], v166 offset:2336
	ds_read_b64_tr_b16 v[244:245], v166 offset:64
	ds_read_b64_tr_b16 v[246:247], v166 offset:2368
	ds_read_b64_tr_b16 v[248:249], v166 offset:96
	ds_read_b64_tr_b16 v[250:251], v166 offset:2400
	s_waitcnt lgkmcnt(0)
	s_waitcnt vmcnt(2)
	ds_write_b128 v165, v[64:67]
	ds_write_b128 v165, v[68:71] offset:1152
	ds_write_b128 v165, v[72:75] offset:2304
	ds_write_b128 v165, v[76:79] offset:3456
	v_mfma_f32_16x16x32_bf16 v[204:207], v[236:239], v[120:123], v[204:207]
	v_mfma_f32_16x16x32_bf16 v[208:211], v[240:243], v[120:123], v[208:211]
	v_mfma_f32_16x16x32_bf16 v[212:215], v[244:247], v[120:123], v[212:215]
	v_mfma_f32_16x16x32_bf16 v[216:219], v[248:251], v[120:123], v[216:219]
	s_waitcnt lgkmcnt(0)
	ds_read_b64_tr_b16 v[236:237], v166
	ds_read_b64_tr_b16 v[238:239], v166 offset:2304
	ds_read_b64_tr_b16 v[240:241], v166 offset:32
	ds_read_b64_tr_b16 v[242:243], v166 offset:2336
	ds_read_b64_tr_b16 v[244:245], v166 offset:64
	ds_read_b64_tr_b16 v[246:247], v166 offset:2368
	ds_read_b64_tr_b16 v[248:249], v166 offset:96
	ds_read_b64_tr_b16 v[250:251], v166 offset:2400
	s_waitcnt lgkmcnt(0)
	s_waitcnt vmcnt(0)
	ds_write_b128 v165, v[80:83]
	ds_write_b128 v165, v[84:87] offset:1152
	v_mfma_f32_16x16x32_bf16 v[204:207], v[236:239], v[124:127], v[204:207]
	v_mfma_f32_16x16x32_bf16 v[208:211], v[240:243], v[124:127], v[208:211]
	v_mfma_f32_16x16x32_bf16 v[212:215], v[244:247], v[124:127], v[212:215]
	v_mfma_f32_16x16x32_bf16 v[216:219], v[248:251], v[124:127], v[216:219]
	s_waitcnt lgkmcnt(0)
	ds_read_b64_tr_b16 v[236:237], v166
	ds_read_b64_tr_b16 v[238:239], v166 offset:2304
	ds_read_b64_tr_b16 v[240:241], v166 offset:32
	ds_read_b64_tr_b16 v[242:243], v166 offset:2336
	ds_read_b64_tr_b16 v[244:245], v166 offset:64
	ds_read_b64_tr_b16 v[246:247], v166 offset:2368
	ds_read_b64_tr_b16 v[248:249], v166 offset:96
	ds_read_b64_tr_b16 v[250:251], v166 offset:2400
	s_waitcnt lgkmcnt(0)
	v_mfma_f32_16x16x32_bf16 v[204:207], v[236:239], v[128:131], v[204:207]
	v_mfma_f32_16x16x32_bf16 v[208:211], v[240:243], v[128:131], v[208:211]
	v_mfma_f32_16x16x32_bf16 v[212:215], v[244:247], v[128:131], v[212:215]
	v_mfma_f32_16x16x32_bf16 v[216:219], v[248:251], v[128:131], v[216:219]
	s_add_i32 s2, s42, -64
	v_add_u32_e32 v138, s2, v164
	v_lshlrev_b32_e32 v138, 4, v138
	v_add_u32_e32 v138, s43, v138
	v_and_b32_e32 v139, 3, v138
	v_lshlrev_b32_e32 v139, s13, v139
	v_bfe_u32 v140, v138, 2, 2
	v_add_u32_e32 v139, v139, v140
	v_lshl_add_u32 v139, v139, 7, v162
	v_ashrrev_i32_e32 v138, 4, v138
	v_med3_i32 v138, v138, 0, s14
	v_lshl_add_u32 v138, v138, 9, v139
	global_load_dwordx4 v[64:67], v138, s[22:23]
	s_add_i32 s2, s42, -56
	v_add_u32_e32 v138, s2, v164
	v_lshlrev_b32_e32 v138, 4, v138
	v_add_u32_e32 v138, s43, v138
	v_and_b32_e32 v139, 3, v138
	v_lshlrev_b32_e32 v139, s13, v139
	v_bfe_u32 v140, v138, 2, 2
	v_add_u32_e32 v139, v139, v140
	v_lshl_add_u32 v139, v139, 7, v162
	v_ashrrev_i32_e32 v138, 4, v138
	v_med3_i32 v138, v138, 0, s14
	v_lshl_add_u32 v138, v138, 9, v139
	global_load_dwordx4 v[68:71], v138, s[22:23]
	s_add_i32 s2, s42, -48
	v_add_u32_e32 v138, s2, v164
	v_lshlrev_b32_e32 v138, 4, v138
	v_add_u32_e32 v138, s43, v138
	v_and_b32_e32 v139, 3, v138
	v_lshlrev_b32_e32 v139, s13, v139
	v_bfe_u32 v140, v138, 2, 2
	v_add_u32_e32 v139, v139, v140
	v_lshl_add_u32 v139, v139, 7, v162
	v_ashrrev_i32_e32 v138, 4, v138
	v_med3_i32 v138, v138, 0, s14
	v_lshl_add_u32 v138, v138, 9, v139
	global_load_dwordx4 v[72:75], v138, s[22:23]
	s_add_i32 s2, s42, -40
	v_add_u32_e32 v138, s2, v164
	v_lshlrev_b32_e32 v138, 4, v138
	v_add_u32_e32 v138, s43, v138
	v_and_b32_e32 v139, 3, v138
	v_lshlrev_b32_e32 v139, s13, v139
	v_bfe_u32 v140, v138, 2, 2
	v_add_u32_e32 v139, v139, v140
	v_lshl_add_u32 v139, v139, 7, v162
	v_ashrrev_i32_e32 v138, 4, v138
	v_med3_i32 v138, v138, 0, s14
	v_lshl_add_u32 v138, v138, 9, v139
	global_load_dwordx4 v[76:79], v138, s[22:23]
	s_add_i32 s2, s42, -32
	v_add_u32_e32 v138, s2, v164
	v_lshlrev_b32_e32 v138, 4, v138
	v_add_u32_e32 v138, s43, v138
	v_and_b32_e32 v139, 3, v138
	v_lshlrev_b32_e32 v139, s13, v139
	v_bfe_u32 v140, v138, 2, 2
	v_add_u32_e32 v139, v139, v140
	v_lshl_add_u32 v139, v139, 7, v162
	v_ashrrev_i32_e32 v138, 4, v138
	v_med3_i32 v138, v138, 0, s14
	v_lshl_add_u32 v138, v138, 9, v139
	global_load_dwordx4 v[80:83], v138, s[22:23]
	s_add_i32 s2, s42, -24
	v_add_u32_e32 v138, s2, v164
	v_lshlrev_b32_e32 v138, 4, v138
	v_add_u32_e32 v138, s43, v138
	v_and_b32_e32 v139, 3, v138
	v_lshlrev_b32_e32 v139, s13, v139
	v_bfe_u32 v140, v138, 2, 2
	v_add_u32_e32 v139, v139, v140
	v_lshl_add_u32 v139, v139, 7, v162
	v_ashrrev_i32_e32 v138, 4, v138
	v_med3_i32 v138, v138, 0, s14
	v_lshl_add_u32 v138, v138, 9, v139
	global_load_dwordx4 v[84:87], v138, s[22:23]
	s_add_i32 s2, s42, -16
	v_add_u32_e32 v138, s2, v164
	v_lshlrev_b32_e32 v138, 4, v138
	v_add_u32_e32 v138, s43, v138
	v_and_b32_e32 v139, 3, v138
	v_lshlrev_b32_e32 v139, s13, v139
	v_bfe_u32 v140, v138, 2, 2
	v_add_u32_e32 v139, v139, v140
	v_lshl_add_u32 v139, v139, 7, v162
	v_ashrrev_i32_e32 v138, 4, v138
	v_med3_i32 v138, v138, 0, s14
	v_lshl_add_u32 v138, v138, 9, v139
	global_load_dwordx4 v[88:91], v138, s[22:23]
	s_add_i32 s2, s42, -8
	v_add_u32_e32 v138, s2, v164
	v_lshlrev_b32_e32 v138, 4, v138
	v_add_u32_e32 v138, s43, v138
	v_and_b32_e32 v139, 3, v138
	v_lshlrev_b32_e32 v139, s13, v139
	v_bfe_u32 v140, v138, 2, 2
	v_add_u32_e32 v139, v139, v140
	v_lshl_add_u32 v139, v139, 7, v162
	v_ashrrev_i32_e32 v138, 4, v138
	v_med3_i32 v138, v138, 0, s14
	v_lshl_add_u32 v138, v138, 9, v139
	global_load_dwordx4 v[92:95], v138, s[22:23]
	s_add_i32 s2, s42, 0
	v_add_u32_e32 v138, s2, v164
	v_lshlrev_b32_e32 v138, 4, v138
	v_add_u32_e32 v138, s43, v138
	v_and_b32_e32 v139, 3, v138
	v_lshlrev_b32_e32 v139, s13, v139
	v_bfe_u32 v140, v138, 2, 2
	v_add_u32_e32 v139, v139, v140
	v_lshl_add_u32 v139, v139, 7, v162
	v_ashrrev_i32_e32 v138, 4, v138
	v_med3_i32 v138, v138, 0, s14
	v_lshl_add_u32 v138, v138, 9, v139
	global_load_dwordx4 v[96:99], v138, s[22:23]
	s_add_i32 s2, s42, 8
	v_add_u32_e32 v138, s2, v164
	v_lshlrev_b32_e32 v138, 4, v138
	v_add_u32_e32 v138, s43, v138
	v_and_b32_e32 v139, 3, v138
	v_lshlrev_b32_e32 v139, s13, v139
	v_bfe_u32 v140, v138, 2, 2
	v_add_u32_e32 v139, v139, v140
	v_lshl_add_u32 v139, v139, 7, v162
	v_ashrrev_i32_e32 v138, 4, v138
	v_med3_i32 v138, v138, 0, s14
	v_lshl_add_u32 v138, v138, 9, v139
	global_load_dwordx4 v[100:103], v138, s[22:23]
	s_add_i32 s2, s42, 16
	v_add_u32_e32 v138, s2, v164
	v_lshlrev_b32_e32 v138, 4, v138
	v_add_u32_e32 v138, s43, v138
	v_and_b32_e32 v139, 3, v138
	v_lshlrev_b32_e32 v139, s13, v139
	v_bfe_u32 v140, v138, 2, 2
	v_add_u32_e32 v139, v139, v140
	v_lshl_add_u32 v139, v139, 7, v162
	v_ashrrev_i32_e32 v138, 4, v138
	v_med3_i32 v138, v138, 0, s14
	v_lshl_add_u32 v138, v138, 9, v139
	global_load_dwordx4 v[104:107], v138, s[22:23]
	s_add_i32 s2, s42, 24
	v_add_u32_e32 v138, s2, v164
	v_lshlrev_b32_e32 v138, 4, v138
	v_add_u32_e32 v138, s43, v138
	v_and_b32_e32 v139, 3, v138
	v_lshlrev_b32_e32 v139, s13, v139
	v_bfe_u32 v140, v138, 2, 2
	v_add_u32_e32 v139, v139, v140
	v_lshl_add_u32 v139, v139, 7, v162
	v_ashrrev_i32_e32 v138, 4, v138
	v_med3_i32 v138, v138, 0, s14
	v_lshl_add_u32 v138, v138, 9, v139
	global_load_dwordx4 v[108:111], v138, s[22:23]
	ds_read_b128 v[236:239], v173 offset:0
	ds_read_b128 v[240:243], v173 offset:64
	ds_read_b128 v[244:247], v173 offset:128
	ds_read_b128 v[248:251], v173 offset:192
	ds_read_b32 v142, v174 offset:0
	s_waitcnt lgkmcnt(0)
	v_add_f32_e32 v204, v236, v204
	v_add_f32_e32 v205, v237, v205
	v_add_f32_e32 v206, v238, v206
	v_add_f32_e32 v207, v239, v207
	v_add_f32_e32 v208, v240, v208
	v_add_f32_e32 v209, v241, v209
	v_add_f32_e32 v210, v242, v210
	v_add_f32_e32 v211, v243, v211
	v_add_f32_e32 v212, v244, v212
	v_add_f32_e32 v213, v245, v213
	v_add_f32_e32 v214, v246, v214
	v_add_f32_e32 v215, v247, v215
	v_add_f32_e32 v216, v248, v216
	v_add_f32_e32 v217, v249, v217
	v_add_f32_e32 v218, v250, v218
	v_add_f32_e32 v219, v251, v219
	v_add_f32_e32 v132, v142, v132
	ds_write_b128 v173, v[204:207] offset:0
	ds_write_b128 v173, v[208:211] offset:64
	ds_write_b128 v173, v[212:215] offset:128
	ds_write_b128 v173, v[216:219] offset:192
	ds_write_b32 v174, v132 offset:0
	s_mov_b32 s40, s42
	s_mov_b32 s41, s43
	v_mov_b32_e32 v173, v176
	v_mov_b32_e32 v174, v177
	v_mov_b32_e32 v175, v178
	v_mov_b32_e32 v179, v183
	v_mov_b32_e32 v182, v252
	s_lshr_b32 s44, s33, 4
	s_add_i32 s45, s10, s8
	s_cmp_lt_u32 s45, 0x800
	s_cbranch_scc1 .Latt_newunit
	s_mov_b32 s37, 1
	s_branch .Latt_ud_done

.Latt_ud_done:
	s_lshl_b32 s2, s0, 5
	s_add_i32 s42, s15, s2
	s_mov_b32 s43, 0
	s_waitcnt vmcnt(12)
	v_mov_b32_e32 v132, 0
	v_mfma_f32_16x16x32_bf16 v[236:239], v[0:3], v[48:51], 0
	v_mfma_f32_16x16x32_bf16 v[236:239], v[4:7], v[52:55], v[236:239]
	v_mfma_f32_16x16x32_bf16 v[240:243], v[8:11], v[48:51], 0
	v_mfma_f32_16x16x32_bf16 v[240:243], v[12:15], v[52:55], v[240:243]
	s_nop 7
	v_min_f32_e32 v152, 0x42a00000, v236
	v_min_f32_e32 v153, 0x42a00000, v237
	v_min_f32_e32 v154, 0x42a00000, v238
	v_min_f32_e32 v155, 0x42a00000, v239
	v_mfma_f32_16x16x32_bf16 v[236:239], v[16:19], v[48:51], 0
	v_mfma_f32_16x16x32_bf16 v[236:239], v[20:23], v[52:55], v[236:239]
	v_add_u32_e32 v136, 0x60, v182
	v_med3_i32 v136, v136, 0, s38
	v_lshl_add_u32 v136, v136, 9, v179
	global_load_dwordx4 v[0:3], v136, s[24:25]
	global_load_dwordx4 v[4:7], v136, s[24:25] offset:64
	v_mul_f32_e32 v152, 0x3fb8aa3b, v152
	v_mul_f32_e32 v153, 0x3fb8aa3b, v153
	v_mul_f32_e32 v154, 0x3fb8aa3b, v154
	v_mul_f32_e32 v155, 0x3fb8aa3b, v155
	v_exp_f32_e32 v152, v152
	v_exp_f32_e32 v153, v153
	v_exp_f32_e32 v154, v154
	v_exp_f32_e32 v155, v155
	v_add_u32_e32 v138, 0, v175
	v_add_u32_e32 v139, 1, v175
	v_add_u32_e32 v140, 2, v175
	v_add_u32_e32 v141, 3, v175
	v_cmp_gt_u32_e64 s[70:71], s44, v138
	v_cmp_gt_u32_e64 s[72:73], s44, v139
	v_cmp_gt_u32_e64 s[74:75], s44, v140
	v_cmp_gt_u32_e64 s[76:77], s44, v141
	v_cndmask_b32_e64 v152, 0, v152, s[54:55]
	v_cndmask_b32_e64 v153, 0, v153, s[56:57]
	v_cndmask_b32_e64 v154, 0, v154, s[58:59]
	v_cndmask_b32_e64 v155, 0, v155, s[60:61]
	v_cndmask_b32_e64 v152, 0, v152, s[70:71]
	v_cndmask_b32_e64 v153, 0, v153, s[72:73]
	v_cndmask_b32_e64 v154, 0, v154, s[74:75]
	v_cndmask_b32_e64 v155, 0, v155, s[76:77]
	v_add_f32_e32 v132, v132, v152
	v_add_f32_e32 v132, v132, v153
	v_add_f32_e32 v132, v132, v154
	v_add_f32_e32 v132, v132, v155
	v_cvt_pk_bf16_f32 v112, v152, v153
	v_cvt_pk_bf16_f32 v113, v154, v155
	v_min_f32_e32 v152, 0x42a00000, v240
	v_min_f32_e32 v153, 0x42a00000, v241
	v_min_f32_e32 v154, 0x42a00000, v242
	v_min_f32_e32 v155, 0x42a00000, v243
	v_mfma_f32_16x16x32_bf16 v[240:243], v[24:27], v[48:51], 0
	v_mfma_f32_16x16x32_bf16 v[240:243], v[28:31], v[52:55], v[240:243]
	v_add_u32_e32 v135, 0x70, v182
	v_med3_i32 v135, v135, 0, s38
	v_lshl_add_u32 v135, v135, 9, v179
	global_load_dwordx4 v[8:11], v135, s[24:25]
	global_load_dwordx4 v[12:15], v135, s[24:25] offset:64
	v_mul_f32_e32 v152, 0x3fb8aa3b, v152
	v_mul_f32_e32 v153, 0x3fb8aa3b, v153
	v_mul_f32_e32 v154, 0x3fb8aa3b, v154
	v_mul_f32_e32 v155, 0x3fb8aa3b, v155
	v_exp_f32_e32 v152, v152
	v_exp_f32_e32 v153, v153
	v_exp_f32_e32 v154, v154
	v_exp_f32_e32 v155, v155
	v_add_u32_e32 v138, 16, v175
	v_add_u32_e32 v139, 17, v175
	v_add_u32_e32 v140, 18, v175
	v_add_u32_e32 v141, 19, v175
	v_cmp_gt_u32_e64 s[70:71], s44, v138
	v_cmp_gt_u32_e64 s[72:73], s44, v139
	v_cmp_gt_u32_e64 s[74:75], s44, v140
	v_cmp_gt_u32_e64 s[76:77], s44, v141
	v_cndmask_b32_e64 v152, 0, v152, s[70:71]
	v_cndmask_b32_e64 v153, 0, v153, s[72:73]
	v_cndmask_b32_e64 v154, 0, v154, s[74:75]
	v_cndmask_b32_e64 v155, 0, v155, s[76:77]
	v_add_f32_e32 v132, v132, v152
	v_add_f32_e32 v132, v132, v153
	v_add_f32_e32 v132, v132, v154
	v_add_f32_e32 v132, v132, v155
	v_cvt_pk_bf16_f32 v114, v152, v153
	v_cvt_pk_bf16_f32 v115, v154, v155
	v_min_f32_e32 v152, 0x42a00000, v236
	v_min_f32_e32 v153, 0x42a00000, v237
	v_min_f32_e32 v154, 0x42a00000, v238
	v_min_f32_e32 v155, 0x42a00000, v239
	v_mfma_f32_16x16x32_bf16 v[236:239], v[32:35], v[48:51], 0
	v_mfma_f32_16x16x32_bf16 v[236:239], v[36:39], v[52:55], v[236:239]
	v_add_u32_e32 v136, 0x80, v182
	v_med3_i32 v136, v136, 0, s38
	v_lshl_add_u32 v136, v136, 9, v179
	global_load_dwordx4 v[16:19], v136, s[24:25]
	global_load_dwordx4 v[20:23], v136, s[24:25] offset:64
	v_mul_f32_e32 v152, 0x3fb8aa3b, v152
	v_mul_f32_e32 v153, 0x3fb8aa3b, v153
	v_mul_f32_e32 v154, 0x3fb8aa3b, v154
	v_mul_f32_e32 v155, 0x3fb8aa3b, v155
	v_exp_f32_e32 v152, v152
	v_exp_f32_e32 v153, v153
	v_exp_f32_e32 v154, v154
	v_exp_f32_e32 v155, v155
	v_add_u32_e32 v138, 32, v175
	v_add_u32_e32 v139, 33, v175
	v_add_u32_e32 v140, 34, v175
	v_add_u32_e32 v141, 35, v175
	v_cmp_gt_u32_e64 s[70:71], s44, v138
	v_cmp_gt_u32_e64 s[72:73], s44, v139
	v_cmp_gt_u32_e64 s[74:75], s44, v140
	v_cmp_gt_u32_e64 s[76:77], s44, v141
	v_cndmask_b32_e64 v152, 0, v152, s[70:71]
	v_cndmask_b32_e64 v153, 0, v153, s[72:73]
	v_cndmask_b32_e64 v154, 0, v154, s[74:75]
	v_cndmask_b32_e64 v155, 0, v155, s[76:77]
	v_add_f32_e32 v132, v132, v152
	v_add_f32_e32 v132, v132, v153
	v_add_f32_e32 v132, v132, v154
	v_add_f32_e32 v132, v132, v155
	v_cvt_pk_bf16_f32 v116, v152, v153
	v_cvt_pk_bf16_f32 v117, v154, v155
	v_min_f32_e32 v152, 0x42a00000, v240
	v_min_f32_e32 v153, 0x42a00000, v241
	v_min_f32_e32 v154, 0x42a00000, v242
	v_min_f32_e32 v155, 0x42a00000, v243
	v_mfma_f32_16x16x32_bf16 v[240:243], v[40:43], v[48:51], 0
	v_mfma_f32_16x16x32_bf16 v[240:243], v[44:47], v[52:55], v[240:243]
	v_mul_f32_e32 v152, 0x3fb8aa3b, v152
	v_mul_f32_e32 v153, 0x3fb8aa3b, v153
	v_mul_f32_e32 v154, 0x3fb8aa3b, v154
	v_mul_f32_e32 v155, 0x3fb8aa3b, v155
	v_exp_f32_e32 v152, v152
	v_exp_f32_e32 v153, v153
	v_exp_f32_e32 v154, v154
	v_exp_f32_e32 v155, v155
	v_add_u32_e32 v138, 48, v175
	v_add_u32_e32 v139, 49, v175
	v_add_u32_e32 v140, 50, v175
	v_add_u32_e32 v141, 51, v175
	v_cmp_gt_u32_e64 s[70:71], s44, v138
	v_cmp_gt_u32_e64 s[72:73], s44, v139
	v_cmp_gt_u32_e64 s[74:75], s44, v140
	v_cmp_gt_u32_e64 s[76:77], s44, v141
	v_cndmask_b32_e64 v152, 0, v152, s[70:71]
	v_cndmask_b32_e64 v153, 0, v153, s[72:73]
	v_cndmask_b32_e64 v154, 0, v154, s[74:75]
	v_cndmask_b32_e64 v155, 0, v155, s[76:77]
	v_add_f32_e32 v132, v132, v152
	v_add_f32_e32 v132, v132, v153
	v_add_f32_e32 v132, v132, v154
	v_add_f32_e32 v132, v132, v155
	v_cvt_pk_bf16_f32 v118, v152, v153
	v_cvt_pk_bf16_f32 v119, v154, v155
	v_min_f32_e32 v152, 0x42a00000, v236
	v_min_f32_e32 v153, 0x42a00000, v237
	v_min_f32_e32 v154, 0x42a00000, v238
	v_min_f32_e32 v155, 0x42a00000, v239
	s_waitcnt vmcnt(4)
	v_mfma_f32_16x16x32_bf16 v[236:239], v[0:3], v[48:51], 0
	v_mfma_f32_16x16x32_bf16 v[236:239], v[4:7], v[52:55], v[236:239]
	v_mul_f32_e32 v152, 0x3fb8aa3b, v152
	v_mul_f32_e32 v153, 0x3fb8aa3b, v153
	v_mul_f32_e32 v154, 0x3fb8aa3b, v154
	v_mul_f32_e32 v155, 0x3fb8aa3b, v155
	v_exp_f32_e32 v152, v152
	v_exp_f32_e32 v153, v153
	v_exp_f32_e32 v154, v154
	v_exp_f32_e32 v155, v155
	v_add_u32_e32 v138, 64, v175
	v_add_u32_e32 v139, 0x41, v175
	v_add_u32_e32 v140, 0x42, v175
	v_add_u32_e32 v141, 0x43, v175
	v_cmp_gt_u32_e64 s[70:71], s44, v138
	v_cmp_gt_u32_e64 s[72:73], s44, v139
	v_cmp_gt_u32_e64 s[74:75], s44, v140
	v_cmp_gt_u32_e64 s[76:77], s44, v141
	v_cndmask_b32_e64 v152, 0, v152, s[70:71]
	v_cndmask_b32_e64 v153, 0, v153, s[72:73]
	v_cndmask_b32_e64 v154, 0, v154, s[74:75]
	v_cndmask_b32_e64 v155, 0, v155, s[76:77]
	v_add_f32_e32 v132, v132, v152
	v_add_f32_e32 v132, v132, v153
	v_add_f32_e32 v132, v132, v154
	v_add_f32_e32 v132, v132, v155
	v_cvt_pk_bf16_f32 v120, v152, v153
	v_cvt_pk_bf16_f32 v121, v154, v155
	v_min_f32_e32 v152, 0x42a00000, v240
	v_min_f32_e32 v153, 0x42a00000, v241
	v_min_f32_e32 v154, 0x42a00000, v242
	v_min_f32_e32 v155, 0x42a00000, v243
	s_waitcnt vmcnt(2)
	v_mfma_f32_16x16x32_bf16 v[240:243], v[8:11], v[48:51], 0
	v_mfma_f32_16x16x32_bf16 v[240:243], v[12:15], v[52:55], v[240:243]
	v_mul_f32_e32 v152, 0x3fb8aa3b, v152
	v_mul_f32_e32 v153, 0x3fb8aa3b, v153
	v_mul_f32_e32 v154, 0x3fb8aa3b, v154
	v_mul_f32_e32 v155, 0x3fb8aa3b, v155
	v_exp_f32_e32 v152, v152
	v_exp_f32_e32 v153, v153
	v_exp_f32_e32 v154, v154
	v_exp_f32_e32 v155, v155
	v_add_u32_e32 v138, 0x50, v175
	v_add_u32_e32 v139, 0x51, v175
	v_add_u32_e32 v140, 0x52, v175
	v_add_u32_e32 v141, 0x53, v175
	v_cmp_gt_u32_e64 s[70:71], s44, v138
	v_cmp_gt_u32_e64 s[72:73], s44, v139
	v_cmp_gt_u32_e64 s[74:75], s44, v140
	v_cmp_gt_u32_e64 s[76:77], s44, v141
	v_cndmask_b32_e64 v152, 0, v152, s[70:71]
	v_cndmask_b32_e64 v153, 0, v153, s[72:73]
	v_cndmask_b32_e64 v154, 0, v154, s[74:75]
	v_cndmask_b32_e64 v155, 0, v155, s[76:77]
	v_add_f32_e32 v132, v132, v152
	v_add_f32_e32 v132, v132, v153
	v_add_f32_e32 v132, v132, v154
	v_add_f32_e32 v132, v132, v155
	v_cvt_pk_bf16_f32 v122, v152, v153
	v_cvt_pk_bf16_f32 v123, v154, v155
	v_min_f32_e32 v152, 0x42a00000, v236
	v_min_f32_e32 v153, 0x42a00000, v237
	v_min_f32_e32 v154, 0x42a00000, v238
	v_min_f32_e32 v155, 0x42a00000, v239
	s_waitcnt vmcnt(0)
	v_mfma_f32_16x16x32_bf16 v[236:239], v[16:19], v[48:51], 0
	v_mfma_f32_16x16x32_bf16 v[236:239], v[20:23], v[52:55], v[236:239]
	v_mul_f32_e32 v152, 0x3fb8aa3b, v152
	v_mul_f32_e32 v153, 0x3fb8aa3b, v153
	v_mul_f32_e32 v154, 0x3fb8aa3b, v154
	v_mul_f32_e32 v155, 0x3fb8aa3b, v155
	v_exp_f32_e32 v152, v152
	v_exp_f32_e32 v153, v153
	v_exp_f32_e32 v154, v154
	v_exp_f32_e32 v155, v155
	v_add_u32_e32 v138, 0x60, v175
	v_add_u32_e32 v139, 0x61, v175
	v_add_u32_e32 v140, 0x62, v175
	v_add_u32_e32 v141, 0x63, v175
	v_cmp_gt_u32_e64 s[70:71], s44, v138
	v_cmp_gt_u32_e64 s[72:73], s44, v139
	v_cmp_gt_u32_e64 s[74:75], s44, v140
	v_cmp_gt_u32_e64 s[76:77], s44, v141
	v_cndmask_b32_e64 v152, 0, v152, s[70:71]
	v_cndmask_b32_e64 v153, 0, v153, s[72:73]
	v_cndmask_b32_e64 v154, 0, v154, s[74:75]
	v_cndmask_b32_e64 v155, 0, v155, s[76:77]
	v_add_f32_e32 v132, v132, v152
	v_add_f32_e32 v132, v132, v153
	v_add_f32_e32 v132, v132, v154
	v_add_f32_e32 v132, v132, v155
	v_cvt_pk_bf16_f32 v124, v152, v153
	v_cvt_pk_bf16_f32 v125, v154, v155
	v_min_f32_e32 v152, 0x42a00000, v240
	v_min_f32_e32 v153, 0x42a00000, v241
	v_min_f32_e32 v154, 0x42a00000, v242
	v_min_f32_e32 v155, 0x42a00000, v243
	v_mul_f32_e32 v152, 0x3fb8aa3b, v152
	v_mul_f32_e32 v153, 0x3fb8aa3b, v153
	v_mul_f32_e32 v154, 0x3fb8aa3b, v154
	v_mul_f32_e32 v155, 0x3fb8aa3b, v155
	v_exp_f32_e32 v152, v152
	v_exp_f32_e32 v153, v153
	v_exp_f32_e32 v154, v154
	v_exp_f32_e32 v155, v155
	v_add_u32_e32 v138, 0x70, v175
	v_add_u32_e32 v139, 0x71, v175
	v_add_u32_e32 v140, 0x72, v175
	v_add_u32_e32 v141, 0x73, v175
	v_cmp_gt_u32_e64 s[70:71], s44, v138
	v_cmp_gt_u32_e64 s[72:73], s44, v139
	v_cmp_gt_u32_e64 s[74:75], s44, v140
	v_cmp_gt_u32_e64 s[76:77], s44, v141
	v_cndmask_b32_e64 v152, 0, v152, s[70:71]
	v_cndmask_b32_e64 v153, 0, v153, s[72:73]
	v_cndmask_b32_e64 v154, 0, v154, s[74:75]
	v_cndmask_b32_e64 v155, 0, v155, s[76:77]
	v_add_f32_e32 v132, v132, v152
	v_add_f32_e32 v132, v132, v153
	v_add_f32_e32 v132, v132, v154
	v_add_f32_e32 v132, v132, v155
	v_cvt_pk_bf16_f32 v126, v152, v153
	v_cvt_pk_bf16_f32 v127, v154, v155
	v_min_f32_e32 v152, 0x42a00000, v236
	v_min_f32_e32 v153, 0x42a00000, v237
	v_min_f32_e32 v154, 0x42a00000, v238
	v_min_f32_e32 v155, 0x42a00000, v239
	v_mul_f32_e32 v152, 0x3fb8aa3b, v152
	v_mul_f32_e32 v153, 0x3fb8aa3b, v153
	v_mul_f32_e32 v154, 0x3fb8aa3b, v154
	v_mul_f32_e32 v155, 0x3fb8aa3b, v155
	v_exp_f32_e32 v152, v152
	v_exp_f32_e32 v153, v153
	v_exp_f32_e32 v154, v154
	v_exp_f32_e32 v155, v155
	v_add_u32_e32 v138, 0x80, v175
	v_add_u32_e32 v139, 0x81, v175
	v_add_u32_e32 v140, 0x82, v175
	v_add_u32_e32 v141, 0x83, v175
	v_cmp_gt_u32_e64 s[70:71], s44, v138
	v_cmp_gt_u32_e64 s[72:73], s44, v139
	v_cmp_gt_u32_e64 s[74:75], s44, v140
	v_cmp_gt_u32_e64 s[76:77], s44, v141
	v_cndmask_b32_e64 v152, 0, v152, s[62:63]
	v_cndmask_b32_e64 v153, 0, v153, s[64:65]
	v_cndmask_b32_e64 v154, 0, v154, s[66:67]
	v_cndmask_b32_e64 v155, 0, v155, s[68:69]
	v_cndmask_b32_e64 v152, 0, v152, s[70:71]
	v_cndmask_b32_e64 v153, 0, v153, s[72:73]
	v_cndmask_b32_e64 v154, 0, v154, s[74:75]
	v_cndmask_b32_e64 v155, 0, v155, s[76:77]
	v_add_f32_e32 v132, v132, v152
	v_add_f32_e32 v132, v132, v153
	v_add_f32_e32 v132, v132, v154
	v_add_f32_e32 v132, v132, v155
	v_cvt_pk_bf16_f32 v128, v152, v153
	v_cvt_pk_bf16_f32 v129, v154, v155
	v_add_u32_e32 v134, s42, v160
	v_add_u32_e32 v134, s43, v134
	v_subrev_u32_e32 v135, s15, v134
	v_lshrrev_b32_e32 v136, 4, v135
	v_add_u32_e32 v136, v136, v135
	v_mad_u32_u24 v176, v136, s79, v161
	v_lshl_add_u32 v177, v135, 2, s80
	s_sub_i32 s2, s42, 64
	v_add_u32_e32 v178, s2, v169
	v_and_b32_e32 v135, 3, v134
	v_lshlrev_b32_e32 v135, s13, v135
	v_lshrrev_b32_e32 v136, 2, v134
	v_add_u32_e32 v135, v135, v136
	v_lshl_add_u32 v135, v135, 7, v161
	global_load_dwordx4 v[48:51], v135, s[18:19] nt
	global_load_dwordx4 v[52:55], v135, s[18:19] offset:64 nt
	v_add_u32_e32 v137, 16, v134
	v_and_b32_e32 v135, 3, v137
	v_lshlrev_b32_e32 v135, s13, v135
	v_lshrrev_b32_e32 v136, 2, v137
	v_add_u32_e32 v135, v135, v136
	v_lshl_add_u32 v135, v135, 7, v161
	global_load_dwordx4 v[56:59], v135, s[18:19] nt
	global_load_dwordx4 v[60:63], v135, s[18:19] offset:64 nt
	v_subrev_u32_e32 v134, 64, v134
	v_and_b32_e32 v137, 3, v134
	v_lshlrev_b32_e32 v137, s13, v137
	v_bfe_u32 v135, v134, 2, 2
	v_add_u32_e32 v137, v137, v135
	v_lshl_add_u32 v183, v137, 7, v161
	v_ashrrev_i32_e32 v252, 4, v134
	v_med3_i32 v136, v252, 0, s14
	v_lshl_add_u32 v136, v136, 9, v183
	global_load_dwordx4 v[0:3], v136, s[20:21]
	global_load_dwordx4 v[4:7], v136, s[20:21] offset:64
	v_add_u32_e32 v135, 1, v252
	v_med3_i32 v135, v135, 0, s14
	v_lshl_add_u32 v135, v135, 9, v183
	global_load_dwordx4 v[8:11], v135, s[20:21]
	global_load_dwordx4 v[12:15], v135, s[20:21] offset:64
	v_add_u32_e32 v136, 2, v252
	v_med3_i32 v136, v136, 0, s14
	v_lshl_add_u32 v136, v136, 9, v183
	global_load_dwordx4 v[16:19], v136, s[20:21]
	global_load_dwordx4 v[20:23], v136, s[20:21] offset:64
	v_add_u32_e32 v135, 3, v252
	v_med3_i32 v135, v135, 0, s14
	v_lshl_add_u32 v135, v135, 9, v183
	global_load_dwordx4 v[24:27], v135, s[20:21]
	global_load_dwordx4 v[28:31], v135, s[20:21] offset:64
	v_add_u32_e32 v136, 4, v252
	v_med3_i32 v136, v136, 0, s14
	v_lshl_add_u32 v136, v136, 9, v183
	global_load_dwordx4 v[32:35], v136, s[20:21]
	global_load_dwordx4 v[36:39], v136, s[20:21] offset:64
	v_add_u32_e32 v135, 5, v252
	v_med3_i32 v135, v135, 0, s14
	v_lshl_add_u32 v135, v135, 9, v183
	global_load_dwordx4 v[40:43], v135, s[20:21]
	global_load_dwordx4 v[44:47], v135, s[20:21] offset:64
	ds_bpermute_b32 v142, v167, v132
	s_waitcnt lgkmcnt(0)
	v_add_f32_e32 v132, v132, v142
	ds_bpermute_b32 v142, v168, v132
	s_waitcnt lgkmcnt(0)
	v_add_f32_e32 v132, v132, v142
	s_waitcnt vmcnt(16)
	ds_write_b128 v165, v[64:67]
	ds_write_b128 v165, v[68:71] offset:1152
	ds_write_b128 v165, v[72:75] offset:2304
	ds_write_b128 v165, v[76:79] offset:3456
	s_waitcnt lgkmcnt(0)
	ds_read_b64_tr_b16 v[236:237], v166
	ds_read_b64_tr_b16 v[238:239], v166 offset:2304
	ds_read_b64_tr_b16 v[240:241], v166 offset:32
	ds_read_b64_tr_b16 v[242:243], v166 offset:2336
	ds_read_b64_tr_b16 v[244:245], v166 offset:64
	ds_read_b64_tr_b16 v[246:247], v166 offset:2368
	ds_read_b64_tr_b16 v[248:249], v166 offset:96
	ds_read_b64_tr_b16 v[250:251], v166 offset:2400
	s_waitcnt lgkmcnt(0)
	s_add_i32 s2, s40, 32
	v_add_u32_e32 v138, s2, v164
	v_lshlrev_b32_e32 v138, 4, v138
	v_add_u32_e32 v138, s41, v138
	v_and_b32_e32 v139, 3, v138
	v_lshlrev_b32_e32 v139, s39, v139
	v_bfe_u32 v140, v138, 2, 2
	v_add_u32_e32 v139, v139, v140
	v_lshl_add_u32 v139, v139, 7, v162
	v_ashrrev_i32_e32 v138, 4, v138
	v_med3_i32 v138, v138, 0, s38
	v_lshl_add_u32 v138, v138, 9, v139
	global_load_dwordx4 v[64:67], v138, s[26:27]
	s_add_i32 s2, s40, 40
	v_add_u32_e32 v138, s2, v164
	v_lshlrev_b32_e32 v138, 4, v138
	v_add_u32_e32 v138, s41, v138
	v_and_b32_e32 v139, 3, v138
	v_lshlrev_b32_e32 v139, s39, v139
	v_bfe_u32 v140, v138, 2, 2
	v_add_u32_e32 v139, v139, v140
	v_lshl_add_u32 v139, v139, 7, v162
	v_ashrrev_i32_e32 v138, 4, v138
	v_med3_i32 v138, v138, 0, s38
	v_lshl_add_u32 v138, v138, 9, v139
	global_load_dwordx4 v[68:71], v138, s[26:27]
	s_add_i32 s2, s40, 48
	v_add_u32_e32 v138, s2, v164
	v_lshlrev_b32_e32 v138, 4, v138
	v_add_u32_e32 v138, s41, v138
	v_and_b32_e32 v139, 3, v138
	v_lshlrev_b32_e32 v139, s39, v139
	v_bfe_u32 v140, v138, 2, 2
	v_add_u32_e32 v139, v139, v140
	v_lshl_add_u32 v139, v139, 7, v162
	v_ashrrev_i32_e32 v138, 4, v138
	v_med3_i32 v138, v138, 0, s38
	v_lshl_add_u32 v138, v138, 9, v139
	global_load_dwordx4 v[72:75], v138, s[26:27]
	s_add_i32 s2, s40, 56
	v_add_u32_e32 v138, s2, v164
	v_lshlrev_b32_e32 v138, 4, v138
	v_add_u32_e32 v138, s41, v138
	v_and_b32_e32 v139, 3, v138
	v_lshlrev_b32_e32 v139, s39, v139
	v_bfe_u32 v140, v138, 2, 2
	v_add_u32_e32 v139, v139, v140
	v_lshl_add_u32 v139, v139, 7, v162
	v_ashrrev_i32_e32 v138, 4, v138
	v_med3_i32 v138, v138, 0, s38
	v_lshl_add_u32 v138, v138, 9, v139
	global_load_dwordx4 v[76:79], v138, s[26:27]
	ds_write_b128 v165, v[80:83]
	ds_write_b128 v165, v[84:87] offset:1152
	ds_write_b128 v165, v[88:91] offset:2304
	ds_write_b128 v165, v[92:95] offset:3456
	v_mfma_f32_16x16x32_bf16 v[204:207], v[236:239], v[112:115], 0
	v_mfma_f32_16x16x32_bf16 v[208:211], v[240:243], v[112:115], 0
	v_mfma_f32_16x16x32_bf16 v[212:215], v[244:247], v[112:115], 0
	v_mfma_f32_16x16x32_bf16 v[216:219], v[248:251], v[112:115], 0
	s_waitcnt lgkmcnt(0)
	ds_read_b64_tr_b16 v[236:237], v166
	ds_read_b64_tr_b16 v[238:239], v166 offset:2304
	ds_read_b64_tr_b16 v[240:241], v166 offset:32
	ds_read_b64_tr_b16 v[242:243], v166 offset:2336
	ds_read_b64_tr_b16 v[244:245], v166 offset:64
	ds_read_b64_tr_b16 v[246:247], v166 offset:2368
	ds_read_b64_tr_b16 v[248:249], v166 offset:96
	ds_read_b64_tr_b16 v[250:251], v166 offset:2400
	s_waitcnt lgkmcnt(0)
	s_add_i32 s2, s40, 64
	v_add_u32_e32 v138, s2, v164
	v_lshlrev_b32_e32 v138, 4, v138
	v_add_u32_e32 v138, s41, v138
	v_and_b32_e32 v139, 3, v138
	v_lshlrev_b32_e32 v139, s39, v139
	v_bfe_u32 v140, v138, 2, 2
	v_add_u32_e32 v139, v139, v140
	v_lshl_add_u32 v139, v139, 7, v162
	v_ashrrev_i32_e32 v138, 4, v138
	v_med3_i32 v138, v138, 0, s38
	v_lshl_add_u32 v138, v138, 9, v139
	global_load_dwordx4 v[80:83], v138, s[26:27]
	s_add_i32 s2, s40, 72
	v_add_u32_e32 v138, s2, v164
	v_lshlrev_b32_e32 v138, 4, v138
	v_add_u32_e32 v138, s41, v138
	v_and_b32_e32 v139, 3, v138
	v_lshlrev_b32_e32 v139, s39, v139
	v_bfe_u32 v140, v138, 2, 2
	v_add_u32_e32 v139, v139, v140
	v_lshl_add_u32 v139, v139, 7, v162
	v_ashrrev_i32_e32 v138, 4, v138
	v_med3_i32 v138, v138, 0, s38
	v_lshl_add_u32 v138, v138, 9, v139
	global_load_dwordx4 v[84:87], v138, s[26:27]
	ds_write_b128 v165, v[96:99]
	ds_write_b128 v165, v[100:103] offset:1152
	ds_write_b128 v165, v[104:107] offset:2304
	ds_write_b128 v165, v[108:111] offset:3456
	v_mfma_f32_16x16x32_bf16 v[204:207], v[236:239], v[116:119], v[204:207]
	v_mfma_f32_16x16x32_bf16 v[208:211], v[240:243], v[116:119], v[208:211]
	v_mfma_f32_16x16x32_bf16 v[212:215], v[244:247], v[116:119], v[212:215]
	v_mfma_f32_16x16x32_bf16 v[216:219], v[248:251], v[116:119], v[216:219]
	s_waitcnt lgkmcnt(0)
	ds_read_b64_tr_b16 v[236:237], v166
	ds_read_b64_tr_b16 v[238:239], v166 offset:2304
	ds_read_b64_tr_b16 v[240:241], v166 offset:32
	ds_read_b64_tr_b16 v[242:243], v166 offset:2336
	ds_read_b64_tr_b16 v[244:245], v166 offset:64
	ds_read_b64_tr_b16 v[246:247], v166 offset:2368
	ds_read_b64_tr_b16 v[248:249], v166 offset:96
	ds_read_b64_tr_b16 v[250:251], v166 offset:2400
	s_waitcnt lgkmcnt(0)
	s_waitcnt vmcnt(2)
	ds_write_b128 v165, v[64:67]
	ds_write_b128 v165, v[68:71] offset:1152
	ds_write_b128 v165, v[72:75] offset:2304
	ds_write_b128 v165, v[76:79] offset:3456
	v_mfma_f32_16x16x32_bf16 v[204:207], v[236:239], v[120:123], v[204:207]
	v_mfma_f32_16x16x32_bf16 v[208:211], v[240:243], v[120:123], v[208:211]
	v_mfma_f32_16x16x32_bf16 v[212:215], v[244:247], v[120:123], v[212:215]
	v_mfma_f32_16x16x32_bf16 v[216:219], v[248:251], v[120:123], v[216:219]
	s_waitcnt lgkmcnt(0)
	ds_read_b64_tr_b16 v[236:237], v166
	ds_read_b64_tr_b16 v[238:239], v166 offset:2304
	ds_read_b64_tr_b16 v[240:241], v166 offset:32
	ds_read_b64_tr_b16 v[242:243], v166 offset:2336
	ds_read_b64_tr_b16 v[244:245], v166 offset:64
	ds_read_b64_tr_b16 v[246:247], v166 offset:2368
	ds_read_b64_tr_b16 v[248:249], v166 offset:96
	ds_read_b64_tr_b16 v[250:251], v166 offset:2400
	s_waitcnt lgkmcnt(0)
	s_waitcnt vmcnt(0)
	ds_write_b128 v165, v[80:83]
	ds_write_b128 v165, v[84:87] offset:1152
	v_mfma_f32_16x16x32_bf16 v[204:207], v[236:239], v[124:127], v[204:207]
	v_mfma_f32_16x16x32_bf16 v[208:211], v[240:243], v[124:127], v[208:211]
	v_mfma_f32_16x16x32_bf16 v[212:215], v[244:247], v[124:127], v[212:215]
	v_mfma_f32_16x16x32_bf16 v[216:219], v[248:251], v[124:127], v[216:219]
	s_waitcnt lgkmcnt(0)
	ds_read_b64_tr_b16 v[236:237], v166
	ds_read_b64_tr_b16 v[238:239], v166 offset:2304
	ds_read_b64_tr_b16 v[240:241], v166 offset:32
	ds_read_b64_tr_b16 v[242:243], v166 offset:2336
	ds_read_b64_tr_b16 v[244:245], v166 offset:64
	ds_read_b64_tr_b16 v[246:247], v166 offset:2368
	ds_read_b64_tr_b16 v[248:249], v166 offset:96
	ds_read_b64_tr_b16 v[250:251], v166 offset:2400
	s_waitcnt lgkmcnt(0)
	v_mfma_f32_16x16x32_bf16 v[204:207], v[236:239], v[128:131], v[204:207]
	v_mfma_f32_16x16x32_bf16 v[208:211], v[240:243], v[128:131], v[208:211]
	v_mfma_f32_16x16x32_bf16 v[212:215], v[244:247], v[128:131], v[212:215]
	v_mfma_f32_16x16x32_bf16 v[216:219], v[248:251], v[128:131], v[216:219]
	s_add_i32 s2, s42, -64
	v_add_u32_e32 v138, s2, v164
	v_add_u32_e32 v138, s43, v138
	v_and_b32_e32 v139, 3, v138
	v_lshlrev_b32_e32 v139, s13, v139
	v_bfe_u32 v140, v138, 2, 2
	v_add_u32_e32 v139, v139, v140
	v_lshl_add_u32 v139, v139, 7, v162
	v_ashrrev_i32_e32 v138, 4, v138
	v_med3_i32 v138, v138, 0, s14
	v_lshl_add_u32 v138, v138, 9, v139
	global_load_dwordx4 v[64:67], v138, s[22:23]
	s_add_i32 s2, s42, -56
	v_add_u32_e32 v138, s2, v164
	v_add_u32_e32 v138, s43, v138
	v_and_b32_e32 v139, 3, v138
	v_lshlrev_b32_e32 v139, s13, v139
	v_bfe_u32 v140, v138, 2, 2
	v_add_u32_e32 v139, v139, v140
	v_lshl_add_u32 v139, v139, 7, v162
	v_ashrrev_i32_e32 v138, 4, v138
	v_med3_i32 v138, v138, 0, s14
	v_lshl_add_u32 v138, v138, 9, v139
	global_load_dwordx4 v[68:71], v138, s[22:23]
	s_add_i32 s2, s42, -48
	v_add_u32_e32 v138, s2, v164
	v_add_u32_e32 v138, s43, v138
	v_and_b32_e32 v139, 3, v138
	v_lshlrev_b32_e32 v139, s13, v139
	v_bfe_u32 v140, v138, 2, 2
	v_add_u32_e32 v139, v139, v140
	v_lshl_add_u32 v139, v139, 7, v162
	v_ashrrev_i32_e32 v138, 4, v138
	v_med3_i32 v138, v138, 0, s14
	v_lshl_add_u32 v138, v138, 9, v139
	global_load_dwordx4 v[72:75], v138, s[22:23]
	s_add_i32 s2, s42, -40
	v_add_u32_e32 v138, s2, v164
	v_add_u32_e32 v138, s43, v138
	v_and_b32_e32 v139, 3, v138
	v_lshlrev_b32_e32 v139, s13, v139
	v_bfe_u32 v140, v138, 2, 2
	v_add_u32_e32 v139, v139, v140
	v_lshl_add_u32 v139, v139, 7, v162
	v_ashrrev_i32_e32 v138, 4, v138
	v_med3_i32 v138, v138, 0, s14
	v_lshl_add_u32 v138, v138, 9, v139
	global_load_dwordx4 v[76:79], v138, s[22:23]
	s_add_i32 s2, s42, -32
	v_add_u32_e32 v138, s2, v164
	v_add_u32_e32 v138, s43, v138
	v_and_b32_e32 v139, 3, v138
	v_lshlrev_b32_e32 v139, s13, v139
	v_bfe_u32 v140, v138, 2, 2
	v_add_u32_e32 v139, v139, v140
	v_lshl_add_u32 v139, v139, 7, v162
	v_ashrrev_i32_e32 v138, 4, v138
	v_med3_i32 v138, v138, 0, s14
	v_lshl_add_u32 v138, v138, 9, v139
	global_load_dwordx4 v[80:83], v138, s[22:23]
	s_add_i32 s2, s42, -24
	v_add_u32_e32 v138, s2, v164
	v_add_u32_e32 v138, s43, v138
	v_and_b32_e32 v139, 3, v138
	v_lshlrev_b32_e32 v139, s13, v139
	v_bfe_u32 v140, v138, 2, 2
	v_add_u32_e32 v139, v139, v140
	v_lshl_add_u32 v139, v139, 7, v162
	v_ashrrev_i32_e32 v138, 4, v138
	v_med3_i32 v138, v138, 0, s14
	v_lshl_add_u32 v138, v138, 9, v139
	global_load_dwordx4 v[84:87], v138, s[22:23]
	s_add_i32 s2, s42, -16
	v_add_u32_e32 v138, s2, v164
	v_add_u32_e32 v138, s43, v138
	v_and_b32_e32 v139, 3, v138
	v_lshlrev_b32_e32 v139, s13, v139
	v_bfe_u32 v140, v138, 2, 2
	v_add_u32_e32 v139, v139, v140
	v_lshl_add_u32 v139, v139, 7, v162
	v_ashrrev_i32_e32 v138, 4, v138
	v_med3_i32 v138, v138, 0, s14
	v_lshl_add_u32 v138, v138, 9, v139
	global_load_dwordx4 v[88:91], v138, s[22:23]
	s_add_i32 s2, s42, -8
	v_add_u32_e32 v138, s2, v164
	v_add_u32_e32 v138, s43, v138
	v_and_b32_e32 v139, 3, v138
	v_lshlrev_b32_e32 v139, s13, v139
	v_bfe_u32 v140, v138, 2, 2
	v_add_u32_e32 v139, v139, v140
	v_lshl_add_u32 v139, v139, 7, v162
	v_ashrrev_i32_e32 v138, 4, v138
	v_med3_i32 v138, v138, 0, s14
	v_lshl_add_u32 v138, v138, 9, v139
	global_load_dwordx4 v[92:95], v138, s[22:23]
	s_add_i32 s2, s42, 0
	v_add_u32_e32 v138, s2, v164
	v_add_u32_e32 v138, s43, v138
	v_and_b32_e32 v139, 3, v138
	v_lshlrev_b32_e32 v139, s13, v139
	v_bfe_u32 v140, v138, 2, 2
	v_add_u32_e32 v139, v139, v140
	v_lshl_add_u32 v139, v139, 7, v162
	v_ashrrev_i32_e32 v138, 4, v138
	v_med3_i32 v138, v138, 0, s14
	v_lshl_add_u32 v138, v138, 9, v139
	global_load_dwordx4 v[96:99], v138, s[22:23]
	s_add_i32 s2, s42, 8
	v_add_u32_e32 v138, s2, v164
	v_add_u32_e32 v138, s43, v138
	v_and_b32_e32 v139, 3, v138
	v_lshlrev_b32_e32 v139, s13, v139
	v_bfe_u32 v140, v138, 2, 2
	v_add_u32_e32 v139, v139, v140
	v_lshl_add_u32 v139, v139, 7, v162
	v_ashrrev_i32_e32 v138, 4, v138
	v_med3_i32 v138, v138, 0, s14
	v_lshl_add_u32 v138, v138, 9, v139
	global_load_dwordx4 v[100:103], v138, s[22:23]
	s_add_i32 s2, s42, 16
	v_add_u32_e32 v138, s2, v164
	v_add_u32_e32 v138, s43, v138
	v_and_b32_e32 v139, 3, v138
	v_lshlrev_b32_e32 v139, s13, v139
	v_bfe_u32 v140, v138, 2, 2
	v_add_u32_e32 v139, v139, v140
	v_lshl_add_u32 v139, v139, 7, v162
	v_ashrrev_i32_e32 v138, 4, v138
	v_med3_i32 v138, v138, 0, s14
	v_lshl_add_u32 v138, v138, 9, v139
	global_load_dwordx4 v[104:107], v138, s[22:23]
	s_add_i32 s2, s42, 24
	v_add_u32_e32 v138, s2, v164
	v_add_u32_e32 v138, s43, v138
	v_and_b32_e32 v139, 3, v138
	v_lshlrev_b32_e32 v139, s13, v139
	v_bfe_u32 v140, v138, 2, 2
	v_add_u32_e32 v139, v139, v140
	v_lshl_add_u32 v139, v139, 7, v162
	v_ashrrev_i32_e32 v138, 4, v138
	v_med3_i32 v138, v138, 0, s14
	v_lshl_add_u32 v138, v138, 9, v139
	global_load_dwordx4 v[108:111], v138, s[22:23]
	ds_read_b128 v[236:239], v173 offset:0
	ds_read_b128 v[240:243], v173 offset:64
	ds_read_b128 v[244:247], v173 offset:128
	ds_read_b128 v[248:251], v173 offset:192
	ds_read_b32 v142, v174 offset:0
	s_waitcnt lgkmcnt(0)
	v_add_f32_e32 v204, v236, v204
	v_add_f32_e32 v205, v237, v205
	v_add_f32_e32 v206, v238, v206
	v_add_f32_e32 v207, v239, v207
	v_add_f32_e32 v208, v240, v208
	v_add_f32_e32 v209, v241, v209
	v_add_f32_e32 v210, v242, v210
	v_add_f32_e32 v211, v243, v211
	v_add_f32_e32 v212, v244, v212
	v_add_f32_e32 v213, v245, v213
	v_add_f32_e32 v214, v246, v214
	v_add_f32_e32 v215, v247, v215
	v_add_f32_e32 v216, v248, v216
	v_add_f32_e32 v217, v249, v217
	v_add_f32_e32 v218, v250, v218
	v_add_f32_e32 v219, v251, v219
	v_add_f32_e32 v132, v142, v132
	ds_write_b128 v173, v[204:207] offset:0
	ds_write_b128 v173, v[208:211] offset:64
	ds_write_b128 v173, v[212:215] offset:128
	ds_write_b128 v173, v[216:219] offset:192
	ds_write_b32 v174, v132 offset:0
	s_waitcnt lgkmcnt(0)
	s_barrier
	ds_read_b128 v[204:207], v170
	ds_read_b128 v[208:211], v170 offset:16
	ds_read_b128 v[212:215], v170 offset:32
	ds_read_b128 v[216:219], v170 offset:48
	ds_read_b128 v[220:223], v170 offset:64
	ds_read_b128 v[224:227], v170 offset:80
	ds_read_b128 v[228:231], v170 offset:96
	ds_read_b128 v[232:235], v170 offset:112
	ds_read_b32 v142, v171
	s_lshl_b32 s2, s35, 11
	s_lshl_b32 s3, s36, 7
	s_add_u32 s2, s2, s3
	s_add_u32 s90, s6, s2
	s_addc_u32 s91, s7, 0
	s_waitcnt lgkmcnt(0)
	v_div_scale_f32 v143, s[30:31], v142, v142, 1.0
	v_rcp_f32_e32 v147, v143
	v_div_scale_f32 v134, vcc, 1.0, v142, 1.0
	v_fma_f32 v135, -v143, v147, 1.0
	v_fmac_f32_e32 v147, v135, v147
	v_mul_f32_e32 v135, v134, v147
	v_fma_f32 v136, -v143, v135, v134
	v_fmac_f32_e32 v135, v136, v147
	v_fma_f32 v143, -v143, v135, v134
	v_div_fmas_f32 v143, v143, v147, v135
	v_div_fixup_f32 v142, v143, v142, 1.0
	v_mul_f32_e32 v204, v142, v204
	v_mul_f32_e32 v205, v142, v205
	v_mul_f32_e32 v206, v142, v206
	v_mul_f32_e32 v207, v142, v207
	v_mul_f32_e32 v208, v142, v208
	v_mul_f32_e32 v209, v142, v209
	v_mul_f32_e32 v210, v142, v210
	v_mul_f32_e32 v211, v142, v211
	v_mul_f32_e32 v212, v142, v212
	v_mul_f32_e32 v213, v142, v213
	v_mul_f32_e32 v214, v142, v214
	v_mul_f32_e32 v215, v142, v215
	v_mul_f32_e32 v216, v142, v216
	v_mul_f32_e32 v217, v142, v217
	v_mul_f32_e32 v218, v142, v218
	v_mul_f32_e32 v219, v142, v219
	v_mul_f32_e32 v220, v142, v220
	v_mul_f32_e32 v221, v142, v221
	v_mul_f32_e32 v222, v142, v222
	v_mul_f32_e32 v223, v142, v223
	v_mul_f32_e32 v224, v142, v224
	v_mul_f32_e32 v225, v142, v225
	v_mul_f32_e32 v226, v142, v226
	v_mul_f32_e32 v227, v142, v227
	v_mul_f32_e32 v228, v142, v228
	v_mul_f32_e32 v229, v142, v229
	v_mul_f32_e32 v230, v142, v230
	v_mul_f32_e32 v231, v142, v231
	v_mul_f32_e32 v232, v142, v232
	v_mul_f32_e32 v233, v142, v233
	v_mul_f32_e32 v234, v142, v234
	v_mul_f32_e32 v235, v142, v235
	v_cvt_pk_bf16_f32 v112, v204, v205
	v_cvt_pk_bf16_f32 v113, v206, v207
	v_cvt_pk_bf16_f32 v114, v208, v209
	v_cvt_pk_bf16_f32 v115, v210, v211
	v_cvt_pk_bf16_f32 v116, v212, v213
	v_cvt_pk_bf16_f32 v117, v214, v215
	v_cvt_pk_bf16_f32 v118, v216, v217
	v_cvt_pk_bf16_f32 v119, v218, v219
	v_cvt_pk_bf16_f32 v120, v220, v221
	v_cvt_pk_bf16_f32 v121, v222, v223
	v_cvt_pk_bf16_f32 v122, v224, v225
	v_cvt_pk_bf16_f32 v123, v226, v227
	v_cvt_pk_bf16_f32 v124, v228, v229
	v_cvt_pk_bf16_f32 v125, v230, v231
	v_cvt_pk_bf16_f32 v126, v232, v233
	v_cvt_pk_bf16_f32 v127, v234, v235
	global_store_dwordx4 v172, v[112:115], s[90:91] nt
	global_store_dwordx4 v172, v[116:119], s[90:91] offset:16 nt
	global_store_dwordx4 v172, v[120:123], s[90:91] offset:32 nt
	global_store_dwordx4 v172, v[124:127], s[90:91] offset:48 nt
	s_barrier
	s_cmp_eq_u32 s37, 0
	s_cbranch_scc1 .Latt_unit
	s_waitcnt vmcnt(0)
	s_branch .LBB0_365
